# stack8 + complementary unit-start order: lagging half zeroes first, then its scalar block, then its offset barrier, then load segment; leading half as stack9 (14 GEMM instances)
# baseline (speedup 1.0000x reference)
;     __device__ __forceinline__ bool next(int i, Unit& u) const {
;         const long L = (long)i * G + c; if (L >= total) return false;
;         if (nM1 == 144 && nN1 == 8 && nM2 == 0 && G == 256) {
;             const int xcd = c & 7, o = c >> 3;
;             const int grp = (i < 4) ? xcd * 4 + i : 32 + (xcd >> 1), idx = (i < 4) ? o : (xcd & 1) * 16 + o;
;             u.pm = grp * 4 + (idx & 3); u.pn = idx >> 2; return true; }
;         int w = (int)L; { const int q = total / NXCD, r = total % NXCD, xcd = w % NXCD, off = w / NXCD; w = (xcd < r ? xcd * (q + 1) : r * (q + 1) + (xcd - r) * q) + off; }
;         int nM = nM1, nN = nN1; const bool second = w >= n1; if (second) { w -= n1; nM = nM2; nN = nN2; }
;         const int wgm = 4;
;         const int nig = wgm * nN, gid = w / nig, fm = gid * wgm, gsz = (nM - fm) < wgm ? (nM - fm) : wgm;
;         int pm = fm + ((w % nig) % gsz), pn = (w % nig) / gsz;
;         if (second) { pm += pm2; pn = pn < split ? a0 + pn : a1 + pn; }
;         u.pm = pm; u.pn = pn; return true;
;     }
.LBB0_213:
	s_and_b64 vcc, exec, s[10:11]
	s_cbranch_vccz .Ly_216
	s_add_i32 s61, s61, 1
	s_mul_i32 s4, s61, s60
	s_mul_hi_u32 s5, s61, s33
	s_add_i32 s5, s5, s4
	s_mul_i32 s4, s61, s33
	s_add_u32 s18, s4, s34
	s_addc_u32 s19, s5, s42
	v_mov_b64_e32 v[2:3], 0x18c0
	v_cmp_lt_i64_e64 s[4:5], s[18:19], v[2:3]
	v_mov_b64_e32 v[2:3], 0x18bf
	v_cmp_gt_i64_e32 vcc, s[18:19], v[2:3]
	s_cbranch_vccnz .LBB0_215
	s_ashr_i32 s12, s18, 31
	s_lshr_b32 s12, s12, 29
	s_add_i32 s12, s18, s12
	s_ashr_i32 s13, s12, 3
	s_and_b32 s12, s12, -8
	s_sub_i32 s12, s18, s12
	s_cmp_lt_i32 s12, 0
	s_movk_i32 s14, 0x319
	s_cselect_b32 s14, s14, 0x318
	s_mul_i32 s12, s12, s14
	s_add_i32 s12, s12, s13
	s_cmpk_lt_i32 s12, 0x18c0
	s_cselect_b32 s13, 0xb0, 4
	v_cvt_f32_ubyte0_e32 v2, s13
	v_rcp_iflag_f32_e32 v2, v2
	s_cselect_b32 s14, 0, 0xffffe740
	s_cselect_b32 s15, 0x90, 0
	s_sub_i32 s19, 0, s13
	v_mul_f32_e32 v2, 0x4f7ffffe, v2
	v_cvt_u32_f32_e32 v2, v2
	s_add_i32 s14, s14, s12
	s_abs_i32 s18, s14
	s_ashr_i32 s12, s14, 31
	v_readfirstlane_b32 s20, v2
	s_mul_i32 s19, s19, s20
	s_mul_hi_u32 s19, s20, s19
	s_add_i32 s20, s20, s19
	s_mul_hi_u32 s19, s18, s20
	s_mul_i32 s20, s19, s13
	s_sub_i32 s18, s18, s20
	s_add_i32 s20, s19, 1
	s_sub_i32 s21, s18, s13
	s_cmp_ge_u32 s18, s13
	s_cselect_b32 s19, s20, s19
	s_cselect_b32 s18, s21, s18
	s_add_i32 s20, s19, 1
	s_cmp_ge_u32 s18, s13
	s_cselect_b32 s18, s20, s19
	s_xor_b32 s18, s18, s12
	s_sub_i32 s12, s18, s12
	s_lshl_b32 s18, s12, 2
	s_sub_i32 s15, s15, s18
	s_min_i32 s15, s15, 4
	s_abs_i32 s19, s15
	v_cvt_f32_u32_e32 v2, s19
	s_sub_i32 s20, 0, s19
	s_mul_i32 s12, s12, s13
	s_sub_i32 s13, s14, s12
	v_rcp_iflag_f32_e32 v2, v2
	s_abs_i32 s12, s13
	s_xor_b32 s14, s13, s15
	s_ashr_i32 s14, s14, 31
	v_mul_f32_e32 v2, 0x4f7ffffe, v2
	v_cvt_u32_f32_e32 v2, v2
	s_nop 0
	v_readfirstlane_b32 s21, v2
	s_mul_i32 s20, s20, s21
	s_mul_hi_u32 s20, s21, s20
	s_add_i32 s21, s21, s20
	s_mul_hi_u32 s20, s12, s21
	s_mul_i32 s21, s20, s19
	s_sub_i32 s12, s12, s21
	s_add_i32 s21, s20, 1
	s_sub_i32 s26, s12, s19
	s_cmp_ge_u32 s12, s19
	s_cselect_b32 s20, s21, s20
	s_cselect_b32 s12, s26, s12
	s_add_i32 s21, s20, 1
	s_cmp_ge_u32 s12, s19
	s_cselect_b32 s12, s21, s20
	s_xor_b32 s12, s12, s14
	s_sub_i32 s12, s12, s14
	s_mul_i32 s14, s12, s15
	s_sub_i32 s13, s13, s14
	s_add_i32 s14, s13, s18

; #define PG8_BAR __builtin_amdgcn_s_barrier()
;     __device__ __forceinline__ bool next(int i, Unit& u) const {
;         const long L = (long)i * G + c; if (L >= total) return false;
;         if (nM1 == 144 && nN1 == 8 && nM2 == 0 && G == 256) {
;             const int xcd = c & 7, o = c >> 3;
;             const int grp = (i < 4) ? xcd * 4 + i : 32 + (xcd >> 1), idx = (i < 4) ? o : (xcd & 1) * 16 + o;
;             u.pm = grp * 4 + (idx & 3); u.pn = idx >> 2; return true; }
;         int w = (int)L; { const int q = total / NXCD, r = total % NXCD, xcd = w % NXCD, off = w / NXCD; w = (xcd < r ? xcd * (q + 1) : r * (q + 1) + (xcd - r) * q) + off; }
;         int nM = nM1, nN = nN1; const bool second = w >= n1; if (second) { w -= n1; nM = nM2; nN = nN2; }
;         const int wgm = 4;
;         const int nig = wgm * nN, gid = w / nig, fm = gid * wgm, gsz = (nM - fm) < wgm ? (nM - fm) : wgm;
;         int pm = fm + ((w % nig) % gsz), pn = (w % nig) / gsz;
;         if (second) { pm += pm2; pn = pn < split ? a0 + pn : a1 + pn; }
;         u.pm = pm; u.pn = pn; return true;
;     }
; template <class Epi, class Sched, bool ALIGN_EPI = false, bool SP2 = false, bool ABLK = false, bool BBLK = false>
; __device__ __forceinline__ void gemm_phase(PG8_LAS unsigned char* lds, const Gemm g, const Sched& S, const Epi& E) {
;     ...
;             PG8_LDB(B0, 0, 0); PG8_LDB(B1, 0, 1); PG8_SCHED; PG8_LDA(At, 0, 0); PG8_STAGE(PG8_SA(1, 1), a1 + hstepA, voffA);
;             PG8_WAIT_V(8); PG8_WAIT_L(0); PG8_BAR; PG8_MMA(0, 0, At, B0); PG8_MMA(0, 1, At, B1); PG8_BAR; PG8_SCHED;
;             PG8_LDA(At, 0, 1); PG8_STAGE(PG8_SB(0, 0), b2, voffB); PG8_STAGE(PG8_SB(0, 1), b2 + hstepB, voffB); PG8_STAGE(PG8_SA(0, 0), a2, voffA);
;             PG8_WAIT_V(8); PG8_WAIT_L(0); PG8_BAR; PG8_MMA(1, 0, At, B0); PG8_MMA(1, 1, At, B1); PG8_BAR; PG8_SCHED;
;             PG8_LDB(B0, 1, 0); PG8_LDB(B1, 1, 1); PG8_SCHED; PG8_LDA(At, 1, 0); PG8_STAGE(PG8_SA(0, 1), a2 + hstepA, voffA);
;             PG8_WAIT_V(8); PG8_WAIT_L(0); PG8_BAR; PG8_MMA(0, 0, At, B0); PG8_MMA(0, 1, At, B1); PG8_BAR; PG8_SCHED;
;             PG8_LDA(At, 1, 1); PG8_STAGE(PG8_SB(1, 0), b3, voffB); PG8_STAGE(PG8_SB(1, 1), b3 + hstepB, voffB); PG8_STAGE(PG8_SA(1, 0), a3, voffA);
;             PG8_WAIT_V(8); PG8_WAIT_L(0); PG8_BAR; PG8_MMA(1, 0, At, B0); PG8_MMA(1, 1, At, B1); PG8_BAR; PG8_SCHED;
;             } else {
.Ly_216:
	v_pk_mov_b32 v[2:3], 0, 0
	v_pk_mov_b32 v[4:5], 0, 0
	v_pk_mov_b32 v[6:7], 0, 0
	v_pk_mov_b32 v[8:9], 0, 0
	v_pk_mov_b32 v[10:11], 0, 0
	v_pk_mov_b32 v[12:13], 0, 0
	v_pk_mov_b32 v[14:15], 0, 0
	v_pk_mov_b32 v[16:17], 0, 0
	v_pk_mov_b32 v[18:19], 0, 0
	v_pk_mov_b32 v[20:21], 0, 0
	v_pk_mov_b32 v[22:23], 0, 0
	v_pk_mov_b32 v[24:25], 0, 0
	v_pk_mov_b32 v[26:27], 0, 0
	v_pk_mov_b32 v[28:29], 0, 0
	v_pk_mov_b32 v[30:31], 0, 0
	v_pk_mov_b32 v[32:33], 0, 0
	v_pk_mov_b32 v[34:35], 0, 0
	v_pk_mov_b32 v[36:37], 0, 0
	v_pk_mov_b32 v[38:39], 0, 0
	v_pk_mov_b32 v[40:41], 0, 0
	v_pk_mov_b32 v[42:43], 0, 0
	v_pk_mov_b32 v[44:45], 0, 0
	v_pk_mov_b32 v[46:47], 0, 0
	v_pk_mov_b32 v[48:49], 0, 0
	v_pk_mov_b32 v[50:51], 0, 0
	v_pk_mov_b32 v[52:53], 0, 0
	v_pk_mov_b32 v[54:55], 0, 0
	v_pk_mov_b32 v[56:57], 0, 0
	v_pk_mov_b32 v[58:59], 0, 0
	v_pk_mov_b32 v[60:61], 0, 0
	v_pk_mov_b32 v[62:63], 0, 0
	v_pk_mov_b32 v[64:65], 0, 0
	v_pk_mov_b32 v[66:67], 0, 0
	v_pk_mov_b32 v[68:69], 0, 0
	v_pk_mov_b32 v[70:71], 0, 0
	v_pk_mov_b32 v[72:73], 0, 0
	v_pk_mov_b32 v[74:75], 0, 0
	v_pk_mov_b32 v[76:77], 0, 0
	v_pk_mov_b32 v[78:79], 0, 0
	v_pk_mov_b32 v[80:81], 0, 0
	v_pk_mov_b32 v[82:83], 0, 0
	v_pk_mov_b32 v[84:85], 0, 0
	v_pk_mov_b32 v[86:87], 0, 0
	v_pk_mov_b32 v[88:89], 0, 0
	v_pk_mov_b32 v[90:91], 0, 0
	v_pk_mov_b32 v[92:93], 0, 0
	v_pk_mov_b32 v[94:95], 0, 0
	v_pk_mov_b32 v[96:97], 0, 0
	v_pk_mov_b32 v[98:99], 0, 0
	v_pk_mov_b32 v[100:101], 0, 0
	v_pk_mov_b32 v[102:103], 0, 0
	v_pk_mov_b32 v[104:105], 0, 0
	v_pk_mov_b32 v[106:107], 0, 0
	v_pk_mov_b32 v[108:109], 0, 0
	v_pk_mov_b32 v[110:111], 0, 0
	v_pk_mov_b32 v[112:113], 0, 0
	v_pk_mov_b32 v[114:115], 0, 0
	v_pk_mov_b32 v[116:117], 0, 0
	v_pk_mov_b32 v[118:119], 0, 0
	v_pk_mov_b32 v[120:121], 0, 0
	v_pk_mov_b32 v[122:123], 0, 0
	v_pk_mov_b32 v[124:125], 0, 0
	v_pk_mov_b32 v[126:127], 0, 0
	v_pk_mov_b32 v[128:129], 0, 0
	s_add_i32 s61, s61, 1
	s_mul_i32 s4, s61, s60
	s_mul_hi_u32 s5, s61, s33
	s_add_i32 s5, s5, s4
	s_mul_i32 s4, s61, s33
	s_add_u32 s18, s4, s34
	s_addc_u32 s19, s5, s42
	v_mov_b64_e32 v[2:3], 0x18c0
	v_cmp_lt_i64_e64 s[4:5], s[18:19], v[2:3]
	v_mov_b64_e32 v[2:3], 0x18bf
	v_cmp_gt_i64_e32 vcc, s[18:19], v[2:3]
	s_cbranch_vccnz .Lyh216_215
	s_ashr_i32 s12, s18, 31
	s_lshr_b32 s12, s12, 29
	s_add_i32 s12, s18, s12
	s_ashr_i32 s13, s12, 3
	s_and_b32 s12, s12, -8
	s_sub_i32 s12, s18, s12
	s_cmp_lt_i32 s12, 0
	s_movk_i32 s14, 0x319
	s_cselect_b32 s14, s14, 0x318
	s_mul_i32 s12, s12, s14
	s_add_i32 s12, s12, s13
	s_cmpk_lt_i32 s12, 0x18c0
	s_cselect_b32 s13, 0xb0, 4
	v_cvt_f32_ubyte0_e32 v2, s13
	v_rcp_iflag_f32_e32 v2, v2
	s_cselect_b32 s14, 0, 0xffffe740
	s_cselect_b32 s15, 0x90, 0
	s_sub_i32 s19, 0, s13
	v_mul_f32_e32 v2, 0x4f7ffffe, v2
	v_cvt_u32_f32_e32 v2, v2
	s_add_i32 s14, s14, s12
	s_abs_i32 s18, s14
	s_ashr_i32 s12, s14, 31
	v_readfirstlane_b32 s20, v2
	s_mul_i32 s19, s19, s20
	s_mul_hi_u32 s19, s20, s19
	s_add_i32 s20, s20, s19
	s_mul_hi_u32 s19, s18, s20
	s_mul_i32 s20, s19, s13
	s_sub_i32 s18, s18, s20
	s_add_i32 s20, s19, 1
	s_sub_i32 s21, s18, s13
	s_cmp_ge_u32 s18, s13
	s_cselect_b32 s19, s20, s19
	s_cselect_b32 s18, s21, s18
	s_add_i32 s20, s19, 1
	s_cmp_ge_u32 s18, s13
	s_cselect_b32 s18, s20, s19
	s_xor_b32 s18, s18, s12
	s_sub_i32 s12, s18, s12
	s_lshl_b32 s18, s12, 2
	s_sub_i32 s15, s15, s18
	s_min_i32 s15, s15, 4
	s_abs_i32 s19, s15
	v_cvt_f32_u32_e32 v2, s19
	s_sub_i32 s20, 0, s19
	s_mul_i32 s12, s12, s13
	s_sub_i32 s13, s14, s12
	v_rcp_iflag_f32_e32 v2, v2
	s_abs_i32 s12, s13
	s_xor_b32 s14, s13, s15
	s_ashr_i32 s14, s14, 31
	v_mul_f32_e32 v2, 0x4f7ffffe, v2
	v_cvt_u32_f32_e32 v2, v2
	s_nop 0
	v_readfirstlane_b32 s21, v2
	s_mul_i32 s20, s20, s21
	s_mul_hi_u32 s20, s21, s20
	s_add_i32 s21, s21, s20
	s_mul_hi_u32 s20, s12, s21
	s_mul_i32 s21, s20, s19
	s_sub_i32 s12, s12, s21
	s_add_i32 s21, s20, 1
	s_sub_i32 s26, s12, s19
	s_cmp_ge_u32 s12, s19
	s_cselect_b32 s20, s21, s20
	s_cselect_b32 s12, s26, s12
	s_add_i32 s21, s20, 1
	s_cmp_ge_u32 s12, s19
	s_cselect_b32 s12, s21, s20
	s_xor_b32 s12, s12, s14
	s_sub_i32 s12, s12, s14
	s_mul_i32 s14, s12, s15
	s_sub_i32 s13, s13, s14
	s_add_i32 s14, s13, s18
.Lyh216_215:
	s_ashr_i32 s15, s14, 31
	s_lshl_b64 s[18:19], s[14:15], 20
	s_add_u32 s18, s35, s18
	s_addc_u32 s19, s36, s19
	s_and_b64 s[20:21], s[4:5], exec
	s_cselect_b32 s15, s19, s23
	s_cselect_b32 s65, s18, s22
	s_ashr_i32 s13, s12, 31
	s_lshl_b64 s[20:21], s[12:13], 20
	s_add_u32 s20, s37, s20
	s_addc_u32 s21, s40, s21
	s_and_b64 s[26:27], s[4:5], exec
	s_cselect_b32 s13, s21, s25
	s_cselect_b32 s68, s20, s24
	s_add_u32 s22, s22, 0xc000
	s_addc_u32 s23, s23, 0
	s_add_u32 s72, s24, 0x10000
	v_mov_b32_e32 v2, 0
	s_addc_u32 s73, s25, 0
	s_mov_b32 s81, -2
	v_pk_mov_b32 v[2:3], 0, 0
	s_barrier
	s_add_u32 s24, s22, 0x4000
	s_addc_u32 s25, s23, 0
	s_cmp_eq_u32 s81, 28
	s_cselect_b32 s28, s65, s24
	s_cselect_b32 s29, s15, s25
	s_cselect_b32 s26, s68, s72
	s_cselect_b32 s27, s13, s73
	s_add_u32 s24, s28, 0x8000
	s_addc_u32 s25, s29, 0
	s_add_i32 s75, 0, 0x10000
	v_add_u32_e32 v142, s75, v145
	s_add_i32 s80, 0, 0x14000
	ds_read_b128 v[148:151], v142
	ds_read_b128 v[152:155], v142 offset:1024
	ds_read_b128 v[156:159], v142 offset:2048
	ds_read_b128 v[160:163], v142 offset:3072
	v_add_u32_e32 v142, s80, v145
	ds_read_b128 v[164:167], v142
	ds_read_b128 v[168:171], v142 offset:1024
	ds_read_b128 v[172:175], v142 offset:2048
	ds_read_b128 v[176:179], v142 offset:3072
	v_lshl_add_u64 v[142:143], s[22:23], 0, v[138:139]
	s_add_i32 m0, s43, 0xc000
	ds_read_b128 v[180:183], v146
	ds_read_b128 v[196:199], v146 offset:1024
	ds_read_b128 v[200:203], v146 offset:2048
	ds_read_b128 v[204:207], v146 offset:3072
	ds_read_b128 v[208:211], v146 offset:4096
	ds_read_b128 v[212:215], v146 offset:5120
	ds_read_b128 v[216:219], v146 offset:6144
	ds_read_b128 v[220:223], v146 offset:7168
	global_load_lds_dwordx4 v[142:143], off
	v_lshl_add_u64 v[142:143], s[22:23], 0, v[140:141]
	s_add_i32 m0, s43, 0xe000
	s_nop 0
	global_load_lds_dwordx4 v[142:143], off
	s_waitcnt vmcnt(8)
	s_waitcnt lgkmcnt(0)
	s_barrier
	s_branch .Lpeel_216

;     __device__ __forceinline__ bool next(int i, Unit& u) const {
;         const long L = (long)i * G + c; if (L >= total) return false;
;         if (nM1 == 144 && nN1 == 8 && nM2 == 0 && G == 256) {
;             const int xcd = c & 7, o = c >> 3;
;             const int grp = (i < 4) ? xcd * 4 + i : 32 + (xcd >> 1), idx = (i < 4) ? o : (xcd & 1) * 16 + o;
;             u.pm = grp * 4 + (idx & 3); u.pn = idx >> 2; return true; }
;         int w = (int)L; { const int q = total / NXCD, r = total % NXCD, xcd = w % NXCD, off = w / NXCD; w = (xcd < r ? xcd * (q + 1) : r * (q + 1) + (xcd - r) * q) + off; }
;         int nM = nM1, nN = nN1; const bool second = w >= n1; if (second) { w -= n1; nM = nM2; nN = nN2; }
;         const int wgm = 4;
;         const int nig = wgm * nN, gid = w / nig, fm = gid * wgm, gsz = (nM - fm) < wgm ? (nM - fm) : wgm;
;         int pm = fm + ((w % nig) % gsz), pn = (w % nig) / gsz;
;         if (second) { pm += pm2; pn = pn < split ? a0 + pn : a1 + pn; }
;         u.pm = pm; u.pn = pn; return true;
;     }
.LBB0_295:
	s_and_b64 vcc, exec, s[18:19]
	s_cbranch_vccz .Ly_305
	s_add_i32 s5, s26, 1
	s_mul_i32 s6, s5, s96
	s_mul_hi_u32 s7, s5, s50
	s_add_i32 s7, s7, s6
	s_mul_i32 s6, s5, s50
	s_add_u32 s6, s6, s51
	s_addc_u32 s7, s7, s97
	v_mov_b64_e32 v[2:3], 0x480
	v_cmp_lt_i64_e64 s[8:9], s[6:7], v[2:3]
	v_mov_b64_e32 v[2:3], 0x47f
	v_cmp_gt_i64_e32 vcc, s[6:7], v[2:3]
	s_cbranch_vccnz .LBB0_300
	s_mov_b64 s[24:25], -1
	s_and_b64 vcc, exec, s[22:23]
	s_cbranch_vccz .LBB0_298
	s_ashr_i32 s7, s6, 31
	s_lshr_b32 s7, s7, 29
	s_add_i32 s7, s6, s7
	s_ashr_i32 s24, s7, 3
	s_and_b32 s7, s7, -8
	s_sub_i32 s6, s6, s7
	s_cmp_lt_i32 s6, 0
	s_movk_i32 s7, 0x91
	s_cselect_b32 s7, s7, 0x90
	s_mul_i32 s6, s6, s7
	s_add_i32 s6, s6, s24
	s_cmpk_lt_i32 s6, 0x480
	s_cselect_b32 s7, 32, 4
	v_cvt_f32_ubyte0_e32 v2, s7
	v_rcp_iflag_f32_e32 v2, v2
	s_cselect_b32 s24, 0, 0xfffffb80
	s_cselect_b32 s25, 0x90, 0
	s_sub_i32 s29, 0, s7
	v_mul_f32_e32 v2, 0x4f7ffffe, v2
	v_cvt_u32_f32_e32 v2, v2
	s_add_i32 s24, s24, s6
	s_abs_i32 s27, s24
	s_ashr_i32 s6, s24, 31
	v_readfirstlane_b32 s31, v2
	s_mul_i32 s29, s29, s31
	s_mul_hi_u32 s29, s31, s29
	s_add_i32 s31, s31, s29
	s_mul_hi_u32 s29, s27, s31
	s_mul_i32 s31, s29, s7
	s_sub_i32 s27, s27, s31
	s_add_i32 s31, s29, 1
	s_sub_i32 s33, s27, s7
	s_cmp_ge_u32 s27, s7
	s_cselect_b32 s29, s31, s29
	s_cselect_b32 s27, s33, s27
	s_add_i32 s31, s29, 1
	s_cmp_ge_u32 s27, s7
	s_cselect_b32 s27, s31, s29
	s_xor_b32 s27, s27, s6
	s_sub_i32 s6, s27, s6
	s_lshl_b32 s27, s6, 2
	s_sub_i32 s25, s25, s27
	s_min_i32 s25, s25, 4
	s_abs_i32 s29, s25
	v_cvt_f32_u32_e32 v2, s29
	s_sub_i32 s31, 0, s29
	s_mul_i32 s6, s6, s7
	s_sub_i32 s6, s24, s6
	v_rcp_iflag_f32_e32 v2, v2
	s_abs_i32 s7, s6
	s_xor_b32 s24, s6, s25
	s_ashr_i32 s24, s24, 31
	v_mul_f32_e32 v2, 0x4f7ffffe, v2
	v_cvt_u32_f32_e32 v2, v2
	s_nop 0
	v_readfirstlane_b32 s33, v2
	s_mul_i32 s31, s31, s33
	s_mul_hi_u32 s31, s33, s31
	s_add_i32 s33, s33, s31
	s_mul_hi_u32 s31, s7, s33
	s_mul_i32 s33, s31, s29
	s_sub_i32 s7, s7, s33
	s_add_i32 s33, s31, 1
	s_sub_i32 s36, s7, s29
	s_cmp_ge_u32 s7, s29
	s_cselect_b32 s31, s33, s31
	s_cselect_b32 s7, s36, s7
	s_add_i32 s33, s31, 1
	s_cmp_ge_u32 s7, s29
	s_cselect_b32 s7, s33, s31
	s_xor_b32 s7, s7, s24
	s_sub_i32 s88, s7, s24
	s_mul_i32 s7, s88, s25
	s_sub_i32 s6, s6, s7
	s_add_i32 s89, s6, s27
	s_mov_b64 s[24:25], 0

;     __device__ __forceinline__ bool next(int i, Unit& u) const {
;         const long L = (long)i * G + c; if (L >= total) return false;
;         if (nM1 == 144 && nN1 == 8 && nM2 == 0 && G == 256) {
;             const int xcd = c & 7, o = c >> 3;
;             const int grp = (i < 4) ? xcd * 4 + i : 32 + (xcd >> 1), idx = (i < 4) ? o : (xcd & 1) * 16 + o;
;             u.pm = grp * 4 + (idx & 3); u.pn = idx >> 2; return true; }
;         int w = (int)L; { const int q = total / NXCD, r = total % NXCD, xcd = w % NXCD, off = w / NXCD; w = (xcd < r ? xcd * (q + 1) : r * (q + 1) + (xcd - r) * q) + off; }
;         int nM = nM1, nN = nN1; const bool second = w >= n1; if (second) { w -= n1; nM = nM2; nN = nN2; }
;         const int wgm = 4;
;         const int nig = wgm * nN, gid = w / nig, fm = gid * wgm, gsz = (nM - fm) < wgm ? (nM - fm) : wgm;
;         int pm = fm + ((w % nig) % gsz), pn = (w % nig) / gsz;
;         if (second) { pm += pm2; pn = pn < split ? a0 + pn : a1 + pn; }
;         u.pm = pm; u.pn = pn; return true;
;     }
; template <class Epi, class Sched, bool ALIGN_EPI = false, bool SP2 = false, bool ABLK = false, bool BBLK = false>
; __device__ __forceinline__ void gemm_phase(PG8_LAS unsigned char* lds, const Gemm g, const Sched& S, const Epi& E) {
;     ...
; #pragma unroll
;         for (int a = 0; a < 2; ++a)
; #pragma unroll
;             for (int b = 0; b < 2; ++b)
; #pragma unroll
;                 for (int m = 0; m < 4; ++m)
; #pragma unroll
;                     for (int n = 0; n < 2; ++n) acc[a][b][m][n] = (f32x4){0.f, 0.f, 0.f, 0.f};
.Ly_305:
	v_pk_mov_b32 v[2:3], 0, 0
	v_pk_mov_b32 v[4:5], 0, 0
	v_pk_mov_b32 v[6:7], 0, 0
	v_pk_mov_b32 v[8:9], 0, 0
	v_pk_mov_b32 v[10:11], 0, 0
	v_pk_mov_b32 v[12:13], 0, 0
	v_pk_mov_b32 v[14:15], 0, 0
	v_pk_mov_b32 v[16:17], 0, 0
	v_pk_mov_b32 v[18:19], 0, 0
	v_pk_mov_b32 v[20:21], 0, 0
	v_pk_mov_b32 v[22:23], 0, 0
	v_pk_mov_b32 v[24:25], 0, 0
	v_pk_mov_b32 v[26:27], 0, 0
	v_pk_mov_b32 v[28:29], 0, 0
	v_pk_mov_b32 v[30:31], 0, 0
	v_pk_mov_b32 v[32:33], 0, 0
	v_pk_mov_b32 v[34:35], 0, 0
	v_pk_mov_b32 v[36:37], 0, 0
	v_pk_mov_b32 v[38:39], 0, 0
	v_pk_mov_b32 v[40:41], 0, 0
	v_pk_mov_b32 v[42:43], 0, 0
	v_pk_mov_b32 v[44:45], 0, 0
	v_pk_mov_b32 v[46:47], 0, 0
	v_pk_mov_b32 v[48:49], 0, 0
	v_pk_mov_b32 v[50:51], 0, 0
	v_pk_mov_b32 v[52:53], 0, 0
	v_pk_mov_b32 v[54:55], 0, 0
	v_pk_mov_b32 v[56:57], 0, 0
	v_pk_mov_b32 v[58:59], 0, 0
	v_pk_mov_b32 v[60:61], 0, 0
	v_pk_mov_b32 v[62:63], 0, 0
	v_pk_mov_b32 v[64:65], 0, 0
	v_pk_mov_b32 v[66:67], 0, 0
	v_pk_mov_b32 v[68:69], 0, 0
	v_pk_mov_b32 v[70:71], 0, 0
	v_pk_mov_b32 v[72:73], 0, 0
	v_pk_mov_b32 v[74:75], 0, 0
	v_pk_mov_b32 v[76:77], 0, 0
	v_pk_mov_b32 v[78:79], 0, 0
	v_pk_mov_b32 v[80:81], 0, 0
	v_pk_mov_b32 v[82:83], 0, 0
	v_pk_mov_b32 v[84:85], 0, 0
	v_pk_mov_b32 v[86:87], 0, 0
	v_pk_mov_b32 v[88:89], 0, 0
	v_pk_mov_b32 v[90:91], 0, 0
	v_pk_mov_b32 v[92:93], 0, 0
	v_pk_mov_b32 v[94:95], 0, 0
	v_pk_mov_b32 v[96:97], 0, 0
	v_pk_mov_b32 v[98:99], 0, 0
	v_pk_mov_b32 v[100:101], 0, 0
	v_pk_mov_b32 v[102:103], 0, 0
	v_pk_mov_b32 v[104:105], 0, 0
	v_pk_mov_b32 v[106:107], 0, 0
	v_pk_mov_b32 v[108:109], 0, 0
	v_pk_mov_b32 v[110:111], 0, 0
	v_pk_mov_b32 v[112:113], 0, 0
	v_pk_mov_b32 v[114:115], 0, 0
	v_pk_mov_b32 v[116:117], 0, 0
	v_pk_mov_b32 v[118:119], 0, 0
	v_pk_mov_b32 v[120:121], 0, 0
	v_pk_mov_b32 v[122:123], 0, 0
	v_pk_mov_b32 v[124:125], 0, 0
	v_pk_mov_b32 v[126:127], 0, 0
	v_pk_mov_b32 v[128:129], 0, 0
	s_add_i32 s5, s26, 1
	s_mul_i32 s6, s5, s96
	s_mul_hi_u32 s7, s5, s50
	s_add_i32 s7, s7, s6
	s_mul_i32 s6, s5, s50
	s_add_u32 s6, s6, s51
	s_addc_u32 s7, s7, s97
	v_mov_b64_e32 v[2:3], 0x480
	v_cmp_lt_i64_e64 s[8:9], s[6:7], v[2:3]
	v_mov_b64_e32 v[2:3], 0x47f
	v_cmp_gt_i64_e32 vcc, s[6:7], v[2:3]
	s_cbranch_vccnz .Lyh305_300
	s_mov_b64 s[24:25], -1
	s_and_b64 vcc, exec, s[22:23]
	s_cbranch_vccz .Lyh305_298
	s_ashr_i32 s7, s6, 31
	s_lshr_b32 s7, s7, 29
	s_add_i32 s7, s6, s7
	s_ashr_i32 s24, s7, 3
	s_and_b32 s7, s7, -8
	s_sub_i32 s6, s6, s7
	s_cmp_lt_i32 s6, 0
	s_movk_i32 s7, 0x91
	s_cselect_b32 s7, s7, 0x90
	s_mul_i32 s6, s6, s7
	s_add_i32 s6, s6, s24
	s_cmpk_lt_i32 s6, 0x480
	s_cselect_b32 s7, 32, 4
	v_cvt_f32_ubyte0_e32 v2, s7
	v_rcp_iflag_f32_e32 v2, v2
	s_cselect_b32 s24, 0, 0xfffffb80
	s_cselect_b32 s25, 0x90, 0
	s_sub_i32 s29, 0, s7
	v_mul_f32_e32 v2, 0x4f7ffffe, v2
	v_cvt_u32_f32_e32 v2, v2
	s_add_i32 s24, s24, s6
	s_abs_i32 s27, s24
	s_ashr_i32 s6, s24, 31
	v_readfirstlane_b32 s31, v2
	s_mul_i32 s29, s29, s31
	s_mul_hi_u32 s29, s31, s29
	s_add_i32 s31, s31, s29
	s_mul_hi_u32 s29, s27, s31
	s_mul_i32 s31, s29, s7
	s_sub_i32 s27, s27, s31
	s_add_i32 s31, s29, 1
	s_sub_i32 s33, s27, s7
	s_cmp_ge_u32 s27, s7
	s_cselect_b32 s29, s31, s29
	s_cselect_b32 s27, s33, s27
	s_add_i32 s31, s29, 1
	s_cmp_ge_u32 s27, s7
	s_cselect_b32 s27, s31, s29
	s_xor_b32 s27, s27, s6
	s_sub_i32 s6, s27, s6
	s_lshl_b32 s27, s6, 2
	s_sub_i32 s25, s25, s27
	s_min_i32 s25, s25, 4
	s_abs_i32 s29, s25
	v_cvt_f32_u32_e32 v2, s29
	s_sub_i32 s31, 0, s29
	s_mul_i32 s6, s6, s7
	s_sub_i32 s6, s24, s6
	v_rcp_iflag_f32_e32 v2, v2
	s_abs_i32 s7, s6
	s_xor_b32 s24, s6, s25
	s_ashr_i32 s24, s24, 31
	v_mul_f32_e32 v2, 0x4f7ffffe, v2
	v_cvt_u32_f32_e32 v2, v2
	s_nop 0
	v_readfirstlane_b32 s33, v2
	s_mul_i32 s31, s31, s33
	s_mul_hi_u32 s31, s33, s31
	s_add_i32 s33, s33, s31
	s_mul_hi_u32 s31, s7, s33
	s_mul_i32 s33, s31, s29
	s_sub_i32 s7, s7, s33
	s_add_i32 s33, s31, 1
	s_sub_i32 s36, s7, s29
	s_cmp_ge_u32 s7, s29
	s_cselect_b32 s31, s33, s31
	s_cselect_b32 s7, s36, s7
	s_add_i32 s33, s31, 1
	s_cmp_ge_u32 s7, s29
	s_cselect_b32 s7, s33, s31
	s_xor_b32 s7, s7, s24
	s_sub_i32 s88, s7, s24
	s_mul_i32 s7, s88, s25
	s_sub_i32 s6, s6, s7
	s_add_i32 s89, s6, s27
	s_mov_b64 s[24:25], 0

; #define PG8_STAGE(bufoff, gbase, voff) do { _Pragma("unroll") for (int _i = 0; _i < 2; ++_i) \
;         __builtin_amdgcn_global_load_lds((const unsigned*)((const char*)(gbase) + (voff)[_i]), (PG8_LAS unsigned*)(lds + (bufoff) + ldsw + _i * 8192), 16, 0, 0); } while (0)
; #define PG8_LDA(dst, b, h) do { _Pragma("unroll") for (int m = 0; m < 4; ++m) _Pragma("unroll") for (int k = 0; k < 2; ++k) dst[m][k] = *(const PG8_LAS bf16x8*)(lds + PG8_SA(b, h) + aoff + m * 2048 + k * 1024); } while (0)
; #define PG8_LDB(dst, b, h) do { _Pragma("unroll") for (int n = 0; n < 2; ++n) _Pragma("unroll") for (int k = 0; k < 2; ++k) dst[n][k] = *(const PG8_LAS bf16x8*)(lds + PG8_SB(b, h) + boff + n * 2048 + k * 1024); } while (0)
; #define PG8_MMA(ai, bj, At, Bt) do { __builtin_amdgcn_s_setprio(1); _Pragma("unroll") for (int m = 0; m < 4; ++m) _Pragma("unroll") for (int n = 0; n < 2; ++n) _Pragma("unroll") for (int k = 0; k < 2; ++k) \
;         acc[ai][bj][m][n] = __builtin_amdgcn_mfma_f32_16x16x32_bf16(Bt[n][k], At[m][k], acc[ai][bj][m][n], 0, 0, 0); __builtin_amdgcn_s_setprio(0); } while (0)
; #define PG8_WAIT_V(n) asm volatile("s_waitcnt vmcnt(" #n ")" ::: "memory")
; template <class Epi, class Sched, bool ALIGN_EPI = false, bool SP2 = false, bool ABLK = false, bool BBLK = false>
; __device__ __forceinline__ void gemm_phase(PG8_LAS unsigned char* lds, const Gemm g, const Sched& S, const Epi& E) {
;     ...
;         const char* nA = has_next ? (const char*)g.A + (size_t)nxt.pm * tstepA : cA; const char* nB = has_next ? (const char*)g.Bt + (size_t)nxt.pn * tstepB : cB;
;         for (int t = 0; t < nt; t += 2) {
;             const bool last = (t == nt - 2);
;             const char* a1 = cA + (size_t)(t + 1) * kstepA;
;             const char* a2 = last ? nA : cA + (size_t)(t + 2) * kstepA; const char* b2 = last ? nB : cB + (size_t)(t + 2) * kstepB;
;             const char* a3 = a2 + kstepA; const char* b3 = b2 + kstepB;
;             if (last && has_next) S.a_ready(nxt);
;             if constexpr (SP2) {
;             PG8_LDB(B0, 0, 0); PG8_LDB(B1, 0, 1); PG8_SCHED; PG8_LDA(At, 0, 0); PG8_STAGE(PG8_SA(1, 1), a1 + hstepA, voffA);
;             PG8_WAIT_V(8); PG8_WAIT_L(0); PG8_BAR; PG8_MMA(0, 0, At, B0); PG8_MMA(0, 1, At, B1); PG8_BAR; PG8_SCHED;
;     ...
;         cur = nxt; cA = nA; cB = nB; ++ui;
;         if constexpr (ALIGN_EPI) { if (wr == 1) PG8_BAR; }
.Lyh305_304:
	s_add_u32 s0, s0, 0xc000
	s_addc_u32 s1, s1, 0
	s_add_u32 s29, s34, 0x10000
	v_mov_b32_e32 v2, 0
	s_addc_u32 s31, s35, 0
	s_mov_b32 s33, -2
	v_pk_mov_b32 v[2:3], 0, 0
	s_barrier
	s_add_u32 s8, s0, 0x4000
	s_addc_u32 s9, s1, 0
	s_cmpk_eq_i32 s33, 0x54
	s_cselect_b32 s36, s24, s8
	s_cselect_b32 s37, s25, s9
	s_cselect_b32 s34, s26, s29
	s_cselect_b32 s35, s27, s31
	s_add_u32 s8, s36, 0x8000
	s_addc_u32 s9, s37, 0
	s_add_i32 s40, 0, 0x10000
	s_add_i32 s44, 0, 0x14000
	v_add_u32_e32 v142, s40, v206
	v_add_u32_e32 v158, s44, v206
	ds_read_b128 v[130:133], v142
	ds_read_b128 v[134:137], v142 offset:1024
	ds_read_b128 v[138:141], v142 offset:2048
	ds_read_b128 v[142:145], v142 offset:3072
	ds_read_b128 v[146:149], v158
	ds_read_b128 v[150:153], v158 offset:1024
	ds_read_b128 v[154:157], v158 offset:2048
	ds_read_b128 v[158:161], v158 offset:3072
	v_lshl_add_u64 v[202:203], s[0:1], 0, v[184:185]
	s_add_i32 m0, s3, 0xc000
	ds_read_b128 v[162:165], v207
	ds_read_b128 v[166:169], v207 offset:1024
	ds_read_b128 v[170:173], v207 offset:2048
	ds_read_b128 v[174:177], v207 offset:3072
	ds_read_b128 v[198:201], v207 offset:4096
	ds_read_b128 v[208:211], v207 offset:5120
	ds_read_b128 v[212:215], v207 offset:6144
	ds_read_b128 v[216:219], v207 offset:7168
	global_load_lds_dwordx4 v[202:203], off
	v_lshl_add_u64 v[202:203], s[0:1], 0, v[196:197]
	s_add_i32 m0, s3, 0xe000
	s_nop 0
	global_load_lds_dwordx4 v[202:203], off
	s_waitcnt vmcnt(8)
	s_waitcnt lgkmcnt(0)
	s_barrier
	s_branch .Lpeel_305

;     __device__ __forceinline__ bool next(int i, Unit& u) const {
;         const long L = (long)i * G + c; if (L >= total) return false;
;         if (nM1 == 144 && nN1 == 8 && nM2 == 0 && G == 256) {
;             const int xcd = c & 7, o = c >> 3;
;             const int grp = (i < 4) ? xcd * 4 + i : 32 + (xcd >> 1), idx = (i < 4) ? o : (xcd & 1) * 16 + o;
;             u.pm = grp * 4 + (idx & 3); u.pn = idx >> 2; return true; }
;         int w = (int)L; { const int q = total / NXCD, r = total % NXCD, xcd = w % NXCD, off = w / NXCD; w = (xcd < r ? xcd * (q + 1) : r * (q + 1) + (xcd - r) * q) + off; }
;         int nM = nM1, nN = nN1; const bool second = w >= n1; if (second) { w -= n1; nM = nM2; nN = nN2; }
;         const int wgm = 4;
;         const int nig = wgm * nN, gid = w / nig, fm = gid * wgm, gsz = (nM - fm) < wgm ? (nM - fm) : wgm;
;         int pm = fm + ((w % nig) % gsz), pn = (w % nig) / gsz;
;         if (second) { pm += pm2; pn = pn < split ? a0 + pn : a1 + pn; }
;         u.pm = pm; u.pn = pn; return true;
;     }
.LBB0_357:
	s_and_b64 vcc, exec, s[18:19]
	s_cbranch_vccz .Ly_367
	s_add_i32 s68, s26, 1
	s_mul_i32 s6, s68, s60
	s_mul_hi_u32 s7, s68, s50
	s_add_i32 s7, s7, s6
	s_mul_i32 s6, s68, s50
	s_add_u32 s6, s6, s51
	s_addc_u32 s7, s7, s61
	v_mov_b64_e32 v[2:3], 0x480
	v_cmp_lt_i64_e64 s[8:9], s[6:7], v[2:3]
	v_mov_b64_e32 v[2:3], 0x47f
	v_cmp_gt_i64_e32 vcc, s[6:7], v[2:3]
	s_cbranch_vccnz .LBB0_362
	v_readlane_b32 s36, v254, 55
	v_readlane_b32 s37, v254, 56
	s_mov_b64 s[24:25], -1
	s_and_b64 vcc, exec, s[36:37]
	s_cbranch_vccz .LBB0_360
	s_ashr_i32 s7, s6, 31
	s_lshr_b32 s7, s7, 29
	s_add_i32 s7, s6, s7
	s_ashr_i32 s24, s7, 3
	s_and_b32 s7, s7, -8
	s_sub_i32 s6, s6, s7
	s_cmp_lt_i32 s6, 0
	s_movk_i32 s7, 0x91
	s_cselect_b32 s7, s7, 0x90
	s_mul_i32 s6, s6, s7
	s_add_i32 s6, s6, s24
	s_cmpk_lt_i32 s6, 0x480
	s_cselect_b32 s7, 32, 4
	v_cvt_f32_ubyte0_e32 v2, s7
	v_rcp_iflag_f32_e32 v2, v2
	s_cselect_b32 s24, 0, 0xfffffb80
	s_cselect_b32 s25, 0x90, 0
	s_sub_i32 s29, 0, s7
	v_mul_f32_e32 v2, 0x4f7ffffe, v2
	v_cvt_u32_f32_e32 v2, v2
	s_add_i32 s24, s24, s6
	s_abs_i32 s27, s24
	s_ashr_i32 s6, s24, 31
	v_readfirstlane_b32 s31, v2
	s_mul_i32 s29, s29, s31
	s_mul_hi_u32 s29, s31, s29
	s_add_i32 s31, s31, s29
	s_mul_hi_u32 s29, s27, s31
	s_mul_i32 s31, s29, s7
	s_sub_i32 s27, s27, s31
	s_add_i32 s31, s29, 1
	s_sub_i32 s33, s27, s7
	s_cmp_ge_u32 s27, s7
	s_cselect_b32 s29, s31, s29
	s_cselect_b32 s27, s33, s27
	s_add_i32 s31, s29, 1
	s_cmp_ge_u32 s27, s7
	s_cselect_b32 s27, s31, s29
	s_xor_b32 s27, s27, s6
	s_sub_i32 s6, s27, s6
	s_lshl_b32 s27, s6, 2
	s_sub_i32 s25, s25, s27
	s_min_i32 s25, s25, 4
	s_abs_i32 s29, s25
	v_cvt_f32_u32_e32 v2, s29
	s_sub_i32 s31, 0, s29
	s_mul_i32 s6, s6, s7
	s_sub_i32 s6, s24, s6
	v_rcp_iflag_f32_e32 v2, v2
	s_abs_i32 s7, s6
	s_xor_b32 s24, s6, s25
	s_ashr_i32 s24, s24, 31
	v_mul_f32_e32 v2, 0x4f7ffffe, v2
	v_cvt_u32_f32_e32 v2, v2
	s_nop 0
	v_readfirstlane_b32 s33, v2
	s_mul_i32 s31, s31, s33
	s_mul_hi_u32 s31, s33, s31
	s_add_i32 s33, s33, s31
	s_mul_hi_u32 s31, s7, s33
	s_mul_i32 s33, s31, s29
	s_sub_i32 s7, s7, s33
	s_add_i32 s33, s31, 1
	s_sub_i32 s36, s7, s29
	s_cmp_ge_u32 s7, s29
	s_cselect_b32 s31, s33, s31
	s_cselect_b32 s7, s36, s7
	s_add_i32 s33, s31, 1
	s_cmp_ge_u32 s7, s29
	s_cselect_b32 s7, s33, s31
	s_xor_b32 s7, s7, s24
	s_sub_i32 s72, s7, s24
	s_mul_i32 s7, s72, s25
	s_sub_i32 s6, s6, s7
	s_add_i32 s73, s6, s27
	s_mov_b64 s[24:25], 0

;     __device__ __forceinline__ bool next(int i, Unit& u) const {
;         const long L = (long)i * G + c; if (L >= total) return false;
;         if (nM1 == 144 && nN1 == 8 && nM2 == 0 && G == 256) {
;             const int xcd = c & 7, o = c >> 3;
;             const int grp = (i < 4) ? xcd * 4 + i : 32 + (xcd >> 1), idx = (i < 4) ? o : (xcd & 1) * 16 + o;
;             u.pm = grp * 4 + (idx & 3); u.pn = idx >> 2; return true; }
;         int w = (int)L; { const int q = total / NXCD, r = total % NXCD, xcd = w % NXCD, off = w / NXCD; w = (xcd < r ? xcd * (q + 1) : r * (q + 1) + (xcd - r) * q) + off; }
;         int nM = nM1, nN = nN1; const bool second = w >= n1; if (second) { w -= n1; nM = nM2; nN = nN2; }
;         const int wgm = 4;
;         const int nig = wgm * nN, gid = w / nig, fm = gid * wgm, gsz = (nM - fm) < wgm ? (nM - fm) : wgm;
;         int pm = fm + ((w % nig) % gsz), pn = (w % nig) / gsz;
;         if (second) { pm += pm2; pn = pn < split ? a0 + pn : a1 + pn; }
;         u.pm = pm; u.pn = pn; return true;
;     }
; template <class Epi, class Sched, bool ALIGN_EPI = false, bool SP2 = false, bool ABLK = false, bool BBLK = false>
; __device__ __forceinline__ void gemm_phase(PG8_LAS unsigned char* lds, const Gemm g, const Sched& S, const Epi& E) {
;     ...
; #pragma unroll
;         for (int a = 0; a < 2; ++a)
; #pragma unroll
;             for (int b = 0; b < 2; ++b)
; #pragma unroll
;                 for (int m = 0; m < 4; ++m)
; #pragma unroll
;                     for (int n = 0; n < 2; ++n) acc[a][b][m][n] = (f32x4){0.f, 0.f, 0.f, 0.f};
.Ly_367:
	v_pk_mov_b32 v[2:3], 0, 0
	v_pk_mov_b32 v[4:5], 0, 0
	v_pk_mov_b32 v[6:7], 0, 0
	v_pk_mov_b32 v[8:9], 0, 0
	v_pk_mov_b32 v[10:11], 0, 0
	v_pk_mov_b32 v[12:13], 0, 0
	v_pk_mov_b32 v[14:15], 0, 0
	v_pk_mov_b32 v[16:17], 0, 0
	v_pk_mov_b32 v[18:19], 0, 0
	v_pk_mov_b32 v[20:21], 0, 0
	v_pk_mov_b32 v[22:23], 0, 0
	v_pk_mov_b32 v[24:25], 0, 0
	v_pk_mov_b32 v[34:35], 0, 0
	v_pk_mov_b32 v[36:37], 0, 0
	v_pk_mov_b32 v[38:39], 0, 0
	v_pk_mov_b32 v[40:41], 0, 0
	v_pk_mov_b32 v[42:43], 0, 0
	v_pk_mov_b32 v[44:45], 0, 0
	v_pk_mov_b32 v[46:47], 0, 0
	v_pk_mov_b32 v[48:49], 0, 0
	v_pk_mov_b32 v[50:51], 0, 0
	v_pk_mov_b32 v[52:53], 0, 0
	v_pk_mov_b32 v[54:55], 0, 0
	v_pk_mov_b32 v[56:57], 0, 0
	v_pk_mov_b32 v[58:59], 0, 0
	v_pk_mov_b32 v[60:61], 0, 0
	v_pk_mov_b32 v[62:63], 0, 0
	v_pk_mov_b32 v[64:65], 0, 0
	v_pk_mov_b32 v[66:67], 0, 0
	v_pk_mov_b32 v[68:69], 0, 0
	v_pk_mov_b32 v[70:71], 0, 0
	v_pk_mov_b32 v[72:73], 0, 0
	v_pk_mov_b32 v[74:75], 0, 0
	v_pk_mov_b32 v[76:77], 0, 0
	v_pk_mov_b32 v[78:79], 0, 0
	v_pk_mov_b32 v[80:81], 0, 0
	v_pk_mov_b32 v[82:83], 0, 0
	v_pk_mov_b32 v[84:85], 0, 0
	v_pk_mov_b32 v[86:87], 0, 0
	v_pk_mov_b32 v[88:89], 0, 0
	v_pk_mov_b32 v[90:91], 0, 0
	v_pk_mov_b32 v[92:93], 0, 0
	v_pk_mov_b32 v[94:95], 0, 0
	v_pk_mov_b32 v[96:97], 0, 0
	v_pk_mov_b32 v[98:99], 0, 0
	v_pk_mov_b32 v[100:101], 0, 0
	v_pk_mov_b32 v[102:103], 0, 0
	v_pk_mov_b32 v[104:105], 0, 0
	v_pk_mov_b32 v[106:107], 0, 0
	v_pk_mov_b32 v[108:109], 0, 0
	v_pk_mov_b32 v[110:111], 0, 0
	v_pk_mov_b32 v[112:113], 0, 0
	v_pk_mov_b32 v[114:115], 0, 0
	v_pk_mov_b32 v[116:117], 0, 0
	v_pk_mov_b32 v[118:119], 0, 0
	v_pk_mov_b32 v[120:121], 0, 0
	v_pk_mov_b32 v[122:123], 0, 0
	v_pk_mov_b32 v[124:125], 0, 0
	v_pk_mov_b32 v[126:127], 0, 0
	v_pk_mov_b32 v[128:129], 0, 0
	v_pk_mov_b32 v[130:131], 0, 0
	v_pk_mov_b32 v[132:133], 0, 0
	v_pk_mov_b32 v[134:135], 0, 0
	v_pk_mov_b32 v[136:137], 0, 0
	s_add_i32 s68, s26, 1
	s_mul_i32 s6, s68, s60
	s_mul_hi_u32 s7, s68, s50
	s_add_i32 s7, s7, s6
	s_mul_i32 s6, s68, s50
	s_add_u32 s6, s6, s51
	s_addc_u32 s7, s7, s61
	v_mov_b64_e32 v[2:3], 0x480
	v_cmp_lt_i64_e64 s[8:9], s[6:7], v[2:3]
	v_mov_b64_e32 v[2:3], 0x47f
	v_cmp_gt_i64_e32 vcc, s[6:7], v[2:3]
	s_cbranch_vccnz .Lyh367_362
	v_readlane_b32 s36, v254, 55
	v_readlane_b32 s37, v254, 56
	s_mov_b64 s[24:25], -1
	s_and_b64 vcc, exec, s[36:37]
	s_cbranch_vccz .Lyh367_360
	s_ashr_i32 s7, s6, 31
	s_lshr_b32 s7, s7, 29
	s_add_i32 s7, s6, s7
	s_ashr_i32 s24, s7, 3
	s_and_b32 s7, s7, -8
	s_sub_i32 s6, s6, s7
	s_cmp_lt_i32 s6, 0
	s_movk_i32 s7, 0x91
	s_cselect_b32 s7, s7, 0x90
	s_mul_i32 s6, s6, s7
	s_add_i32 s6, s6, s24
	s_cmpk_lt_i32 s6, 0x480
	s_cselect_b32 s7, 32, 4
	v_cvt_f32_ubyte0_e32 v2, s7
	v_rcp_iflag_f32_e32 v2, v2
	s_cselect_b32 s24, 0, 0xfffffb80
	s_cselect_b32 s25, 0x90, 0
	s_sub_i32 s29, 0, s7
	v_mul_f32_e32 v2, 0x4f7ffffe, v2
	v_cvt_u32_f32_e32 v2, v2
	s_add_i32 s24, s24, s6
	s_abs_i32 s27, s24
	s_ashr_i32 s6, s24, 31
	v_readfirstlane_b32 s31, v2
	s_mul_i32 s29, s29, s31
	s_mul_hi_u32 s29, s31, s29
	s_add_i32 s31, s31, s29
	s_mul_hi_u32 s29, s27, s31
	s_mul_i32 s31, s29, s7
	s_sub_i32 s27, s27, s31
	s_add_i32 s31, s29, 1
	s_sub_i32 s33, s27, s7
	s_cmp_ge_u32 s27, s7
	s_cselect_b32 s29, s31, s29
	s_cselect_b32 s27, s33, s27
	s_add_i32 s31, s29, 1
	s_cmp_ge_u32 s27, s7
	s_cselect_b32 s27, s31, s29
	s_xor_b32 s27, s27, s6
	s_sub_i32 s6, s27, s6
	s_lshl_b32 s27, s6, 2
	s_sub_i32 s25, s25, s27
	s_min_i32 s25, s25, 4
	s_abs_i32 s29, s25
	v_cvt_f32_u32_e32 v2, s29
	s_sub_i32 s31, 0, s29
	s_mul_i32 s6, s6, s7
	s_sub_i32 s6, s24, s6
	v_rcp_iflag_f32_e32 v2, v2
	s_abs_i32 s7, s6
	s_xor_b32 s24, s6, s25
	s_ashr_i32 s24, s24, 31
	v_mul_f32_e32 v2, 0x4f7ffffe, v2
	v_cvt_u32_f32_e32 v2, v2
	s_nop 0
	v_readfirstlane_b32 s33, v2
	s_mul_i32 s31, s31, s33
	s_mul_hi_u32 s31, s33, s31
	s_add_i32 s33, s33, s31
	s_mul_hi_u32 s31, s7, s33
	s_mul_i32 s33, s31, s29
	s_sub_i32 s7, s7, s33
	s_add_i32 s33, s31, 1
	s_sub_i32 s36, s7, s29
	s_cmp_ge_u32 s7, s29
	s_cselect_b32 s31, s33, s31
	s_cselect_b32 s7, s36, s7
	s_add_i32 s33, s31, 1
	s_cmp_ge_u32 s7, s29
	s_cselect_b32 s7, s33, s31
	s_xor_b32 s7, s7, s24
	s_sub_i32 s72, s7, s24
	s_mul_i32 s7, s72, s25
	s_sub_i32 s6, s6, s7
	s_add_i32 s73, s6, s27
	s_mov_b64 s[24:25], 0

; #define PG8_STAGE(bufoff, gbase, voff) do { _Pragma("unroll") for (int _i = 0; _i < 2; ++_i) \
;         __builtin_amdgcn_global_load_lds((const unsigned*)((const char*)(gbase) + (voff)[_i]), (PG8_LAS unsigned*)(lds + (bufoff) + ldsw + _i * 8192), 16, 0, 0); } while (0)
; #define PG8_LDA(dst, b, h) do { _Pragma("unroll") for (int m = 0; m < 4; ++m) _Pragma("unroll") for (int k = 0; k < 2; ++k) dst[m][k] = *(const PG8_LAS bf16x8*)(lds + PG8_SA(b, h) + aoff + m * 2048 + k * 1024); } while (0)
; #define PG8_LDB(dst, b, h) do { _Pragma("unroll") for (int n = 0; n < 2; ++n) _Pragma("unroll") for (int k = 0; k < 2; ++k) dst[n][k] = *(const PG8_LAS bf16x8*)(lds + PG8_SB(b, h) + boff + n * 2048 + k * 1024); } while (0)
; #define PG8_MMA(ai, bj, At, Bt) do { __builtin_amdgcn_s_setprio(1); _Pragma("unroll") for (int m = 0; m < 4; ++m) _Pragma("unroll") for (int n = 0; n < 2; ++n) _Pragma("unroll") for (int k = 0; k < 2; ++k) \
;         acc[ai][bj][m][n] = __builtin_amdgcn_mfma_f32_16x16x32_bf16(Bt[n][k], At[m][k], acc[ai][bj][m][n], 0, 0, 0); __builtin_amdgcn_s_setprio(0); } while (0)
; #define PG8_WAIT_V(n) asm volatile("s_waitcnt vmcnt(" #n ")" ::: "memory")
; template <class Epi, class Sched, bool ALIGN_EPI = false, bool SP2 = false, bool ABLK = false, bool BBLK = false>
; __device__ __forceinline__ void gemm_phase(PG8_LAS unsigned char* lds, const Gemm g, const Sched& S, const Epi& E) {
;     ...
;         const char* nA = has_next ? (const char*)g.A + (size_t)nxt.pm * tstepA : cA; const char* nB = has_next ? (const char*)g.Bt + (size_t)nxt.pn * tstepB : cB;
;         for (int t = 0; t < nt; t += 2) {
;             const bool last = (t == nt - 2);
;             const char* a1 = cA + (size_t)(t + 1) * kstepA;
;             const char* a2 = last ? nA : cA + (size_t)(t + 2) * kstepA; const char* b2 = last ? nB : cB + (size_t)(t + 2) * kstepB;
;             const char* a3 = a2 + kstepA; const char* b3 = b2 + kstepB;
;             if (last && has_next) S.a_ready(nxt);
;             if constexpr (SP2) {
;             PG8_LDB(B0, 0, 0); PG8_LDB(B1, 0, 1); PG8_SCHED; PG8_LDA(At, 0, 0); PG8_STAGE(PG8_SA(1, 1), a1 + hstepA, voffA);
;             PG8_WAIT_V(8); PG8_WAIT_L(0); PG8_BAR; PG8_MMA(0, 0, At, B0); PG8_MMA(0, 1, At, B1); PG8_BAR; PG8_SCHED;
;     ...
;         cur = nxt; cA = nA; cB = nB; ++ui;
;         if constexpr (ALIGN_EPI) { if (wr == 1) PG8_BAR; }
.Lyh367_366:
	s_add_u32 s0, s0, 0xc000
	s_addc_u32 s1, s1, 0
	s_add_u32 s29, s34, 0x10000
	v_mov_b32_e32 v66, 0
	s_addc_u32 s31, s35, 0
	s_mov_b32 s33, -2
	v_pk_mov_b32 v[2:3], 0, 0
	v_pk_mov_b32 v[66:67], 0, 0
	s_barrier
	s_add_u32 s8, s0, 0x4000
	s_addc_u32 s9, s1, 0
	s_cmpk_eq_i32 s33, 0x54
	s_cselect_b32 s36, s24, s8
	s_cselect_b32 s37, s25, s9
	s_cselect_b32 s34, s26, s29
	s_cselect_b32 s35, s27, s31
	s_add_u32 s8, s36, 0x8000
	s_addc_u32 s9, s37, 0
	s_add_i32 s40, 0, 0x10000
	s_add_i32 s44, 0, 0x14000
	v_add_u32_e32 v142, s40, v206
	v_add_u32_e32 v158, s44, v206
	ds_read_b128 v[26:29], v142
	ds_read_b128 v[30:33], v142 offset:1024
	ds_read_b128 v[138:141], v142 offset:2048
	ds_read_b128 v[142:145], v142 offset:3072
	ds_read_b128 v[146:149], v158
	ds_read_b128 v[150:153], v158 offset:1024
	ds_read_b128 v[154:157], v158 offset:2048
	ds_read_b128 v[158:161], v158 offset:3072
	v_lshl_add_u64 v[202:203], s[0:1], 0, v[184:185]
	s_add_i32 m0, s83, 0xc000
	ds_read_b128 v[162:165], v207
	ds_read_b128 v[166:169], v207 offset:1024
	ds_read_b128 v[170:173], v207 offset:2048
	ds_read_b128 v[174:177], v207 offset:3072
	ds_read_b128 v[198:201], v207 offset:4096
	ds_read_b128 v[208:211], v207 offset:5120
	ds_read_b128 v[212:215], v207 offset:6144
	ds_read_b128 v[216:219], v207 offset:7168
	global_load_lds_dwordx4 v[202:203], off
	v_lshl_add_u64 v[202:203], s[0:1], 0, v[196:197]
	s_add_i32 m0, s83, 0xe000
	s_nop 0
	global_load_lds_dwordx4 v[202:203], off
	s_waitcnt vmcnt(8)
	s_waitcnt lgkmcnt(0)
	s_barrier
	s_branch .Lpeel_367

;     __device__ __forceinline__ bool next(int i, Unit& u) const {
;         const long L = (long)i * G + c; if (L >= total) return false;
;         if (nM1 == 144 && nN1 == 8 && nM2 == 0 && G == 256) {
;             const int xcd = c & 7, o = c >> 3;
;             const int grp = (i < 4) ? xcd * 4 + i : 32 + (xcd >> 1), idx = (i < 4) ? o : (xcd & 1) * 16 + o;
;             u.pm = grp * 4 + (idx & 3); u.pn = idx >> 2; return true; }
;         int w = (int)L; { const int q = total / NXCD, r = total % NXCD, xcd = w % NXCD, off = w / NXCD; w = (xcd < r ? xcd * (q + 1) : r * (q + 1) + (xcd - r) * q) + off; }
;         int nM = nM1, nN = nN1; const bool second = w >= n1; if (second) { w -= n1; nM = nM2; nN = nN2; }
;         const int wgm = 4;
;         const int nig = wgm * nN, gid = w / nig, fm = gid * wgm, gsz = (nM - fm) < wgm ? (nM - fm) : wgm;
;         int pm = fm + ((w % nig) % gsz), pn = (w % nig) / gsz;
;         if (second) { pm += pm2; pn = pn < split ? a0 + pn : a1 + pn; }
;         u.pm = pm; u.pn = pn; return true;
;     }
;     __device__ __forceinline__ void operator()(const f32x4 (&acc)[2][2][4][2], const Unit& u, int wr, int wc, int fr_, int fq) const {
;     ...
;         f32x4 bv[2][2];
; #pragma unroll
;         for (int bj = 0; bj < 2; ++bj)
; #pragma unroll
;             for (int n = 0; n < 2; ++n) bv[bj][n] = *(const f32x4*)(bmg + (gate ? colt : 0) + cl + bj * HALF + 4 * n) * (gate ? 1.0f : 0.0f);
.LBB0_591:
	s_and_b64 vcc, exec, s[18:19]
	s_cbranch_vccz .Ly_594
	s_lshl_b32 s100, s8, 8
	s_add_i32 s100, s100, 0xfffff200
	s_cmp_gt_i32 s8, 13
	s_cselect_b32 s100, s100, 0
	s_ashr_i32 s101, s100, 31
	v_lshl_add_u64 v[250:251], s[100:101], 2, v[154:155]
	global_load_dwordx4 v[224:227], v[250:251], off
	global_load_dwordx4 v[246:249], v[250:251], off offset:16
	global_load_dwordx4 v[188:191], v[250:251], off offset:528
	s_nop 0
	global_load_dwordx4 v[250:253], v[250:251], off offset:512
	s_add_i32 s93, s93, 1
	s_mul_i32 s6, s93, s56
	s_mul_hi_u32 s7, s93, s42
	s_add_i32 s7, s7, s6
	s_mul_i32 s6, s93, s42
	s_add_u32 s24, s6, s46
	s_addc_u32 s25, s7, s68
	v_mov_b64_e32 v[2:3], s[2:3]
	v_cmp_ge_i64_e32 vcc, s[24:25], v[2:3]
	v_cmp_lt_i64_e64 s[6:7], s[24:25], v[2:3]
	s_cbranch_vccnz .LBB0_593
	s_ashr_i32 s9, s24, 31
	s_lshr_b32 s9, s9, 29
	s_add_i32 s9, s24, s9
	s_ashr_i32 s16, s9, 3
	s_and_b32 s9, s9, -8
	s_sub_i32 s9, s24, s9
	s_lshr_b32 s20, s9, 31
	s_or_b32 s20, s72, s20
	s_mul_i32 s9, s20, s9
	s_add_i32 s9, s9, s16
	s_cmpk_lt_i32 s9, 0x1300
	s_cselect_b32 s21, 0x98, s73
	s_cselect_b32 s16, 0, 0xffffed00
	s_cselect_b32 s20, 0x80, 16
	s_abs_i32 s22, s21
	v_cvt_f32_u32_e32 v2, s22
	s_sub_i32 s25, 0, s22
	s_add_i32 s16, s16, s9
	s_abs_i32 s24, s16
	v_rcp_iflag_f32_e32 v2, v2
	s_xor_b32 s23, s16, s21
	s_ashr_i32 s23, s23, 31
	v_mul_f32_e32 v2, 0x4f7ffffe, v2
	v_cvt_u32_f32_e32 v2, v2
	s_nop 0
	v_readfirstlane_b32 s26, v2
	s_mul_i32 s25, s25, s26
	s_mul_hi_u32 s25, s26, s25
	s_add_i32 s26, s26, s25
	s_mul_hi_u32 s25, s24, s26
	s_mul_i32 s26, s25, s22
	s_sub_i32 s24, s24, s26
	s_add_i32 s27, s25, 1
	s_sub_i32 s26, s24, s22
	s_cmp_ge_u32 s24, s22
	s_cselect_b32 s25, s27, s25
	s_cselect_b32 s24, s26, s24
	s_add_i32 s26, s25, 1
	s_cmp_ge_u32 s24, s22
	s_cselect_b32 s22, s26, s25
	s_xor_b32 s22, s22, s23
	s_sub_i32 s22, s22, s23
	s_lshl_b32 s23, s22, 2
	s_sub_i32 s20, s20, s23
	s_min_i32 s20, s20, 4
	s_abs_i32 s24, s20
	v_cvt_f32_u32_e32 v2, s24
	s_sub_i32 s25, 0, s24
	s_mul_i32 s22, s22, s21
	s_sub_i32 s16, s16, s22
	v_rcp_iflag_f32_e32 v2, v2
	s_abs_i32 s21, s16
	s_xor_b32 s22, s16, s20
	s_ashr_i32 s22, s22, 31
	v_mul_f32_e32 v2, 0x4f7ffffe, v2
	v_cvt_u32_f32_e32 v2, v2
	s_nop 0
	v_readfirstlane_b32 s26, v2
	s_mul_i32 s25, s25, s26
	s_mul_hi_u32 s25, s26, s25
	s_add_i32 s26, s26, s25
	s_mul_hi_u32 s25, s21, s26
	s_mul_i32 s26, s25, s24
	s_sub_i32 s21, s21, s26
	s_add_i32 s27, s25, 1
	s_sub_i32 s26, s21, s24
	s_cmp_ge_u32 s21, s24
	s_cselect_b32 s25, s27, s25
	s_cselect_b32 s21, s26, s21
	s_add_i32 s26, s25, 1
	s_cmp_ge_u32 s21, s24
	s_cselect_b32 s21, s26, s25
	s_xor_b32 s21, s21, s22
	s_sub_i32 s21, s21, s22
	s_mul_i32 s20, s21, s20
	s_sub_i32 s16, s16, s20
	s_add_i32 s16, s16, s23
	s_add_i32 s20, s16, 0x80
	s_cmpk_lt_i32 s9, 0x1300
	s_cselect_b32 s20, s16, s20
	s_cmp_lt_i32 s21, s33
	s_cselect_b32 s16, s47, s65
	s_cmpk_lt_i32 s9, 0x1300
	s_cselect_b32 s9, 0, s16
	s_add_i32 s22, s9, s21

; #define PG8_BAR __builtin_amdgcn_s_barrier()
;     __device__ __forceinline__ bool next(int i, Unit& u) const {
;         const long L = (long)i * G + c; if (L >= total) return false;
;         if (nM1 == 144 && nN1 == 8 && nM2 == 0 && G == 256) {
;             const int xcd = c & 7, o = c >> 3;
;             const int grp = (i < 4) ? xcd * 4 + i : 32 + (xcd >> 1), idx = (i < 4) ? o : (xcd & 1) * 16 + o;
;             u.pm = grp * 4 + (idx & 3); u.pn = idx >> 2; return true; }
;         int w = (int)L; { const int q = total / NXCD, r = total % NXCD, xcd = w % NXCD, off = w / NXCD; w = (xcd < r ? xcd * (q + 1) : r * (q + 1) + (xcd - r) * q) + off; }
;         int nM = nM1, nN = nN1; const bool second = w >= n1; if (second) { w -= n1; nM = nM2; nN = nN2; }
;         const int wgm = 4;
;         const int nig = wgm * nN, gid = w / nig, fm = gid * wgm, gsz = (nM - fm) < wgm ? (nM - fm) : wgm;
;         int pm = fm + ((w % nig) % gsz), pn = (w % nig) / gsz;
;         if (second) { pm += pm2; pn = pn < split ? a0 + pn : a1 + pn; }
;         u.pm = pm; u.pn = pn; return true;
;     }
; template <class Epi, class Sched, bool ALIGN_EPI = false, bool SP2 = false, bool ABLK = false, bool BBLK = false>
; __device__ __forceinline__ void gemm_phase(PG8_LAS unsigned char* lds, const Gemm g, const Sched& S, const Epi& E) {
;     ...
;             PG8_LDB(B0, 0, 0); PG8_LDB(B1, 0, 1); PG8_SCHED; PG8_LDA(At, 0, 0); PG8_STAGE(PG8_SA(1, 1), a1 + hstepA, voffA);
;             PG8_WAIT_V(8); PG8_WAIT_L(0); PG8_BAR; PG8_MMA(0, 0, At, B0); PG8_MMA(0, 1, At, B1); PG8_BAR; PG8_SCHED;
;             PG8_LDA(At, 0, 1); PG8_STAGE(PG8_SB(0, 0), b2, voffB); PG8_STAGE(PG8_SB(0, 1), b2 + hstepB, voffB); PG8_STAGE(PG8_SA(0, 0), a2, voffA);
;             PG8_WAIT_V(8); PG8_WAIT_L(0); PG8_BAR; PG8_MMA(1, 0, At, B0); PG8_MMA(1, 1, At, B1); PG8_BAR; PG8_SCHED;
;             PG8_LDB(B0, 1, 0); PG8_LDB(B1, 1, 1); PG8_SCHED; PG8_LDA(At, 1, 0); PG8_STAGE(PG8_SA(0, 1), a2 + hstepA, voffA);
;             PG8_WAIT_V(8); PG8_WAIT_L(0); PG8_BAR; PG8_MMA(0, 0, At, B0); PG8_MMA(0, 1, At, B1); PG8_BAR; PG8_SCHED;
;             PG8_LDA(At, 1, 1); PG8_STAGE(PG8_SB(1, 0), b3, voffB); PG8_STAGE(PG8_SB(1, 1), b3 + hstepB, voffB); PG8_STAGE(PG8_SA(1, 0), a3, voffA);
;             PG8_WAIT_V(8); PG8_WAIT_L(0); PG8_BAR; PG8_MMA(1, 0, At, B0); PG8_MMA(1, 1, At, B1); PG8_BAR; PG8_SCHED;
;             } else {
.Ly_594:
	v_pk_mov_b32 v[10:11], 0, 0
	v_pk_mov_b32 v[12:13], 0, 0
	v_pk_mov_b32 v[14:15], 0, 0
	v_pk_mov_b32 v[16:17], 0, 0
	v_pk_mov_b32 v[18:19], 0, 0
	v_pk_mov_b32 v[20:21], 0, 0
	v_pk_mov_b32 v[22:23], 0, 0
	v_pk_mov_b32 v[24:25], 0, 0
	v_pk_mov_b32 v[26:27], 0, 0
	v_pk_mov_b32 v[28:29], 0, 0
	v_pk_mov_b32 v[30:31], 0, 0
	v_pk_mov_b32 v[32:33], 0, 0
	v_pk_mov_b32 v[34:35], 0, 0
	v_pk_mov_b32 v[36:37], 0, 0
	v_pk_mov_b32 v[38:39], 0, 0
	v_pk_mov_b32 v[40:41], 0, 0
	v_pk_mov_b32 v[42:43], 0, 0
	v_pk_mov_b32 v[44:45], 0, 0
	v_pk_mov_b32 v[46:47], 0, 0
	v_pk_mov_b32 v[48:49], 0, 0
	v_pk_mov_b32 v[50:51], 0, 0
	v_pk_mov_b32 v[52:53], 0, 0
	v_pk_mov_b32 v[54:55], 0, 0
	v_pk_mov_b32 v[56:57], 0, 0
	v_pk_mov_b32 v[58:59], 0, 0
	v_pk_mov_b32 v[60:61], 0, 0
	v_pk_mov_b32 v[62:63], 0, 0
	v_pk_mov_b32 v[64:65], 0, 0
	v_pk_mov_b32 v[66:67], 0, 0
	v_pk_mov_b32 v[68:69], 0, 0
	v_pk_mov_b32 v[70:71], 0, 0
	v_pk_mov_b32 v[72:73], 0, 0
	v_pk_mov_b32 v[74:75], 0, 0
	v_pk_mov_b32 v[76:77], 0, 0
	v_pk_mov_b32 v[78:79], 0, 0
	v_pk_mov_b32 v[80:81], 0, 0
	v_pk_mov_b32 v[82:83], 0, 0
	v_pk_mov_b32 v[84:85], 0, 0
	v_pk_mov_b32 v[86:87], 0, 0
	v_pk_mov_b32 v[88:89], 0, 0
	v_pk_mov_b32 v[90:91], 0, 0
	v_pk_mov_b32 v[92:93], 0, 0
	v_pk_mov_b32 v[94:95], 0, 0
	v_pk_mov_b32 v[96:97], 0, 0
	v_pk_mov_b32 v[98:99], 0, 0
	v_pk_mov_b32 v[100:101], 0, 0
	v_pk_mov_b32 v[102:103], 0, 0
	v_pk_mov_b32 v[104:105], 0, 0
	v_pk_mov_b32 v[106:107], 0, 0
	v_pk_mov_b32 v[108:109], 0, 0
	v_pk_mov_b32 v[110:111], 0, 0
	v_pk_mov_b32 v[112:113], 0, 0
	v_pk_mov_b32 v[114:115], 0, 0
	v_pk_mov_b32 v[116:117], 0, 0
	v_pk_mov_b32 v[118:119], 0, 0
	v_pk_mov_b32 v[120:121], 0, 0
	v_pk_mov_b32 v[122:123], 0, 0
	v_pk_mov_b32 v[124:125], 0, 0
	v_pk_mov_b32 v[126:127], 0, 0
	v_pk_mov_b32 v[128:129], 0, 0
	s_lshl_b32 s100, s8, 8
	s_add_i32 s100, s100, 0xfffff200
	s_cmp_gt_i32 s8, 13
	s_cselect_b32 s100, s100, 0
	s_ashr_i32 s101, s100, 31
	v_lshl_add_u64 v[250:251], s[100:101], 2, v[154:155]
	global_load_dwordx4 v[224:227], v[250:251], off
	global_load_dwordx4 v[246:249], v[250:251], off offset:16
	global_load_dwordx4 v[188:191], v[250:251], off offset:528
	s_nop 0
	global_load_dwordx4 v[250:253], v[250:251], off offset:512
	s_add_i32 s93, s93, 1
	s_mul_i32 s6, s93, s56
	s_mul_hi_u32 s7, s93, s42
	s_add_i32 s7, s7, s6
	s_mul_i32 s6, s93, s42
	s_add_u32 s24, s6, s46
	s_addc_u32 s25, s7, s68
	v_mov_b64_e32 v[2:3], s[2:3]
	v_cmp_ge_i64_e32 vcc, s[24:25], v[2:3]
	v_cmp_lt_i64_e64 s[6:7], s[24:25], v[2:3]
	s_cbranch_vccnz .Lyh594_593
	s_ashr_i32 s9, s24, 31
	s_lshr_b32 s9, s9, 29
	s_add_i32 s9, s24, s9
	s_ashr_i32 s16, s9, 3
	s_and_b32 s9, s9, -8
	s_sub_i32 s9, s24, s9
	s_lshr_b32 s20, s9, 31
	s_or_b32 s20, s72, s20
	s_mul_i32 s9, s20, s9
	s_add_i32 s9, s9, s16
	s_cmpk_lt_i32 s9, 0x1300
	s_cselect_b32 s21, 0x98, s73
	s_cselect_b32 s16, 0, 0xffffed00
	s_cselect_b32 s20, 0x80, 16
	s_abs_i32 s22, s21
	v_cvt_f32_u32_e32 v2, s22
	s_sub_i32 s25, 0, s22
	s_add_i32 s16, s16, s9
	s_abs_i32 s24, s16
	v_rcp_iflag_f32_e32 v2, v2
	s_xor_b32 s23, s16, s21
	s_ashr_i32 s23, s23, 31
	v_mul_f32_e32 v2, 0x4f7ffffe, v2
	v_cvt_u32_f32_e32 v2, v2
	s_nop 0
	v_readfirstlane_b32 s26, v2
	s_mul_i32 s25, s25, s26
	s_mul_hi_u32 s25, s26, s25
	s_add_i32 s26, s26, s25
	s_mul_hi_u32 s25, s24, s26
	s_mul_i32 s26, s25, s22
	s_sub_i32 s24, s24, s26
	s_add_i32 s27, s25, 1
	s_sub_i32 s26, s24, s22
	s_cmp_ge_u32 s24, s22
	s_cselect_b32 s25, s27, s25
	s_cselect_b32 s24, s26, s24
	s_add_i32 s26, s25, 1
	s_cmp_ge_u32 s24, s22
	s_cselect_b32 s22, s26, s25
	s_xor_b32 s22, s22, s23
	s_sub_i32 s22, s22, s23
	s_lshl_b32 s23, s22, 2
	s_sub_i32 s20, s20, s23
	s_min_i32 s20, s20, 4
	s_abs_i32 s24, s20
	v_cvt_f32_u32_e32 v2, s24
	s_sub_i32 s25, 0, s24
	s_mul_i32 s22, s22, s21
	s_sub_i32 s16, s16, s22
	v_rcp_iflag_f32_e32 v2, v2
	s_abs_i32 s21, s16
	s_xor_b32 s22, s16, s20
	s_ashr_i32 s22, s22, 31
	v_mul_f32_e32 v2, 0x4f7ffffe, v2
	v_cvt_u32_f32_e32 v2, v2
	s_nop 0
	v_readfirstlane_b32 s26, v2
	s_mul_i32 s25, s25, s26
	s_mul_hi_u32 s25, s26, s25
	s_add_i32 s26, s26, s25
	s_mul_hi_u32 s25, s21, s26
	s_mul_i32 s26, s25, s24
	s_sub_i32 s21, s21, s26
	s_add_i32 s27, s25, 1
	s_sub_i32 s26, s21, s24
	s_cmp_ge_u32 s21, s24
	s_cselect_b32 s25, s27, s25
	s_cselect_b32 s21, s26, s21
	s_add_i32 s26, s25, 1
	s_cmp_ge_u32 s21, s24
	s_cselect_b32 s21, s26, s25
	s_xor_b32 s21, s21, s22
	s_sub_i32 s21, s21, s22
	s_mul_i32 s20, s21, s20
	s_sub_i32 s16, s16, s20
	s_add_i32 s16, s16, s23
	s_add_i32 s20, s16, 0x80
	s_cmpk_lt_i32 s9, 0x1300
	s_cselect_b32 s20, s16, s20
	s_cmp_lt_i32 s21, s33
	s_cselect_b32 s16, s47, s65
	s_cmpk_lt_i32 s9, 0x1300
	s_cselect_b32 s9, 0, s16
	s_add_i32 s22, s9, s21
.Lyh594_593:
	s_ashr_i32 s21, s20, 31
	s_lshl_b64 s[24:25], s[20:21], 20
	s_add_u32 s24, s51, s24
	s_addc_u32 s25, s53, s25
	s_and_b64 s[26:27], s[6:7], exec
	s_cselect_b32 s9, s25, s1
	s_cselect_b32 s16, s24, s0
	s_ashr_i32 s23, s22, 31
	s_lshl_b64 s[26:27], s[22:23], 20
	s_add_u32 s26, s44, s26
	s_addc_u32 s27, s45, s27
	s_and_b64 s[34:35], s[6:7], exec
	s_cselect_b32 s21, s27, s31
	s_cselect_b32 s23, s26, s30
	s_add_u32 s0, s0, 0xc000
	s_addc_u32 s1, s1, 0
	s_add_u32 s29, s30, 0x10000
	v_mov_b32_e32 v2, 0
	s_addc_u32 s40, s31, 0
	s_mov_b32 s41, -2
	v_mov_b32_e32 v3, v2
	v_mov_b32_e32 v4, v2
	v_mov_b32_e32 v5, v2
	v_mov_b32_e32 v6, v2
	v_mov_b32_e32 v7, v2
	v_mov_b32_e32 v8, v2
	v_mov_b32_e32 v9, v2
	s_waitcnt vmcnt(0)
	v_pk_mov_b32 v[2:3], 0, 0
	v_pk_mov_b32 v[4:5], 0, 0
	v_pk_mov_b32 v[6:7], 0, 0
	v_pk_mov_b32 v[8:9], 0, 0
	s_barrier
	s_add_u32 s30, s0, 0x4000
	s_addc_u32 s31, s1, 0
	s_cmp_eq_u32 s41, 28
	s_cselect_b32 s36, s16, s30
	s_cselect_b32 s37, s9, s31
	s_cselect_b32 s34, s23, s29
	s_cselect_b32 s35, s21, s40
	s_add_u32 s30, s36, 0x8000
	s_addc_u32 s31, s37, 0
	s_add_i32 s60, 0, 0x10000
	s_add_i32 s75, 0, 0x14000
	v_add_u32_e32 v142, s60, v169
	v_add_u32_e32 v171, s75, v169
	ds_read_b128 v[130:133], v142
	ds_read_b128 v[134:137], v142 offset:1024
	ds_read_b128 v[138:141], v142 offset:2048
	ds_read_b128 v[142:145], v142 offset:3072
	ds_read_b128 v[160:163], v171
	ds_read_b128 v[164:167], v171 offset:1024
	ds_read_b128 v[172:175], v171 offset:2048
	ds_read_b128 v[176:179], v171 offset:3072
	v_lshl_add_u64 v[184:185], s[0:1], 0, v[156:157]
	s_add_i32 m0, s83, 0xc000
	ds_read_b128 v[180:183], v170
	ds_read_b128 v[196:199], v170 offset:1024
	ds_read_b128 v[200:203], v170 offset:2048
	ds_read_b128 v[204:207], v170 offset:3072
	ds_read_b128 v[208:211], v170 offset:4096
	ds_read_b128 v[212:215], v170 offset:5120
	ds_read_b128 v[216:219], v170 offset:6144
	ds_read_b128 v[220:223], v170 offset:7168
	global_load_lds_dwordx4 v[184:185], off
	v_lshl_add_u64 v[184:185], s[0:1], 0, v[158:159]
	s_add_i32 m0, s83, 0xe000
	s_nop 0
	global_load_lds_dwordx4 v[184:185], off
	s_waitcnt vmcnt(8)
	s_waitcnt lgkmcnt(0)
	s_barrier
	s_branch .Lpeel_594

;     __device__ __forceinline__ bool next(int i, Unit& u) const {
;         const long L = (long)i * G + c; if (L >= total) return false;
;         if (nM1 == 144 && nN1 == 8 && nM2 == 0 && G == 256) {
;             const int xcd = c & 7, o = c >> 3;
;             const int grp = (i < 4) ? xcd * 4 + i : 32 + (xcd >> 1), idx = (i < 4) ? o : (xcd & 1) * 16 + o;
;             u.pm = grp * 4 + (idx & 3); u.pn = idx >> 2; return true; }
;         int w = (int)L; { const int q = total / NXCD, r = total % NXCD, xcd = w % NXCD, off = w / NXCD; w = (xcd < r ? xcd * (q + 1) : r * (q + 1) + (xcd - r) * q) + off; }
;         int nM = nM1, nN = nN1; const bool second = w >= n1; if (second) { w -= n1; nM = nM2; nN = nN2; }
;         const int wgm = 4;
;         const int nig = wgm * nN, gid = w / nig, fm = gid * wgm, gsz = (nM - fm) < wgm ? (nM - fm) : wgm;
;         int pm = fm + ((w % nig) % gsz), pn = (w % nig) / gsz;
;         if (second) { pm += pm2; pn = pn < split ? a0 + pn : a1 + pn; }
;         u.pm = pm; u.pn = pn; return true;
;     }
.LBB0_655:
	s_and_b64 vcc, exec, s[8:9]
	s_cbranch_vccz .Ly_658
	s_add_i32 s60, s60, 1
	s_mul_i32 s1, s60, s56
	s_mul_hi_u32 s6, s60, s42
	s_add_i32 s6, s6, s1
	s_mul_i32 s1, s60, s42
	s_add_u32 s14, s1, s30
	s_addc_u32 s15, s6, s34
	v_mov_b64_e32 v[2:3], s[16:17]
	v_cmp_ge_i64_e32 vcc, s[14:15], v[2:3]
	v_cmp_lt_i64_e64 s[6:7], s[14:15], v[2:3]
	s_cbranch_vccnz .LBB0_657
	s_ashr_i32 s0, s14, 31
	s_lshr_b32 s0, s0, 29
	s_add_i32 s0, s14, s0
	s_ashr_i32 s1, s0, 3
	s_and_b32 s0, s0, -8
	s_sub_i32 s0, s14, s0
	s_lshr_b32 s12, s0, 31
	s_or_b32 s12, s35, s12
	s_mul_i32 s0, s12, s0
	s_add_i32 s0, s0, s1
	s_cmp_lt_i32 s0, s16
	s_cselect_b32 s13, s36, 4
	s_cselect_b32 s1, 0, s16
	s_cselect_b32 s12, 2, 0
	s_abs_i32 s14, s13
	v_cvt_f32_u32_e32 v2, s14
	s_sub_i32 s18, 0, s14
	s_sub_i32 s0, s0, s1
	s_abs_i32 s15, s0
	v_rcp_iflag_f32_e32 v2, v2
	s_xor_b32 s1, s0, s13
	s_ashr_i32 s1, s1, 31
	v_mul_f32_e32 v2, 0x4f7ffffe, v2
	v_cvt_u32_f32_e32 v2, v2
	s_nop 0
	v_readfirstlane_b32 s19, v2
	s_mul_i32 s18, s18, s19
	s_mul_hi_u32 s18, s19, s18
	s_add_i32 s19, s19, s18
	s_mul_hi_u32 s18, s15, s19
	s_mul_i32 s19, s18, s14
	s_sub_i32 s15, s15, s19
	s_add_i32 s26, s18, 1
	s_sub_i32 s19, s15, s14
	s_cmp_ge_u32 s15, s14
	s_cselect_b32 s18, s26, s18
	s_cselect_b32 s15, s19, s15
	s_add_i32 s19, s18, 1
	s_cmp_ge_u32 s15, s14
	s_cselect_b32 s14, s19, s18
	s_xor_b32 s14, s14, s1
	s_sub_i32 s1, s14, s1
	s_lshl_b32 s14, s1, 2
	s_sub_i32 s12, s12, s14
	s_min_i32 s12, s12, 4
	s_abs_i32 s15, s12
	v_cvt_f32_u32_e32 v2, s15
	s_sub_i32 s18, 0, s15
	s_mul_i32 s1, s1, s13
	s_sub_i32 s1, s0, s1
	v_rcp_iflag_f32_e32 v2, v2
	s_abs_i32 s0, s1
	s_xor_b32 s13, s1, s12
	s_ashr_i32 s13, s13, 31
	v_mul_f32_e32 v2, 0x4f7ffffe, v2
	v_cvt_u32_f32_e32 v2, v2
	s_nop 0
	v_readfirstlane_b32 s19, v2
	s_mul_i32 s18, s18, s19
	s_mul_hi_u32 s18, s19, s18
	s_add_i32 s19, s19, s18
	s_mul_hi_u32 s18, s0, s19
	s_mul_i32 s19, s18, s15
	s_sub_i32 s0, s0, s19
	s_add_i32 s26, s18, 1
	s_sub_i32 s19, s0, s15
	s_cmp_ge_u32 s0, s15
	s_cselect_b32 s18, s26, s18
	s_cselect_b32 s0, s19, s0
	s_add_i32 s19, s18, 1
	s_cmp_ge_u32 s0, s15
	s_cselect_b32 s0, s19, s18
	s_xor_b32 s0, s0, s13
	s_sub_i32 s0, s0, s13
	s_mul_i32 s12, s0, s12
	s_sub_i32 s1, s1, s12
	s_add_i32 s12, s1, s14

; #define PG8_BAR __builtin_amdgcn_s_barrier()
;     __device__ __forceinline__ bool next(int i, Unit& u) const {
;         const long L = (long)i * G + c; if (L >= total) return false;
;         if (nM1 == 144 && nN1 == 8 && nM2 == 0 && G == 256) {
;             const int xcd = c & 7, o = c >> 3;
;             const int grp = (i < 4) ? xcd * 4 + i : 32 + (xcd >> 1), idx = (i < 4) ? o : (xcd & 1) * 16 + o;
;             u.pm = grp * 4 + (idx & 3); u.pn = idx >> 2; return true; }
;         int w = (int)L; { const int q = total / NXCD, r = total % NXCD, xcd = w % NXCD, off = w / NXCD; w = (xcd < r ? xcd * (q + 1) : r * (q + 1) + (xcd - r) * q) + off; }
;         int nM = nM1, nN = nN1; const bool second = w >= n1; if (second) { w -= n1; nM = nM2; nN = nN2; }
;         const int wgm = 4;
;         const int nig = wgm * nN, gid = w / nig, fm = gid * wgm, gsz = (nM - fm) < wgm ? (nM - fm) : wgm;
;         int pm = fm + ((w % nig) % gsz), pn = (w % nig) / gsz;
;         if (second) { pm += pm2; pn = pn < split ? a0 + pn : a1 + pn; }
;         u.pm = pm; u.pn = pn; return true;
;     }
; template <class Epi, class Sched, bool ALIGN_EPI = false, bool SP2 = false, bool ABLK = false, bool BBLK = false>
; __device__ __forceinline__ void gemm_phase(PG8_LAS unsigned char* lds, const Gemm g, const Sched& S, const Epi& E) {
;     ...
;             PG8_LDB(B0, 0, 0); PG8_LDB(B1, 0, 1); PG8_SCHED; PG8_LDA(At, 0, 0); PG8_STAGE(PG8_SA(1, 1), a1 + hstepA, voffA);
;             PG8_WAIT_V(8); PG8_WAIT_L(0); PG8_BAR; PG8_MMA(0, 0, At, B0); PG8_MMA(0, 1, At, B1); PG8_BAR; PG8_SCHED;
;             PG8_LDA(At, 0, 1); PG8_STAGE(PG8_SB(0, 0), b2, voffB); PG8_STAGE(PG8_SB(0, 1), b2 + hstepB, voffB); PG8_STAGE(PG8_SA(0, 0), a2, voffA);
;             PG8_WAIT_V(8); PG8_WAIT_L(0); PG8_BAR; PG8_MMA(1, 0, At, B0); PG8_MMA(1, 1, At, B1); PG8_BAR; PG8_SCHED;
;             PG8_LDB(B0, 1, 0); PG8_LDB(B1, 1, 1); PG8_SCHED; PG8_LDA(At, 1, 0); PG8_STAGE(PG8_SA(0, 1), a2 + hstepA, voffA);
;             PG8_WAIT_V(8); PG8_WAIT_L(0); PG8_BAR; PG8_MMA(0, 0, At, B0); PG8_MMA(0, 1, At, B1); PG8_BAR; PG8_SCHED;
;             PG8_LDA(At, 1, 1); PG8_STAGE(PG8_SB(1, 0), b3, voffB); PG8_STAGE(PG8_SB(1, 1), b3 + hstepB, voffB); PG8_STAGE(PG8_SA(1, 0), a3, voffA);
;             PG8_WAIT_V(8); PG8_WAIT_L(0); PG8_BAR; PG8_MMA(1, 0, At, B0); PG8_MMA(1, 1, At, B1); PG8_BAR; PG8_SCHED;
;             } else {
.Ly_658:
	v_pk_mov_b32 v[2:3], 0, 0
	v_pk_mov_b32 v[4:5], 0, 0
	v_pk_mov_b32 v[6:7], 0, 0
	v_pk_mov_b32 v[8:9], 0, 0
	v_pk_mov_b32 v[10:11], 0, 0
	v_pk_mov_b32 v[12:13], 0, 0
	v_pk_mov_b32 v[14:15], 0, 0
	v_pk_mov_b32 v[16:17], 0, 0
	v_pk_mov_b32 v[18:19], 0, 0
	v_pk_mov_b32 v[20:21], 0, 0
	v_pk_mov_b32 v[22:23], 0, 0
	v_pk_mov_b32 v[24:25], 0, 0
	v_pk_mov_b32 v[26:27], 0, 0
	v_pk_mov_b32 v[28:29], 0, 0
	v_pk_mov_b32 v[30:31], 0, 0
	v_pk_mov_b32 v[32:33], 0, 0
	v_pk_mov_b32 v[34:35], 0, 0
	v_pk_mov_b32 v[36:37], 0, 0
	v_pk_mov_b32 v[38:39], 0, 0
	v_pk_mov_b32 v[40:41], 0, 0
	v_pk_mov_b32 v[42:43], 0, 0
	v_pk_mov_b32 v[44:45], 0, 0
	v_pk_mov_b32 v[46:47], 0, 0
	v_pk_mov_b32 v[48:49], 0, 0
	v_pk_mov_b32 v[50:51], 0, 0
	v_pk_mov_b32 v[52:53], 0, 0
	v_pk_mov_b32 v[54:55], 0, 0
	v_pk_mov_b32 v[56:57], 0, 0
	v_pk_mov_b32 v[58:59], 0, 0
	v_pk_mov_b32 v[60:61], 0, 0
	v_pk_mov_b32 v[62:63], 0, 0
	v_pk_mov_b32 v[64:65], 0, 0
	v_pk_mov_b32 v[66:67], 0, 0
	v_pk_mov_b32 v[68:69], 0, 0
	v_pk_mov_b32 v[70:71], 0, 0
	v_pk_mov_b32 v[72:73], 0, 0
	v_pk_mov_b32 v[74:75], 0, 0
	v_pk_mov_b32 v[76:77], 0, 0
	v_pk_mov_b32 v[78:79], 0, 0
	v_pk_mov_b32 v[80:81], 0, 0
	v_pk_mov_b32 v[82:83], 0, 0
	v_pk_mov_b32 v[84:85], 0, 0
	v_pk_mov_b32 v[86:87], 0, 0
	v_pk_mov_b32 v[88:89], 0, 0
	v_pk_mov_b32 v[90:91], 0, 0
	v_pk_mov_b32 v[92:93], 0, 0
	v_pk_mov_b32 v[94:95], 0, 0
	v_pk_mov_b32 v[96:97], 0, 0
	v_pk_mov_b32 v[98:99], 0, 0
	v_pk_mov_b32 v[100:101], 0, 0
	v_pk_mov_b32 v[102:103], 0, 0
	v_pk_mov_b32 v[104:105], 0, 0
	v_pk_mov_b32 v[106:107], 0, 0
	v_pk_mov_b32 v[108:109], 0, 0
	v_pk_mov_b32 v[110:111], 0, 0
	v_pk_mov_b32 v[112:113], 0, 0
	v_pk_mov_b32 v[114:115], 0, 0
	v_pk_mov_b32 v[116:117], 0, 0
	v_pk_mov_b32 v[118:119], 0, 0
	v_pk_mov_b32 v[120:121], 0, 0
	v_pk_mov_b32 v[122:123], 0, 0
	v_pk_mov_b32 v[124:125], 0, 0
	v_pk_mov_b32 v[126:127], 0, 0
	v_pk_mov_b32 v[128:129], 0, 0
	s_add_i32 s60, s60, 1
	s_mul_i32 s1, s60, s56
	s_mul_hi_u32 s6, s60, s42
	s_add_i32 s6, s6, s1
	s_mul_i32 s1, s60, s42
	s_add_u32 s14, s1, s30
	s_addc_u32 s15, s6, s34
	v_mov_b64_e32 v[2:3], s[16:17]
	v_cmp_ge_i64_e32 vcc, s[14:15], v[2:3]
	v_cmp_lt_i64_e64 s[6:7], s[14:15], v[2:3]
	s_cbranch_vccnz .Lyh658_657
	s_ashr_i32 s0, s14, 31
	s_lshr_b32 s0, s0, 29
	s_add_i32 s0, s14, s0
	s_ashr_i32 s1, s0, 3
	s_and_b32 s0, s0, -8
	s_sub_i32 s0, s14, s0
	s_lshr_b32 s12, s0, 31
	s_or_b32 s12, s35, s12
	s_mul_i32 s0, s12, s0
	s_add_i32 s0, s0, s1
	s_cmp_lt_i32 s0, s16
	s_cselect_b32 s13, s36, 4
	s_cselect_b32 s1, 0, s16
	s_cselect_b32 s12, 2, 0
	s_abs_i32 s14, s13
	v_cvt_f32_u32_e32 v2, s14
	s_sub_i32 s18, 0, s14
	s_sub_i32 s0, s0, s1
	s_abs_i32 s15, s0
	v_rcp_iflag_f32_e32 v2, v2
	s_xor_b32 s1, s0, s13
	s_ashr_i32 s1, s1, 31
	v_mul_f32_e32 v2, 0x4f7ffffe, v2
	v_cvt_u32_f32_e32 v2, v2
	s_nop 0
	v_readfirstlane_b32 s19, v2
	s_mul_i32 s18, s18, s19
	s_mul_hi_u32 s18, s19, s18
	s_add_i32 s19, s19, s18
	s_mul_hi_u32 s18, s15, s19
	s_mul_i32 s19, s18, s14
	s_sub_i32 s15, s15, s19
	s_add_i32 s26, s18, 1
	s_sub_i32 s19, s15, s14
	s_cmp_ge_u32 s15, s14
	s_cselect_b32 s18, s26, s18
	s_cselect_b32 s15, s19, s15
	s_add_i32 s19, s18, 1
	s_cmp_ge_u32 s15, s14
	s_cselect_b32 s14, s19, s18
	s_xor_b32 s14, s14, s1
	s_sub_i32 s1, s14, s1
	s_lshl_b32 s14, s1, 2
	s_sub_i32 s12, s12, s14
	s_min_i32 s12, s12, 4
	s_abs_i32 s15, s12
	v_cvt_f32_u32_e32 v2, s15
	s_sub_i32 s18, 0, s15
	s_mul_i32 s1, s1, s13
	s_sub_i32 s1, s0, s1
	v_rcp_iflag_f32_e32 v2, v2
	s_abs_i32 s0, s1
	s_xor_b32 s13, s1, s12
	s_ashr_i32 s13, s13, 31
	v_mul_f32_e32 v2, 0x4f7ffffe, v2
	v_cvt_u32_f32_e32 v2, v2
	s_nop 0
	v_readfirstlane_b32 s19, v2
	s_mul_i32 s18, s18, s19
	s_mul_hi_u32 s18, s19, s18
	s_add_i32 s19, s19, s18
	s_mul_hi_u32 s18, s0, s19
	s_mul_i32 s19, s18, s15
	s_sub_i32 s0, s0, s19
	s_add_i32 s26, s18, 1
	s_sub_i32 s19, s0, s15
	s_cmp_ge_u32 s0, s15
	s_cselect_b32 s18, s26, s18
	s_cselect_b32 s0, s19, s0
	s_add_i32 s19, s18, 1
	s_cmp_ge_u32 s0, s15
	s_cselect_b32 s0, s19, s18
	s_xor_b32 s0, s0, s13
	s_sub_i32 s0, s0, s13
	s_mul_i32 s12, s0, s12
	s_sub_i32 s1, s1, s12
	s_add_i32 s12, s1, s14
.Lyh658_657:
	s_ashr_i32 s13, s12, 31
	s_lshl_b64 s[14:15], s[12:13], 20
	s_add_u32 s14, s31, s14
	s_addc_u32 s15, s33, s15
	s_and_b64 s[18:19], s[6:7], exec
	s_cselect_b32 s13, s15, s23
	s_cselect_b32 s61, s14, s22
	s_ashr_i32 s1, s0, 31
	s_lshl_b64 s[18:19], s[0:1], 20
	s_add_u32 s18, s51, s18
	s_addc_u32 s19, s53, s19
	s_and_b64 s[26:27], s[6:7], exec
	s_cselect_b32 s1, s19, s25
	s_cselect_b32 s65, s18, s24
	s_add_u32 s22, s22, 0xc000
	s_addc_u32 s23, s23, 0
	s_add_u32 s68, s24, 0x10000
	v_mov_b32_e32 v2, 0
	s_addc_u32 s72, s25, 0
	s_mov_b32 s73, -2
	v_pk_mov_b32 v[2:3], 0, 0
	s_barrier
	s_add_u32 s24, s22, 0x4000
	s_addc_u32 s25, s23, 0
	s_cmp_eq_u32 s73, 28
	s_cselect_b32 s28, s61, s24
	s_cselect_b32 s29, s13, s25
	s_cselect_b32 s26, s65, s68
	s_cselect_b32 s27, s1, s72
	s_add_u32 s24, s28, 0x8000
	s_addc_u32 s25, s29, 0
	s_add_i32 s75, 0, 0x10000
	s_add_i32 s82, 0, 0x14000
	v_add_u32_e32 v158, s75, v147
	v_add_u32_e32 v174, s82, v147
	ds_read_b128 v[142:145], v158
	ds_read_b128 v[150:153], v158 offset:1024
	ds_read_b128 v[154:157], v158 offset:2048
	ds_read_b128 v[158:161], v158 offset:3072
	ds_read_b128 v[162:165], v174
	ds_read_b128 v[166:169], v174 offset:1024
	ds_read_b128 v[170:173], v174 offset:2048
	ds_read_b128 v[174:177], v174 offset:3072
	v_lshl_add_u64 v[220:221], s[22:23], 0, v[138:139]
	s_add_i32 m0, s40, 0xc000
	ds_read_b128 v[178:181], v149
	ds_read_b128 v[182:185], v149 offset:1024
	ds_read_b128 v[196:199], v149 offset:2048
	ds_read_b128 v[200:203], v149 offset:3072
	ds_read_b128 v[204:207], v149 offset:4096
	ds_read_b128 v[208:211], v149 offset:5120
	ds_read_b128 v[212:215], v149 offset:6144
	ds_read_b128 v[216:219], v149 offset:7168
	global_load_lds_dwordx4 v[220:221], off
	v_lshl_add_u64 v[220:221], s[22:23], 0, v[140:141]
	s_add_i32 m0, s40, 0xe000
	s_nop 0
	global_load_lds_dwordx4 v[220:221], off
	s_waitcnt vmcnt(8)
	s_waitcnt lgkmcnt(0)
	s_barrier
	s_branch .Lpeel_658

;     __device__ __forceinline__ bool next(int i, Unit& u) const {
;         const long L = (long)i * G + c; if (L >= total) return false;
;         if (nM1 == 144 && nN1 == 8 && nM2 == 0 && G == 256) {
;             const int xcd = c & 7, o = c >> 3;
;             const int grp = (i < 4) ? xcd * 4 + i : 32 + (xcd >> 1), idx = (i < 4) ? o : (xcd & 1) * 16 + o;
;             u.pm = grp * 4 + (idx & 3); u.pn = idx >> 2; return true; }
;         int w = (int)L; { const int q = total / NXCD, r = total % NXCD, xcd = w % NXCD, off = w / NXCD; w = (xcd < r ? xcd * (q + 1) : r * (q + 1) + (xcd - r) * q) + off; }
;         int nM = nM1, nN = nN1; const bool second = w >= n1; if (second) { w -= n1; nM = nM2; nN = nN2; }
;         const int wgm = 4;
;         const int nig = wgm * nN, gid = w / nig, fm = gid * wgm, gsz = (nM - fm) < wgm ? (nM - fm) : wgm;
;         int pm = fm + ((w % nig) % gsz), pn = (w % nig) / gsz;
.LBB0_759:
	s_and_b64 vcc, exec, s[8:9]
	s_cbranch_vccz .Ly_766
	s_add_i32 s61, s61, 1
	s_mul_i32 s1, s61, s43
	s_mul_hi_u32 s6, s61, s41
	s_add_i32 s6, s6, s1
	s_mul_i32 s1, s61, s41
	s_add_u32 s18, s1, s42
	s_addc_u32 s19, s6, s44
	v_mov_b64_e32 v[2:3], 0x80
	v_cmp_gt_i64_e32 vcc, s[18:19], v[194:195]
	v_cmp_lt_i64_e64 s[6:7], s[18:19], v[2:3]
	s_cbranch_vccnz .LBB0_765
	s_ashr_i32 s1, s18, 31
	s_lshr_b32 s1, s1, 29
	s_add_i32 s1, s18, s1
	s_and_b32 s11, s1, -8
	s_sub_i32 s11, s18, s11
	s_cmp_gt_i32 s11, -1
	s_mov_b64 s[12:13], -1
	s_cbranch_scc0 .LBB0_762
	s_lshl_b32 s14, s11, 4
	s_mov_b64 s[12:13], 0

; #define PG8_BAR __builtin_amdgcn_s_barrier()
;     __device__ __forceinline__ bool next(int i, Unit& u) const {
;         const long L = (long)i * G + c; if (L >= total) return false;
;         if (nM1 == 144 && nN1 == 8 && nM2 == 0 && G == 256) {
;             const int xcd = c & 7, o = c >> 3;
;             const int grp = (i < 4) ? xcd * 4 + i : 32 + (xcd >> 1), idx = (i < 4) ? o : (xcd & 1) * 16 + o;
;             u.pm = grp * 4 + (idx & 3); u.pn = idx >> 2; return true; }
;         int w = (int)L; { const int q = total / NXCD, r = total % NXCD, xcd = w % NXCD, off = w / NXCD; w = (xcd < r ? xcd * (q + 1) : r * (q + 1) + (xcd - r) * q) + off; }
;         int nM = nM1, nN = nN1; const bool second = w >= n1; if (second) { w -= n1; nM = nM2; nN = nN2; }
;         const int wgm = 4;
;         const int nig = wgm * nN, gid = w / nig, fm = gid * wgm, gsz = (nM - fm) < wgm ? (nM - fm) : wgm;
;         int pm = fm + ((w % nig) % gsz), pn = (w % nig) / gsz;
;         if (second) { pm += pm2; pn = pn < split ? a0 + pn : a1 + pn; }
;         u.pm = pm; u.pn = pn; return true;
; template <class Epi, class Sched, bool ALIGN_EPI = false, bool SP2 = false, bool ABLK = false, bool BBLK = false>
; __device__ __forceinline__ void gemm_phase(PG8_LAS unsigned char* lds, const Gemm g, const Sched& S, const Epi& E) {
;     ...
; #pragma unroll
;         for (int a = 0; a < 2; ++a)
; #pragma unroll
;             for (int b = 0; b < 2; ++b)
; #pragma unroll
;                 for (int m = 0; m < 4; ++m)
; #pragma unroll
;                     for (int n = 0; n < 2; ++n) acc[a][b][m][n] = (f32x4){0.f, 0.f, 0.f, 0.f};
;         cur = nxt; cA = nA; cB = nB; ++ui;
;         if constexpr (ALIGN_EPI) { if (wr == 1) PG8_BAR; }
.Ly_766:
	v_pk_mov_b32 v[2:3], 0, 0
	v_pk_mov_b32 v[4:5], 0, 0
	v_pk_mov_b32 v[6:7], 0, 0
	v_pk_mov_b32 v[8:9], 0, 0
	v_pk_mov_b32 v[10:11], 0, 0
	v_pk_mov_b32 v[12:13], 0, 0
	v_pk_mov_b32 v[14:15], 0, 0
	v_pk_mov_b32 v[16:17], 0, 0
	v_pk_mov_b32 v[18:19], 0, 0
	v_pk_mov_b32 v[20:21], 0, 0
	v_pk_mov_b32 v[22:23], 0, 0
	v_pk_mov_b32 v[24:25], 0, 0
	v_pk_mov_b32 v[26:27], 0, 0
	v_pk_mov_b32 v[28:29], 0, 0
	v_pk_mov_b32 v[30:31], 0, 0
	v_pk_mov_b32 v[32:33], 0, 0
	v_pk_mov_b32 v[34:35], 0, 0
	v_pk_mov_b32 v[36:37], 0, 0
	v_pk_mov_b32 v[38:39], 0, 0
	v_pk_mov_b32 v[40:41], 0, 0
	v_pk_mov_b32 v[42:43], 0, 0
	v_pk_mov_b32 v[44:45], 0, 0
	v_pk_mov_b32 v[46:47], 0, 0
	v_pk_mov_b32 v[48:49], 0, 0
	v_pk_mov_b32 v[50:51], 0, 0
	v_pk_mov_b32 v[52:53], 0, 0
	v_pk_mov_b32 v[54:55], 0, 0
	v_pk_mov_b32 v[56:57], 0, 0
	v_pk_mov_b32 v[58:59], 0, 0
	v_pk_mov_b32 v[60:61], 0, 0
	v_pk_mov_b32 v[62:63], 0, 0
	v_pk_mov_b32 v[64:65], 0, 0
	v_pk_mov_b32 v[66:67], 0, 0
	v_pk_mov_b32 v[68:69], 0, 0
	v_pk_mov_b32 v[70:71], 0, 0
	v_pk_mov_b32 v[72:73], 0, 0
	v_pk_mov_b32 v[74:75], 0, 0
	v_pk_mov_b32 v[76:77], 0, 0
	v_pk_mov_b32 v[78:79], 0, 0
	v_pk_mov_b32 v[80:81], 0, 0
	v_pk_mov_b32 v[82:83], 0, 0
	v_pk_mov_b32 v[84:85], 0, 0
	v_pk_mov_b32 v[86:87], 0, 0
	v_pk_mov_b32 v[88:89], 0, 0
	v_pk_mov_b32 v[90:91], 0, 0
	v_pk_mov_b32 v[92:93], 0, 0
	v_pk_mov_b32 v[94:95], 0, 0
	v_pk_mov_b32 v[96:97], 0, 0
	v_pk_mov_b32 v[98:99], 0, 0
	v_pk_mov_b32 v[100:101], 0, 0
	v_pk_mov_b32 v[102:103], 0, 0
	v_pk_mov_b32 v[104:105], 0, 0
	v_pk_mov_b32 v[106:107], 0, 0
	v_pk_mov_b32 v[108:109], 0, 0
	v_pk_mov_b32 v[110:111], 0, 0
	v_pk_mov_b32 v[112:113], 0, 0
	v_pk_mov_b32 v[114:115], 0, 0
	v_pk_mov_b32 v[116:117], 0, 0
	v_pk_mov_b32 v[118:119], 0, 0
	v_pk_mov_b32 v[120:121], 0, 0
	v_pk_mov_b32 v[122:123], 0, 0
	v_pk_mov_b32 v[124:125], 0, 0
	v_pk_mov_b32 v[126:127], 0, 0
	v_pk_mov_b32 v[128:129], 0, 0
	s_add_i32 s61, s61, 1
	s_mul_i32 s1, s61, s43
	s_mul_hi_u32 s6, s61, s41
	s_add_i32 s6, s6, s1
	s_mul_i32 s1, s61, s41
	s_add_u32 s18, s1, s42
	s_addc_u32 s19, s6, s44
	v_mov_b64_e32 v[2:3], 0x80
	v_cmp_gt_i64_e32 vcc, s[18:19], v[194:195]
	v_cmp_lt_i64_e64 s[6:7], s[18:19], v[2:3]
	s_cbranch_vccnz .Lyh766_765
	s_ashr_i32 s1, s18, 31
	s_lshr_b32 s1, s1, 29
	s_add_i32 s1, s18, s1
	s_and_b32 s11, s1, -8
	s_sub_i32 s11, s18, s11
	s_cmp_gt_i32 s11, -1
	s_mov_b64 s[12:13], -1
	s_cbranch_scc0 .Lyh766_762
	s_lshl_b32 s14, s11, 4
	s_mov_b64 s[12:13], 0

; #define PG8_STAGE(bufoff, gbase, voff) do { _Pragma("unroll") for (int _i = 0; _i < 2; ++_i) \
;         __builtin_amdgcn_global_load_lds((const unsigned*)((const char*)(gbase) + (voff)[_i]), (PG8_LAS unsigned*)(lds + (bufoff) + ldsw + _i * 8192), 16, 0, 0); } while (0)
; #define PG8_LDA(dst, b, h) do { _Pragma("unroll") for (int m = 0; m < 4; ++m) _Pragma("unroll") for (int k = 0; k < 2; ++k) dst[m][k] = *(const PG8_LAS bf16x8*)(lds + PG8_SA(b, h) + aoff + m * 2048 + k * 1024); } while (0)
; #define PG8_LDB(dst, b, h) do { _Pragma("unroll") for (int n = 0; n < 2; ++n) _Pragma("unroll") for (int k = 0; k < 2; ++k) dst[n][k] = *(const PG8_LAS bf16x8*)(lds + PG8_SB(b, h) + boff + n * 2048 + k * 1024); } while (0)
; #define PG8_MMA(ai, bj, At, Bt) do { __builtin_amdgcn_s_setprio(1); _Pragma("unroll") for (int m = 0; m < 4; ++m) _Pragma("unroll") for (int n = 0; n < 2; ++n) _Pragma("unroll") for (int k = 0; k < 2; ++k) \
;         acc[ai][bj][m][n] = __builtin_amdgcn_mfma_f32_16x16x32_bf16(Bt[n][k], At[m][k], acc[ai][bj][m][n], 0, 0, 0); __builtin_amdgcn_s_setprio(0); } while (0)
; #define PG8_WAIT_V(n) asm volatile("s_waitcnt vmcnt(" #n ")" ::: "memory")
; template <class Epi, class Sched, bool ALIGN_EPI = false, bool SP2 = false, bool ABLK = false, bool BBLK = false>
; __device__ __forceinline__ void gemm_phase(PG8_LAS unsigned char* lds, const Gemm g, const Sched& S, const Epi& E) {
;     ...
;     for (;;) {
;         const bool has_next = S.next(ui + 1, nxt);
;         const char* nA = has_next ? (const char*)g.A + (size_t)nxt.pm * tstepA : cA; const char* nB = has_next ? (const char*)g.Bt + (size_t)nxt.pn * tstepB : cB;
;         for (int t = 0; t < nt; t += 2) {
;             const bool last = (t == nt - 2);
;             const char* a1 = cA + (size_t)(t + 1) * kstepA;
;             const char* a2 = last ? nA : cA + (size_t)(t + 2) * kstepA; const char* b2 = last ? nB : cB + (size_t)(t + 2) * kstepB;
;             const char* a3 = a2 + kstepA; const char* b3 = b2 + kstepB;
;             if (last && has_next) S.a_ready(nxt);
;             if constexpr (SP2) {
;             PG8_LDB(B0, 0, 0); PG8_LDB(B1, 0, 1); PG8_SCHED; PG8_LDA(At, 0, 0); PG8_STAGE(PG8_SA(1, 1), a1 + hstepA, voffA);
;             PG8_WAIT_V(8); PG8_WAIT_L(0); PG8_BAR; PG8_MMA(0, 0, At, B0); PG8_MMA(0, 1, At, B1); PG8_BAR; PG8_SCHED;
;     ...
;         if constexpr (ALIGN_EPI) { if (wr == 1) PG8_BAR; }
.Lyh766_765:
	s_ashr_i32 s15, s14, 31
	s_lshl_b64 s[18:19], s[14:15], 20
	s_add_u32 s18, s33, s18
	s_addc_u32 s19, s34, s19
	s_and_b64 s[20:21], s[6:7], exec
	s_cselect_b32 s1, s19, s25
	s_cselect_b32 s11, s18, s24
	s_ashr_i32 s13, s12, 31
	s_lshl_b64 s[20:21], s[12:13], 20
	s_add_u32 s20, s35, s20
	s_addc_u32 s21, s36, s21
	s_and_b64 s[28:29], s[6:7], exec
	s_cselect_b32 s13, s21, s27
	s_cselect_b32 s15, s20, s26
	s_add_u32 s24, s24, 0x80080
	s_addc_u32 s25, s25, 0
	s_add_u32 s23, s26, 0x100
	v_mov_b32_e32 v2, 0
	s_addc_u32 s65, s27, 0
	s_mov_b32 s68, -2
	v_pk_mov_b32 v[2:3], 0, 0
	s_barrier
	s_add_u32 s26, s24, 0xfff80080
	s_addc_u32 s27, s25, -1
	s_add_i32 s72, 0, 0x10000
	s_cmp_eq_u32 s68, 28
	s_cselect_b32 s29, s1, s27
	s_cselect_b32 s28, s11, s26
	v_add_u32_e32 v142, s72, v145
	s_cselect_b32 s27, s13, s65
	s_cselect_b32 s26, s15, s23
	s_add_i32 s75, 0, 0x14000
	ds_read_b128 v[148:151], v142
	ds_read_b128 v[152:155], v142 offset:1024
	ds_read_b128 v[156:159], v142 offset:2048
	ds_read_b128 v[160:163], v142 offset:3072
	v_add_u32_e32 v142, s75, v145
	ds_read_b128 v[164:167], v142
	ds_read_b128 v[168:171], v142 offset:1024
	ds_read_b128 v[172:175], v142 offset:2048
	ds_read_b128 v[176:179], v142 offset:3072
	v_lshl_add_u64 v[142:143], s[24:25], 0, v[138:139]
	s_add_i32 m0, s45, 0xc000
	ds_read_b128 v[180:183], v146
	ds_read_b128 v[196:199], v146 offset:1024
	ds_read_b128 v[200:203], v146 offset:2048
	ds_read_b128 v[204:207], v146 offset:3072
	ds_read_b128 v[208:211], v146 offset:4096
	ds_read_b128 v[212:215], v146 offset:5120
	ds_read_b128 v[216:219], v146 offset:6144
	ds_read_b128 v[220:223], v146 offset:7168
	global_load_lds_dwordx4 v[142:143], off
	v_lshl_add_u64 v[142:143], s[24:25], 0, v[140:141]
	s_add_i32 m0, s45, 0xe000
	s_nop 0
	global_load_lds_dwordx4 v[142:143], off
	s_waitcnt vmcnt(8)
	s_waitcnt lgkmcnt(0)
	s_barrier
	s_branch .Lpeel_766

;     __device__ __forceinline__ bool next(int i, Unit& u) const {
;         const long L = (long)i * G + c; if (L >= total) return false;
;         if (nM1 == 144 && nN1 == 8 && nM2 == 0 && G == 256) {
;             const int xcd = c & 7, o = c >> 3;
;             const int grp = (i < 4) ? xcd * 4 + i : 32 + (xcd >> 1), idx = (i < 4) ? o : (xcd & 1) * 16 + o;
;             u.pm = grp * 4 + (idx & 3); u.pn = idx >> 2; return true; }
;         int w = (int)L; { const int q = total / NXCD, r = total % NXCD, xcd = w % NXCD, off = w / NXCD; w = (xcd < r ? xcd * (q + 1) : r * (q + 1) + (xcd - r) * q) + off; }
;         int nM = nM1, nN = nN1; const bool second = w >= n1; if (second) { w -= n1; nM = nM2; nN = nN2; }
;         const int wgm = 4;
;         const int nig = wgm * nN, gid = w / nig, fm = gid * wgm, gsz = (nM - fm) < wgm ? (nM - fm) : wgm;
;         int pm = fm + ((w % nig) % gsz), pn = (w % nig) / gsz;
;         if (second) { pm += pm2; pn = pn < split ? a0 + pn : a1 + pn; }
;         u.pm = pm; u.pn = pn; return true;
; template <class Epi, class Sched, bool ALIGN_EPI = false, bool SP2 = false, bool ABLK = false, bool BBLK = false>
; __device__ __forceinline__ void gemm_phase(PG8_LAS unsigned char* lds, const Gemm g, const Sched& S, const Epi& E) {
;     ...
;         const bool has_next = S.next(ui + 1, nxt);
;         const char* nA = has_next ? (const char*)g.A + (size_t)nxt.pm * tstepA : cA; const char* nB = has_next ? (const char*)g.Bt + (size_t)nxt.pn * tstepB : cB;
.LBB0_783:
	s_and_b64 vcc, exec, s[8:9]
	s_cbranch_vccz .Ly_790
	s_add_i32 s72, s72, 1
	s_mul_i32 s1, s72, s43
	s_mul_hi_u32 s6, s72, s41
	s_add_i32 s6, s6, s1
	s_mul_i32 s1, s72, s41
	s_add_u32 s18, s1, s33
	s_addc_u32 s19, s6, s34
	v_mov_b64_e32 v[2:3], 0x80
	v_cmp_gt_i64_e32 vcc, s[18:19], v[194:195]
	v_cmp_lt_i64_e64 s[6:7], s[18:19], v[2:3]
	s_cbranch_vccnz .LBB0_789
	s_ashr_i32 s1, s18, 31
	s_lshr_b32 s1, s1, 29
	s_add_i32 s1, s18, s1
	s_and_b32 s11, s1, -8
	s_sub_i32 s11, s18, s11
	s_cmp_gt_i32 s11, -1
	s_mov_b64 s[12:13], -1
	s_cbranch_scc0 .LBB0_786
	s_lshl_b32 s14, s11, 4
	s_mov_b64 s[12:13], 0

; #define PG8_BAR __builtin_amdgcn_s_barrier()
;     __device__ __forceinline__ bool next(int i, Unit& u) const {
;         const long L = (long)i * G + c; if (L >= total) return false;
;         if (nM1 == 144 && nN1 == 8 && nM2 == 0 && G == 256) {
;             const int xcd = c & 7, o = c >> 3;
;             const int grp = (i < 4) ? xcd * 4 + i : 32 + (xcd >> 1), idx = (i < 4) ? o : (xcd & 1) * 16 + o;
;             u.pm = grp * 4 + (idx & 3); u.pn = idx >> 2; return true; }
;         int w = (int)L; { const int q = total / NXCD, r = total % NXCD, xcd = w % NXCD, off = w / NXCD; w = (xcd < r ? xcd * (q + 1) : r * (q + 1) + (xcd - r) * q) + off; }
;         int nM = nM1, nN = nN1; const bool second = w >= n1; if (second) { w -= n1; nM = nM2; nN = nN2; }
;         const int wgm = 4;
;         const int nig = wgm * nN, gid = w / nig, fm = gid * wgm, gsz = (nM - fm) < wgm ? (nM - fm) : wgm;
;         int pm = fm + ((w % nig) % gsz), pn = (w % nig) / gsz;
;         if (second) { pm += pm2; pn = pn < split ? a0 + pn : a1 + pn; }
;         u.pm = pm; u.pn = pn; return true;
; template <class Epi, class Sched, bool ALIGN_EPI = false, bool SP2 = false, bool ABLK = false, bool BBLK = false>
; __device__ __forceinline__ void gemm_phase(PG8_LAS unsigned char* lds, const Gemm g, const Sched& S, const Epi& E) {
;     ...
; #pragma unroll
;         for (int a = 0; a < 2; ++a)
; #pragma unroll
;             for (int b = 0; b < 2; ++b)
; #pragma unroll
;                 for (int m = 0; m < 4; ++m)
; #pragma unroll
;                     for (int n = 0; n < 2; ++n) acc[a][b][m][n] = (f32x4){0.f, 0.f, 0.f, 0.f};
;         cur = nxt; cA = nA; cB = nB; ++ui;
;         if constexpr (ALIGN_EPI) { if (wr == 1) PG8_BAR; }
.Ly_790:
	v_pk_mov_b32 v[2:3], 0, 0
	v_pk_mov_b32 v[4:5], 0, 0
	v_pk_mov_b32 v[6:7], 0, 0
	v_pk_mov_b32 v[8:9], 0, 0
	v_pk_mov_b32 v[10:11], 0, 0
	v_pk_mov_b32 v[12:13], 0, 0
	v_pk_mov_b32 v[14:15], 0, 0
	v_pk_mov_b32 v[16:17], 0, 0
	v_pk_mov_b32 v[18:19], 0, 0
	v_pk_mov_b32 v[20:21], 0, 0
	v_pk_mov_b32 v[22:23], 0, 0
	v_pk_mov_b32 v[24:25], 0, 0
	v_pk_mov_b32 v[26:27], 0, 0
	v_pk_mov_b32 v[28:29], 0, 0
	v_pk_mov_b32 v[30:31], 0, 0
	v_pk_mov_b32 v[32:33], 0, 0
	v_pk_mov_b32 v[34:35], 0, 0
	v_pk_mov_b32 v[36:37], 0, 0
	v_pk_mov_b32 v[38:39], 0, 0
	v_pk_mov_b32 v[40:41], 0, 0
	v_pk_mov_b32 v[42:43], 0, 0
	v_pk_mov_b32 v[44:45], 0, 0
	v_pk_mov_b32 v[46:47], 0, 0
	v_pk_mov_b32 v[48:49], 0, 0
	v_pk_mov_b32 v[50:51], 0, 0
	v_pk_mov_b32 v[52:53], 0, 0
	v_pk_mov_b32 v[54:55], 0, 0
	v_pk_mov_b32 v[56:57], 0, 0
	v_pk_mov_b32 v[58:59], 0, 0
	v_pk_mov_b32 v[60:61], 0, 0
	v_pk_mov_b32 v[62:63], 0, 0
	v_pk_mov_b32 v[64:65], 0, 0
	v_pk_mov_b32 v[66:67], 0, 0
	v_pk_mov_b32 v[68:69], 0, 0
	v_pk_mov_b32 v[70:71], 0, 0
	v_pk_mov_b32 v[72:73], 0, 0
	v_pk_mov_b32 v[74:75], 0, 0
	v_pk_mov_b32 v[76:77], 0, 0
	v_pk_mov_b32 v[78:79], 0, 0
	v_pk_mov_b32 v[80:81], 0, 0
	v_pk_mov_b32 v[82:83], 0, 0
	v_pk_mov_b32 v[84:85], 0, 0
	v_pk_mov_b32 v[86:87], 0, 0
	v_pk_mov_b32 v[88:89], 0, 0
	v_pk_mov_b32 v[90:91], 0, 0
	v_pk_mov_b32 v[92:93], 0, 0
	v_pk_mov_b32 v[94:95], 0, 0
	v_pk_mov_b32 v[96:97], 0, 0
	v_pk_mov_b32 v[98:99], 0, 0
	v_pk_mov_b32 v[100:101], 0, 0
	v_pk_mov_b32 v[102:103], 0, 0
	v_pk_mov_b32 v[104:105], 0, 0
	v_pk_mov_b32 v[106:107], 0, 0
	v_pk_mov_b32 v[108:109], 0, 0
	v_pk_mov_b32 v[110:111], 0, 0
	v_pk_mov_b32 v[112:113], 0, 0
	v_pk_mov_b32 v[114:115], 0, 0
	v_pk_mov_b32 v[116:117], 0, 0
	v_pk_mov_b32 v[118:119], 0, 0
	v_pk_mov_b32 v[120:121], 0, 0
	v_pk_mov_b32 v[122:123], 0, 0
	v_pk_mov_b32 v[124:125], 0, 0
	v_pk_mov_b32 v[126:127], 0, 0
	v_pk_mov_b32 v[128:129], 0, 0
	s_add_i32 s72, s72, 1
	s_mul_i32 s1, s72, s43
	s_mul_hi_u32 s6, s72, s41
	s_add_i32 s6, s6, s1
	s_mul_i32 s1, s72, s41
	s_add_u32 s18, s1, s33
	s_addc_u32 s19, s6, s34
	v_mov_b64_e32 v[2:3], 0x80
	v_cmp_gt_i64_e32 vcc, s[18:19], v[194:195]
	v_cmp_lt_i64_e64 s[6:7], s[18:19], v[2:3]
	s_cbranch_vccnz .Lyh790_789
	s_ashr_i32 s1, s18, 31
	s_lshr_b32 s1, s1, 29
	s_add_i32 s1, s18, s1
	s_and_b32 s11, s1, -8
	s_sub_i32 s11, s18, s11
	s_cmp_gt_i32 s11, -1
	s_mov_b64 s[12:13], -1
	s_cbranch_scc0 .Lyh790_786
	s_lshl_b32 s14, s11, 4
	s_mov_b64 s[12:13], 0

; #define PG8_STAGE(bufoff, gbase, voff) do { _Pragma("unroll") for (int _i = 0; _i < 2; ++_i) \
;         __builtin_amdgcn_global_load_lds((const unsigned*)((const char*)(gbase) + (voff)[_i]), (PG8_LAS unsigned*)(lds + (bufoff) + ldsw + _i * 8192), 16, 0, 0); } while (0)
; #define PG8_LDA(dst, b, h) do { _Pragma("unroll") for (int m = 0; m < 4; ++m) _Pragma("unroll") for (int k = 0; k < 2; ++k) dst[m][k] = *(const PG8_LAS bf16x8*)(lds + PG8_SA(b, h) + aoff + m * 2048 + k * 1024); } while (0)
; #define PG8_LDB(dst, b, h) do { _Pragma("unroll") for (int n = 0; n < 2; ++n) _Pragma("unroll") for (int k = 0; k < 2; ++k) dst[n][k] = *(const PG8_LAS bf16x8*)(lds + PG8_SB(b, h) + boff + n * 2048 + k * 1024); } while (0)
; #define PG8_MMA(ai, bj, At, Bt) do { __builtin_amdgcn_s_setprio(1); _Pragma("unroll") for (int m = 0; m < 4; ++m) _Pragma("unroll") for (int n = 0; n < 2; ++n) _Pragma("unroll") for (int k = 0; k < 2; ++k) \
;         acc[ai][bj][m][n] = __builtin_amdgcn_mfma_f32_16x16x32_bf16(Bt[n][k], At[m][k], acc[ai][bj][m][n], 0, 0, 0); __builtin_amdgcn_s_setprio(0); } while (0)
; #define PG8_WAIT_V(n) asm volatile("s_waitcnt vmcnt(" #n ")" ::: "memory")
; template <class Epi, class Sched, bool ALIGN_EPI = false, bool SP2 = false, bool ABLK = false, bool BBLK = false>
; __device__ __forceinline__ void gemm_phase(PG8_LAS unsigned char* lds, const Gemm g, const Sched& S, const Epi& E) {
;     ...
;     for (;;) {
;         const bool has_next = S.next(ui + 1, nxt);
;         const char* nA = has_next ? (const char*)g.A + (size_t)nxt.pm * tstepA : cA; const char* nB = has_next ? (const char*)g.Bt + (size_t)nxt.pn * tstepB : cB;
;         for (int t = 0; t < nt; t += 2) {
;             const bool last = (t == nt - 2);
;             const char* a1 = cA + (size_t)(t + 1) * kstepA;
;             const char* a2 = last ? nA : cA + (size_t)(t + 2) * kstepA; const char* b2 = last ? nB : cB + (size_t)(t + 2) * kstepB;
;             const char* a3 = a2 + kstepA; const char* b3 = b2 + kstepB;
;             if (last && has_next) S.a_ready(nxt);
;             if constexpr (SP2) {
;             PG8_LDB(B0, 0, 0); PG8_LDB(B1, 0, 1); PG8_SCHED; PG8_LDA(At, 0, 0); PG8_STAGE(PG8_SA(1, 1), a1 + hstepA, voffA);
;             PG8_WAIT_V(8); PG8_WAIT_L(0); PG8_BAR; PG8_MMA(0, 0, At, B0); PG8_MMA(0, 1, At, B1); PG8_BAR; PG8_SCHED;
;     ...
;         if constexpr (ALIGN_EPI) { if (wr == 1) PG8_BAR; }
.Lyh790_789:
	s_ashr_i32 s15, s14, 31
	s_lshl_b64 s[18:19], s[14:15], 20
	s_add_u32 s18, s36, s18
	s_addc_u32 s19, s37, s19
	s_and_b64 s[20:21], s[6:7], exec
	s_cselect_b32 s1, s19, s25
	s_cselect_b32 s11, s18, s24
	s_ashr_i32 s13, s12, 31
	s_lshl_b64 s[20:21], s[12:13], 20
	s_add_u32 s20, s44, s20
	s_addc_u32 s21, s45, s21
	s_and_b64 s[28:29], s[6:7], exec
	s_cselect_b32 s13, s21, s27
	s_cselect_b32 s15, s20, s26
	s_add_u32 s24, s24, 0x80080
	s_addc_u32 s25, s25, 0
	s_add_u32 s23, s26, 0x100
	v_mov_b32_e32 v2, 0
	s_addc_u32 s73, s27, 0
	s_mov_b32 s81, -2
	v_pk_mov_b32 v[2:3], 0, 0
	s_barrier
	s_add_u32 s26, s24, 0xfff80080
	s_addc_u32 s27, s25, -1
	s_add_i32 s51, 0, 0x10000
	s_cmp_eq_u32 s81, 28
	s_cselect_b32 s29, s1, s27
	s_cselect_b32 s28, s11, s26
	v_add_u32_e32 v142, s51, v145
	s_cselect_b32 s27, s13, s73
	s_cselect_b32 s26, s15, s23
	s_add_i32 s75, 0, 0x14000
	ds_read_b128 v[148:151], v142
	ds_read_b128 v[152:155], v142 offset:1024
	ds_read_b128 v[156:159], v142 offset:2048
	ds_read_b128 v[160:163], v142 offset:3072
	v_add_u32_e32 v142, s75, v145
	ds_read_b128 v[164:167], v142
	ds_read_b128 v[168:171], v142 offset:1024
	ds_read_b128 v[172:175], v142 offset:2048
	ds_read_b128 v[176:179], v142 offset:3072
	v_lshl_add_u64 v[142:143], s[24:25], 0, v[138:139]
	s_add_i32 m0, s46, 0xc000
	ds_read_b128 v[180:183], v146
	ds_read_b128 v[196:199], v146 offset:1024
	ds_read_b128 v[200:203], v146 offset:2048
	ds_read_b128 v[204:207], v146 offset:3072
	ds_read_b128 v[208:211], v146 offset:4096
	ds_read_b128 v[212:215], v146 offset:5120
	ds_read_b128 v[216:219], v146 offset:6144
	ds_read_b128 v[220:223], v146 offset:7168
	global_load_lds_dwordx4 v[142:143], off
	v_lshl_add_u64 v[142:143], s[24:25], 0, v[140:141]
	s_add_i32 m0, s46, 0xe000
	s_nop 0
	global_load_lds_dwordx4 v[142:143], off
	s_waitcnt vmcnt(8)
	s_waitcnt lgkmcnt(0)
	s_barrier
	s_branch .Lpeel_790

;     __device__ __forceinline__ bool next(int i, Unit& u) const {
;         const long L = (long)i * G + c; if (L >= total) return false;
;         if (nM1 == 144 && nN1 == 8 && nM2 == 0 && G == 256) {
;             const int xcd = c & 7, o = c >> 3;
;             const int grp = (i < 4) ? xcd * 4 + i : 32 + (xcd >> 1), idx = (i < 4) ? o : (xcd & 1) * 16 + o;
;             u.pm = grp * 4 + (idx & 3); u.pn = idx >> 2; return true; }
;         int w = (int)L; { const int q = total / NXCD, r = total % NXCD, xcd = w % NXCD, off = w / NXCD; w = (xcd < r ? xcd * (q + 1) : r * (q + 1) + (xcd - r) * q) + off; }
;         int nM = nM1, nN = nN1; const bool second = w >= n1; if (second) { w -= n1; nM = nM2; nN = nN2; }
;         const int wgm = 4;
;         const int nig = wgm * nN, gid = w / nig, fm = gid * wgm, gsz = (nM - fm) < wgm ? (nM - fm) : wgm;
;         int pm = fm + ((w % nig) % gsz), pn = (w % nig) / gsz;
;         if (second) { pm += pm2; pn = pn < split ? a0 + pn : a1 + pn; }
;         u.pm = pm; u.pn = pn; return true;
; template <class Epi, class Sched, bool ALIGN_EPI = false, bool SP2 = false, bool ABLK = false, bool BBLK = false>
; __device__ __forceinline__ void gemm_phase(PG8_LAS unsigned char* lds, const Gemm g, const Sched& S, const Epi& E) {
;     ...
;         const bool has_next = S.next(ui + 1, nxt);
;         const char* nA = has_next ? (const char*)g.A + (size_t)nxt.pm * tstepA : cA; const char* nB = has_next ? (const char*)g.Bt + (size_t)nxt.pn * tstepB : cB;
.LBB0_1111:
	s_and_b64 vcc, exec, s[18:19]
	s_cbranch_vccz .Ly_1117
	s_add_i32 s90, s21, 1
	s_mul_i32 s6, s90, s42
	s_mul_hi_u32 s7, s90, s16
	s_add_i32 s7, s7, s6
	s_mul_i32 s6, s90, s16
	s_add_u32 s24, s6, s40
	s_addc_u32 s25, s7, s41
	v_mov_b64_e32 v[2:3], s[10:11]
	v_cmp_ge_i64_e32 vcc, s[24:25], v[2:3]
	v_cmp_lt_i64_e64 s[6:7], s[24:25], v[2:3]
	s_cbranch_vccnz .LBB0_1116
	s_mov_b64 s[26:27], -1
	s_and_b64 vcc, exec, s[4:5]
	s_cbranch_vccz .LBB0_1114
	s_ashr_i32 s20, s24, 31
	s_lshr_b32 s20, s20, 29
	s_add_i32 s20, s24, s20
	s_ashr_i32 s22, s20, 3
	s_and_b32 s20, s20, -8
	s_sub_i32 s20, s24, s20
	s_lshr_b32 s23, s20, 31
	v_readlane_b32 s24, v254, 32
	s_or_b32 s23, s24, s23
	s_mul_i32 s20, s23, s20
	s_add_i32 s20, s20, s22
	s_cmp_lt_i32 s20, s10
	s_cselect_b32 s22, 32, 4
	v_cvt_f32_ubyte0_e32 v2, s22
	v_rcp_iflag_f32_e32 v2, v2
	s_cselect_b32 s23, 0, s10
	s_cselect_b32 s24, s24, 0
	s_sub_i32 s26, 0, s22
	v_mul_f32_e32 v2, 0x4f7ffffe, v2
	v_cvt_u32_f32_e32 v2, v2
	s_sub_i32 s20, s20, s23
	s_abs_i32 s25, s20
	s_ashr_i32 s23, s20, 31
	v_readfirstlane_b32 s27, v2
	s_mul_i32 s26, s26, s27
	s_mul_hi_u32 s26, s27, s26
	s_add_i32 s27, s27, s26
	s_mul_hi_u32 s26, s25, s27
	s_mul_i32 s27, s26, s22
	s_sub_i32 s25, s25, s27
	s_add_i32 s27, s26, 1
	s_sub_i32 s31, s25, s22
	s_cmp_ge_u32 s25, s22
	s_cselect_b32 s26, s27, s26
	s_cselect_b32 s25, s31, s25
	s_add_i32 s27, s26, 1
	s_cmp_ge_u32 s25, s22
	s_cselect_b32 s25, s27, s26
	s_xor_b32 s25, s25, s23
	s_sub_i32 s23, s25, s23
	s_lshl_b32 s25, s23, 2
	s_sub_i32 s24, s24, s25
	s_min_i32 s24, s24, 4
	s_abs_i32 s26, s24
	v_cvt_f32_u32_e32 v2, s26
	s_sub_i32 s27, 0, s26
	s_mul_i32 s23, s23, s22
	s_sub_i32 s22, s20, s23
	v_rcp_iflag_f32_e32 v2, v2
	s_abs_i32 s20, s22
	s_xor_b32 s23, s22, s24
	s_ashr_i32 s23, s23, 31
	v_mul_f32_e32 v2, 0x4f7ffffe, v2
	v_cvt_u32_f32_e32 v2, v2
	s_nop 0
	v_readfirstlane_b32 s31, v2
	s_mul_i32 s27, s27, s31
	s_mul_hi_u32 s27, s31, s27
	s_add_i32 s31, s31, s27
	s_mul_hi_u32 s27, s20, s31
	s_mul_i32 s31, s27, s26
	s_sub_i32 s20, s20, s31
	s_add_i32 s31, s27, 1
	s_sub_i32 s36, s20, s26
	s_cmp_ge_u32 s20, s26
	s_cselect_b32 s27, s31, s27
	s_cselect_b32 s20, s36, s20
	s_add_i32 s31, s27, 1
	s_cmp_ge_u32 s20, s26
	s_cselect_b32 s20, s31, s27
	s_xor_b32 s20, s20, s23
	s_sub_i32 s20, s20, s23
	s_mul_i32 s23, s20, s24
	s_sub_i32 s22, s22, s23
	s_add_i32 s22, s22, s25
	s_mov_b64 s[26:27], 0

; #define PG8_BAR __builtin_amdgcn_s_barrier()
;     __device__ __forceinline__ bool next(int i, Unit& u) const {
;         const long L = (long)i * G + c; if (L >= total) return false;
;         if (nM1 == 144 && nN1 == 8 && nM2 == 0 && G == 256) {
;             const int xcd = c & 7, o = c >> 3;
;             const int grp = (i < 4) ? xcd * 4 + i : 32 + (xcd >> 1), idx = (i < 4) ? o : (xcd & 1) * 16 + o;
;             u.pm = grp * 4 + (idx & 3); u.pn = idx >> 2; return true; }
;         int w = (int)L; { const int q = total / NXCD, r = total % NXCD, xcd = w % NXCD, off = w / NXCD; w = (xcd < r ? xcd * (q + 1) : r * (q + 1) + (xcd - r) * q) + off; }
;         int nM = nM1, nN = nN1; const bool second = w >= n1; if (second) { w -= n1; nM = nM2; nN = nN2; }
;         const int wgm = 4;
;         const int nig = wgm * nN, gid = w / nig, fm = gid * wgm, gsz = (nM - fm) < wgm ? (nM - fm) : wgm;
;         int pm = fm + ((w % nig) % gsz), pn = (w % nig) / gsz;
;         if (second) { pm += pm2; pn = pn < split ? a0 + pn : a1 + pn; }
;         u.pm = pm; u.pn = pn; return true;
; template <class Epi, class Sched, bool ALIGN_EPI = false, bool SP2 = false, bool ABLK = false, bool BBLK = false>
; __device__ __forceinline__ void gemm_phase(PG8_LAS unsigned char* lds, const Gemm g, const Sched& S, const Epi& E) {
;     ...
; #pragma unroll
;         for (int a = 0; a < 2; ++a)
; #pragma unroll
;             for (int b = 0; b < 2; ++b)
; #pragma unroll
;                 for (int m = 0; m < 4; ++m)
; #pragma unroll
;                     for (int n = 0; n < 2; ++n) acc[a][b][m][n] = (f32x4){0.f, 0.f, 0.f, 0.f};
;         cur = nxt; cA = nA; cB = nB; ++ui;
;         if constexpr (ALIGN_EPI) { if (wr == 1) PG8_BAR; }
.Ly_1117:
	v_pk_mov_b32 v[2:3], 0, 0
	v_pk_mov_b32 v[4:5], 0, 0
	v_pk_mov_b32 v[6:7], 0, 0
	v_pk_mov_b32 v[8:9], 0, 0
	v_pk_mov_b32 v[10:11], 0, 0
	v_pk_mov_b32 v[12:13], 0, 0
	v_pk_mov_b32 v[14:15], 0, 0
	v_pk_mov_b32 v[16:17], 0, 0
	v_pk_mov_b32 v[18:19], 0, 0
	v_pk_mov_b32 v[20:21], 0, 0
	v_pk_mov_b32 v[22:23], 0, 0
	v_pk_mov_b32 v[24:25], 0, 0
	v_pk_mov_b32 v[26:27], 0, 0
	v_pk_mov_b32 v[28:29], 0, 0
	v_pk_mov_b32 v[30:31], 0, 0
	v_pk_mov_b32 v[32:33], 0, 0
	v_pk_mov_b32 v[34:35], 0, 0
	v_pk_mov_b32 v[36:37], 0, 0
	v_pk_mov_b32 v[38:39], 0, 0
	v_pk_mov_b32 v[40:41], 0, 0
	v_pk_mov_b32 v[42:43], 0, 0
	v_pk_mov_b32 v[44:45], 0, 0
	v_pk_mov_b32 v[46:47], 0, 0
	v_pk_mov_b32 v[48:49], 0, 0
	v_pk_mov_b32 v[50:51], 0, 0
	v_pk_mov_b32 v[52:53], 0, 0
	v_pk_mov_b32 v[54:55], 0, 0
	v_pk_mov_b32 v[56:57], 0, 0
	v_pk_mov_b32 v[58:59], 0, 0
	v_pk_mov_b32 v[60:61], 0, 0
	v_pk_mov_b32 v[62:63], 0, 0
	v_pk_mov_b32 v[64:65], 0, 0
	v_pk_mov_b32 v[66:67], 0, 0
	v_pk_mov_b32 v[68:69], 0, 0
	v_pk_mov_b32 v[70:71], 0, 0
	v_pk_mov_b32 v[72:73], 0, 0
	v_pk_mov_b32 v[74:75], 0, 0
	v_pk_mov_b32 v[76:77], 0, 0
	v_pk_mov_b32 v[78:79], 0, 0
	v_pk_mov_b32 v[80:81], 0, 0
	v_pk_mov_b32 v[82:83], 0, 0
	v_pk_mov_b32 v[84:85], 0, 0
	v_pk_mov_b32 v[86:87], 0, 0
	v_pk_mov_b32 v[88:89], 0, 0
	v_pk_mov_b32 v[90:91], 0, 0
	v_pk_mov_b32 v[92:93], 0, 0
	v_pk_mov_b32 v[94:95], 0, 0
	v_pk_mov_b32 v[96:97], 0, 0
	v_pk_mov_b32 v[98:99], 0, 0
	v_pk_mov_b32 v[100:101], 0, 0
	v_pk_mov_b32 v[102:103], 0, 0
	v_pk_mov_b32 v[104:105], 0, 0
	v_pk_mov_b32 v[106:107], 0, 0
	v_pk_mov_b32 v[108:109], 0, 0
	v_pk_mov_b32 v[110:111], 0, 0
	v_pk_mov_b32 v[112:113], 0, 0
	v_pk_mov_b32 v[114:115], 0, 0
	v_pk_mov_b32 v[116:117], 0, 0
	v_pk_mov_b32 v[118:119], 0, 0
	v_pk_mov_b32 v[120:121], 0, 0
	v_pk_mov_b32 v[122:123], 0, 0
	v_pk_mov_b32 v[124:125], 0, 0
	v_pk_mov_b32 v[126:127], 0, 0
	v_pk_mov_b32 v[128:129], 0, 0
	s_add_i32 s90, s21, 1
	s_mul_i32 s6, s90, s42
	s_mul_hi_u32 s7, s90, s16
	s_add_i32 s7, s7, s6
	s_mul_i32 s6, s90, s16
	s_add_u32 s24, s6, s40
	s_addc_u32 s25, s7, s41
	v_mov_b64_e32 v[2:3], s[10:11]
	v_cmp_ge_i64_e32 vcc, s[24:25], v[2:3]
	v_cmp_lt_i64_e64 s[6:7], s[24:25], v[2:3]
	s_cbranch_vccnz .Lyh1117_1116
	s_mov_b64 s[26:27], -1
	s_and_b64 vcc, exec, s[4:5]
	s_cbranch_vccz .Lyh1117_1114
	s_ashr_i32 s20, s24, 31
	s_lshr_b32 s20, s20, 29
	s_add_i32 s20, s24, s20
	s_ashr_i32 s22, s20, 3
	s_and_b32 s20, s20, -8
	s_sub_i32 s20, s24, s20
	s_lshr_b32 s23, s20, 31
	v_readlane_b32 s24, v254, 32
	s_or_b32 s23, s24, s23
	s_mul_i32 s20, s23, s20
	s_add_i32 s20, s20, s22
	s_cmp_lt_i32 s20, s10
	s_cselect_b32 s22, 32, 4
	v_cvt_f32_ubyte0_e32 v2, s22
	v_rcp_iflag_f32_e32 v2, v2
	s_cselect_b32 s23, 0, s10
	s_cselect_b32 s24, s24, 0
	s_sub_i32 s26, 0, s22
	v_mul_f32_e32 v2, 0x4f7ffffe, v2
	v_cvt_u32_f32_e32 v2, v2
	s_sub_i32 s20, s20, s23
	s_abs_i32 s25, s20
	s_ashr_i32 s23, s20, 31
	v_readfirstlane_b32 s27, v2
	s_mul_i32 s26, s26, s27
	s_mul_hi_u32 s26, s27, s26
	s_add_i32 s27, s27, s26
	s_mul_hi_u32 s26, s25, s27
	s_mul_i32 s27, s26, s22
	s_sub_i32 s25, s25, s27
	s_add_i32 s27, s26, 1
	s_sub_i32 s31, s25, s22
	s_cmp_ge_u32 s25, s22
	s_cselect_b32 s26, s27, s26
	s_cselect_b32 s25, s31, s25
	s_add_i32 s27, s26, 1
	s_cmp_ge_u32 s25, s22
	s_cselect_b32 s25, s27, s26
	s_xor_b32 s25, s25, s23
	s_sub_i32 s23, s25, s23
	s_lshl_b32 s25, s23, 2
	s_sub_i32 s24, s24, s25
	s_min_i32 s24, s24, 4
	s_abs_i32 s26, s24
	v_cvt_f32_u32_e32 v2, s26
	s_sub_i32 s27, 0, s26
	s_mul_i32 s23, s23, s22
	s_sub_i32 s22, s20, s23
	v_rcp_iflag_f32_e32 v2, v2
	s_abs_i32 s20, s22
	s_xor_b32 s23, s22, s24
	s_ashr_i32 s23, s23, 31
	v_mul_f32_e32 v2, 0x4f7ffffe, v2
	v_cvt_u32_f32_e32 v2, v2
	s_nop 0
	v_readfirstlane_b32 s31, v2
	s_mul_i32 s27, s27, s31
	s_mul_hi_u32 s27, s31, s27
	s_add_i32 s31, s31, s27
	s_mul_hi_u32 s27, s20, s31
	s_mul_i32 s31, s27, s26
	s_sub_i32 s20, s20, s31
	s_add_i32 s31, s27, 1
	s_sub_i32 s36, s20, s26
	s_cmp_ge_u32 s20, s26
	s_cselect_b32 s27, s31, s27
	s_cselect_b32 s20, s36, s20
	s_add_i32 s31, s27, 1
	s_cmp_ge_u32 s20, s26
	s_cselect_b32 s20, s31, s27
	s_xor_b32 s20, s20, s23
	s_sub_i32 s20, s20, s23
	s_mul_i32 s23, s20, s24
	s_sub_i32 s22, s22, s23
	s_add_i32 s22, s22, s25
	s_mov_b64 s[26:27], 0

; #define PG8_STAGE(bufoff, gbase, voff) do { _Pragma("unroll") for (int _i = 0; _i < 2; ++_i) \
;         __builtin_amdgcn_global_load_lds((const unsigned*)((const char*)(gbase) + (voff)[_i]), (PG8_LAS unsigned*)(lds + (bufoff) + ldsw + _i * 8192), 16, 0, 0); } while (0)
; #define PG8_LDA(dst, b, h) do { _Pragma("unroll") for (int m = 0; m < 4; ++m) _Pragma("unroll") for (int k = 0; k < 2; ++k) dst[m][k] = *(const PG8_LAS bf16x8*)(lds + PG8_SA(b, h) + aoff + m * 2048 + k * 1024); } while (0)
; #define PG8_LDB(dst, b, h) do { _Pragma("unroll") for (int n = 0; n < 2; ++n) _Pragma("unroll") for (int k = 0; k < 2; ++k) dst[n][k] = *(const PG8_LAS bf16x8*)(lds + PG8_SB(b, h) + boff + n * 2048 + k * 1024); } while (0)
; #define PG8_MMA(ai, bj, At, Bt) do { __builtin_amdgcn_s_setprio(1); _Pragma("unroll") for (int m = 0; m < 4; ++m) _Pragma("unroll") for (int n = 0; n < 2; ++n) _Pragma("unroll") for (int k = 0; k < 2; ++k) \
;         acc[ai][bj][m][n] = __builtin_amdgcn_mfma_f32_16x16x32_bf16(Bt[n][k], At[m][k], acc[ai][bj][m][n], 0, 0, 0); __builtin_amdgcn_s_setprio(0); } while (0)
; #define PG8_WAIT_V(n) asm volatile("s_waitcnt vmcnt(" #n ")" ::: "memory")
; template <class Epi, class Sched, bool ALIGN_EPI = false, bool SP2 = false, bool ABLK = false, bool BBLK = false>
; __device__ __forceinline__ void gemm_phase(PG8_LAS unsigned char* lds, const Gemm g, const Sched& S, const Epi& E) {
;     ...
;     for (;;) {
;         const bool has_next = S.next(ui + 1, nxt);
;         const char* nA = has_next ? (const char*)g.A + (size_t)nxt.pm * tstepA : cA; const char* nB = has_next ? (const char*)g.Bt + (size_t)nxt.pn * tstepB : cB;
;         for (int t = 0; t < nt; t += 2) {
;             const bool last = (t == nt - 2);
;             const char* a1 = cA + (size_t)(t + 1) * kstepA;
;             const char* a2 = last ? nA : cA + (size_t)(t + 2) * kstepA; const char* b2 = last ? nB : cB + (size_t)(t + 2) * kstepB;
;             const char* a3 = a2 + kstepA; const char* b3 = b2 + kstepB;
;             if (last && has_next) S.a_ready(nxt);
;             if constexpr (SP2) {
;             PG8_LDB(B0, 0, 0); PG8_LDB(B1, 0, 1); PG8_SCHED; PG8_LDA(At, 0, 0); PG8_STAGE(PG8_SA(1, 1), a1 + hstepA, voffA);
;             PG8_WAIT_V(8); PG8_WAIT_L(0); PG8_BAR; PG8_MMA(0, 0, At, B0); PG8_MMA(0, 1, At, B1); PG8_BAR; PG8_SCHED;
;     ...
;         if constexpr (ALIGN_EPI) { if (wr == 1) PG8_BAR; }
.Lyh1117_1116:
	s_ashr_i32 s23, s22, 31
	s_lshl_b64 s[24:25], s[22:23], 18
	s_add_u32 s24, s33, s24
	s_addc_u32 s25, s44, s25
	s_and_b64 s[26:27], s[6:7], exec
	s_cselect_b32 s23, s25, s35
	s_cselect_b32 s31, s24, s34
	s_ashr_i32 s21, s20, 31
	s_lshl_b64 s[26:27], s[20:21], 18
	s_add_u32 s26, s45, s26
	s_addc_u32 s27, s46, s27
	s_and_b64 s[36:37], s[6:7], exec
	s_cselect_b32 s21, s27, s1
	s_cselect_b32 s91, s26, s0
	s_add_u32 s92, s0, 0x10000
	s_addc_u32 s93, s1, 0
	s_add_u32 s0, s34, 0x20080
	v_mov_b32_e32 v2, 0
	s_addc_u32 s1, s35, 0
	s_mov_b32 s94, -2
	v_pk_mov_b32 v[2:3], 0, 0
	s_barrier
	s_add_u32 s34, s0, 0xfffe0080
	s_addc_u32 s35, s1, -1
	s_add_i32 s52, 0, 0x10000
	s_cmp_eq_u32 s94, 4
	s_cselect_b32 s37, s23, s35
	s_cselect_b32 s36, s31, s34
	s_cselect_b32 s35, s21, s93
	s_cselect_b32 s34, s91, s92
	s_add_i32 s75, 0, 0x14000
	v_add_u32_e32 v142, s52, v163
	v_add_u32_e32 v160, s75, v163
	ds_read_b128 v[130:133], v142
	ds_read_b128 v[134:137], v142 offset:1024
	ds_read_b128 v[138:141], v142 offset:2048
	ds_read_b128 v[142:145], v142 offset:3072
	ds_read_b128 v[146:149], v160
	ds_read_b128 v[166:169], v160 offset:1024
	ds_read_b128 v[170:173], v160 offset:2048
	ds_read_b128 v[174:177], v160 offset:3072
	v_lshl_add_u64 v[160:161], s[0:1], 0, v[156:157]
	s_add_i32 m0, s29, 0xc000
	ds_read_b128 v[178:181], v165
	ds_read_b128 v[182:185], v165 offset:1024
	ds_read_b128 v[196:199], v165 offset:2048
	ds_read_b128 v[200:203], v165 offset:3072
	ds_read_b128 v[204:207], v165 offset:4096
	ds_read_b128 v[208:211], v165 offset:5120
	ds_read_b128 v[212:215], v165 offset:6144
	ds_read_b128 v[216:219], v165 offset:7168
	global_load_lds_dwordx4 v[160:161], off
	v_lshl_add_u64 v[160:161], s[0:1], 0, v[158:159]
	s_add_i32 m0, s29, 0xe000
	s_nop 0
	global_load_lds_dwordx4 v[160:161], off
	s_waitcnt vmcnt(8)
	s_waitcnt lgkmcnt(0)
	s_barrier
	s_branch .Lpeel_1117

;     __device__ __forceinline__ bool next(int i, Unit& u) const {
;         const long L = (long)i * G + c; if (L >= total) return false;
;         if (nM1 == 144 && nN1 == 8 && nM2 == 0 && G == 256) {
;             const int xcd = c & 7, o = c >> 3;
;             const int grp = (i < 4) ? xcd * 4 + i : 32 + (xcd >> 1), idx = (i < 4) ? o : (xcd & 1) * 16 + o;
;             u.pm = grp * 4 + (idx & 3); u.pn = idx >> 2; return true; }
;         int w = (int)L; { const int q = total / NXCD, r = total % NXCD, xcd = w % NXCD, off = w / NXCD; w = (xcd < r ? xcd * (q + 1) : r * (q + 1) + (xcd - r) * q) + off; }
;         int nM = nM1, nN = nN1; const bool second = w >= n1; if (second) { w -= n1; nM = nM2; nN = nN2; }
;         const int wgm = 4;
;         const int nig = wgm * nN, gid = w / nig, fm = gid * wgm, gsz = (nM - fm) < wgm ? (nM - fm) : wgm;
;         int pm = fm + ((w % nig) % gsz), pn = (w % nig) / gsz;
;         if (second) { pm += pm2; pn = pn < split ? a0 + pn : a1 + pn; }
;         u.pm = pm; u.pn = pn; return true;
; template <class Epi, class Sched, bool ALIGN_EPI = false, bool SP2 = false, bool ABLK = false, bool BBLK = false>
; __device__ __forceinline__ void gemm_phase(PG8_LAS unsigned char* lds, const Gemm g, const Sched& S, const Epi& E) {
;     ...
;         const bool has_next = S.next(ui + 1, nxt);
;         const char* nA = has_next ? (const char*)g.A + (size_t)nxt.pm * tstepA : cA; const char* nB = has_next ? (const char*)g.Bt + (size_t)nxt.pn * tstepB : cB;
.LBB0_1134:
	s_and_b64 vcc, exec, s[14:15]
	s_cbranch_vccz .Ly_1140
	s_add_i32 s90, s21, 1
	s_mul_i32 s6, s90, s42
	s_mul_hi_u32 s7, s90, s16
	s_add_i32 s7, s7, s6
	s_mul_i32 s6, s90, s16
	s_add_u32 s24, s6, s40
	s_addc_u32 s25, s7, s41
	v_mov_b64_e32 v[2:3], s[10:11]
	v_cmp_ge_i64_e32 vcc, s[24:25], v[2:3]
	v_cmp_lt_i64_e64 s[6:7], s[24:25], v[2:3]
	s_cbranch_vccnz .LBB0_1139
	s_mov_b64 s[26:27], -1
	s_and_b64 vcc, exec, s[4:5]
	s_cbranch_vccz .LBB0_1137
	s_ashr_i32 s20, s24, 31
	s_lshr_b32 s20, s20, 29
	s_add_i32 s20, s24, s20
	s_ashr_i32 s22, s20, 3
	s_and_b32 s20, s20, -8
	s_sub_i32 s20, s24, s20
	s_lshr_b32 s23, s20, 31
	v_readlane_b32 s24, v254, 32
	s_or_b32 s23, s24, s23
	s_mul_i32 s20, s23, s20
	s_add_i32 s20, s20, s22
	s_cmp_lt_i32 s20, s10
	s_cselect_b32 s22, 32, 4
	v_cvt_f32_ubyte0_e32 v2, s22
	v_rcp_iflag_f32_e32 v2, v2
	s_cselect_b32 s23, 0, s10
	s_cselect_b32 s24, s24, 0
	s_sub_i32 s26, 0, s22
	v_mul_f32_e32 v2, 0x4f7ffffe, v2
	v_cvt_u32_f32_e32 v2, v2
	s_sub_i32 s20, s20, s23
	s_abs_i32 s25, s20
	s_ashr_i32 s23, s20, 31
	v_readfirstlane_b32 s27, v2
	s_mul_i32 s26, s26, s27
	s_mul_hi_u32 s26, s27, s26
	s_add_i32 s27, s27, s26
	s_mul_hi_u32 s26, s25, s27
	s_mul_i32 s27, s26, s22
	s_sub_i32 s25, s25, s27
	s_add_i32 s27, s26, 1
	s_sub_i32 s31, s25, s22
	s_cmp_ge_u32 s25, s22
	s_cselect_b32 s26, s27, s26
	s_cselect_b32 s25, s31, s25
	s_add_i32 s27, s26, 1
	s_cmp_ge_u32 s25, s22
	s_cselect_b32 s25, s27, s26
	s_xor_b32 s25, s25, s23
	s_sub_i32 s23, s25, s23
	s_lshl_b32 s25, s23, 2
	s_sub_i32 s24, s24, s25
	s_min_i32 s24, s24, 4
	s_abs_i32 s26, s24
	v_cvt_f32_u32_e32 v2, s26
	s_sub_i32 s27, 0, s26
	s_mul_i32 s23, s23, s22
	s_sub_i32 s22, s20, s23
	v_rcp_iflag_f32_e32 v2, v2
	s_abs_i32 s20, s22
	s_xor_b32 s23, s22, s24
	s_ashr_i32 s23, s23, 31
	v_mul_f32_e32 v2, 0x4f7ffffe, v2
	v_cvt_u32_f32_e32 v2, v2
	s_nop 0
	v_readfirstlane_b32 s31, v2
	s_mul_i32 s27, s27, s31
	s_mul_hi_u32 s27, s31, s27
	s_add_i32 s31, s31, s27
	s_mul_hi_u32 s27, s20, s31
	s_mul_i32 s31, s27, s26
	s_sub_i32 s20, s20, s31
	s_add_i32 s31, s27, 1
	s_sub_i32 s36, s20, s26
	s_cmp_ge_u32 s20, s26
	s_cselect_b32 s27, s31, s27
	s_cselect_b32 s20, s36, s20
	s_add_i32 s31, s27, 1
	s_cmp_ge_u32 s20, s26
	s_cselect_b32 s20, s31, s27
	s_xor_b32 s20, s20, s23
	s_sub_i32 s20, s20, s23
	s_mul_i32 s23, s20, s24
	s_sub_i32 s22, s22, s23
	s_add_i32 s22, s22, s25
	s_mov_b64 s[26:27], 0

; #define PG8_STAGE(bufoff, gbase, voff) do { _Pragma("unroll") for (int _i = 0; _i < 2; ++_i) \
;         __builtin_amdgcn_global_load_lds((const unsigned*)((const char*)(gbase) + (voff)[_i]), (PG8_LAS unsigned*)(lds + (bufoff) + ldsw + _i * 8192), 16, 0, 0); } while (0)
; #define PG8_LDA(dst, b, h) do { _Pragma("unroll") for (int m = 0; m < 4; ++m) _Pragma("unroll") for (int k = 0; k < 2; ++k) dst[m][k] = *(const PG8_LAS bf16x8*)(lds + PG8_SA(b, h) + aoff + m * 2048 + k * 1024); } while (0)
; #define PG8_LDB(dst, b, h) do { _Pragma("unroll") for (int n = 0; n < 2; ++n) _Pragma("unroll") for (int k = 0; k < 2; ++k) dst[n][k] = *(const PG8_LAS bf16x8*)(lds + PG8_SB(b, h) + boff + n * 2048 + k * 1024); } while (0)
; #define PG8_MMA(ai, bj, At, Bt) do { __builtin_amdgcn_s_setprio(1); _Pragma("unroll") for (int m = 0; m < 4; ++m) _Pragma("unroll") for (int n = 0; n < 2; ++n) _Pragma("unroll") for (int k = 0; k < 2; ++k) \
;         acc[ai][bj][m][n] = __builtin_amdgcn_mfma_f32_16x16x32_bf16(Bt[n][k], At[m][k], acc[ai][bj][m][n], 0, 0, 0); __builtin_amdgcn_s_setprio(0); } while (0)
; #define PG8_WAIT_V(n) asm volatile("s_waitcnt vmcnt(" #n ")" ::: "memory")
; template <class Epi, class Sched, bool ALIGN_EPI = false, bool SP2 = false, bool ABLK = false, bool BBLK = false>
; __device__ __forceinline__ void gemm_phase(PG8_LAS unsigned char* lds, const Gemm g, const Sched& S, const Epi& E) {
;     ...
;     for (;;) {
;         const bool has_next = S.next(ui + 1, nxt);
;         const char* nA = has_next ? (const char*)g.A + (size_t)nxt.pm * tstepA : cA; const char* nB = has_next ? (const char*)g.Bt + (size_t)nxt.pn * tstepB : cB;
;         for (int t = 0; t < nt; t += 2) {
;             const bool last = (t == nt - 2);
;             const char* a1 = cA + (size_t)(t + 1) * kstepA;
;             const char* a2 = last ? nA : cA + (size_t)(t + 2) * kstepA; const char* b2 = last ? nB : cB + (size_t)(t + 2) * kstepB;
;             const char* a3 = a2 + kstepA; const char* b3 = b2 + kstepB;
;             if (last && has_next) S.a_ready(nxt);
;             if constexpr (SP2) {
;             PG8_LDB(B0, 0, 0); PG8_LDB(B1, 0, 1); PG8_SCHED; PG8_LDA(At, 0, 0); PG8_STAGE(PG8_SA(1, 1), a1 + hstepA, voffA);
;             PG8_WAIT_V(8); PG8_WAIT_L(0); PG8_BAR; PG8_MMA(0, 0, At, B0); PG8_MMA(0, 1, At, B1); PG8_BAR; PG8_SCHED;
;     ...
;         if constexpr (ALIGN_EPI) { if (wr == 1) PG8_BAR; }
.Lyh1140_1139:
	s_ashr_i32 s23, s22, 31
	s_lshl_b64 s[24:25], s[22:23], 19
	s_add_u32 s24, s46, s24
	s_addc_u32 s25, s47, s25
	s_and_b64 s[26:27], s[6:7], exec
	s_cselect_b32 s23, s25, s35
	s_cselect_b32 s31, s24, s34
	s_ashr_i32 s21, s20, 31
	s_lshl_b64 s[26:27], s[20:21], 19
	s_add_u32 s26, s33, s26
	s_addc_u32 s27, s44, s27
	s_and_b64 s[36:37], s[6:7], exec
	s_cselect_b32 s21, s27, s1
	s_cselect_b32 s91, s26, s0
	s_add_u32 s92, s0, 0x10000
	s_addc_u32 s93, s1, 0
	s_add_u32 s0, s34, 0x40080
	v_mov_b32_e32 v2, 0
	s_addc_u32 s1, s35, 0
	s_mov_b32 s94, -2
	v_pk_mov_b32 v[2:3], 0, 0
	s_barrier
	s_add_u32 s34, s0, 0xfffc0080
	s_addc_u32 s35, s1, -1
	s_add_i32 s52, 0, 0x10000
	s_cmp_eq_u32 s94, 12
	s_cselect_b32 s37, s23, s35
	s_cselect_b32 s36, s31, s34
	s_cselect_b32 s35, s21, s93
	s_cselect_b32 s34, s91, s92
	s_add_i32 s75, 0, 0x14000
	v_add_u32_e32 v142, s52, v223
	v_add_u32_e32 v158, s75, v223
	ds_read_b128 v[130:133], v142
	ds_read_b128 v[134:137], v142 offset:1024
	ds_read_b128 v[138:141], v142 offset:2048
	ds_read_b128 v[142:145], v142 offset:3072
	ds_read_b128 v[146:149], v158
	ds_read_b128 v[150:153], v158 offset:1024
	ds_read_b128 v[154:157], v158 offset:2048
	ds_read_b128 v[158:161], v158 offset:3072
	v_lshl_add_u64 v[188:189], s[0:1], 0, v[202:203]
	s_add_i32 m0, s29, 0xc000
	ds_read_b128 v[162:165], v225
	ds_read_b128 v[166:169], v225 offset:1024
	ds_read_b128 v[170:173], v225 offset:2048
	ds_read_b128 v[174:177], v225 offset:3072
	ds_read_b128 v[178:181], v225 offset:4096
	ds_read_b128 v[182:185], v225 offset:5120
	ds_read_b128 v[206:209], v225 offset:6144
	ds_read_b128 v[210:213], v225 offset:7168
	global_load_lds_dwordx4 v[188:189], off
	v_lshl_add_u64 v[188:189], s[0:1], 0, v[204:205]
	s_add_i32 m0, s29, 0xe000
	s_nop 0
	global_load_lds_dwordx4 v[188:189], off
	s_waitcnt vmcnt(8)
	s_waitcnt lgkmcnt(0)
	s_barrier
	s_branch .Lpeel_1140

;     __device__ __forceinline__ bool next(int i, Unit& u) const {
;         const long L = (long)i * G + c; if (L >= total) return false;
;         if (nM1 == 144 && nN1 == 8 && nM2 == 0 && G == 256) {
;             const int xcd = c & 7, o = c >> 3;
;             const int grp = (i < 4) ? xcd * 4 + i : 32 + (xcd >> 1), idx = (i < 4) ? o : (xcd & 1) * 16 + o;
;             u.pm = grp * 4 + (idx & 3); u.pn = idx >> 2; return true; }
;         int w = (int)L; { const int q = total / NXCD, r = total % NXCD, xcd = w % NXCD, off = w / NXCD; w = (xcd < r ? xcd * (q + 1) : r * (q + 1) + (xcd - r) * q) + off; }
;         int nM = nM1, nN = nN1; const bool second = w >= n1; if (second) { w -= n1; nM = nM2; nN = nN2; }
;         const int wgm = 4;
;         const int nig = wgm * nN, gid = w / nig, fm = gid * wgm, gsz = (nM - fm) < wgm ? (nM - fm) : wgm;
;         int pm = fm + ((w % nig) % gsz), pn = (w % nig) / gsz;
;         if (second) { pm += pm2; pn = pn < split ? a0 + pn : a1 + pn; }
;         u.pm = pm; u.pn = pn; return true;
; template <class Epi, class Sched, bool ALIGN_EPI = false, bool SP2 = false, bool ABLK = false, bool BBLK = false>
; __device__ __forceinline__ void gemm_phase(PG8_LAS unsigned char* lds, const Gemm g, const Sched& S, const Epi& E) {
;     ...
;         const bool has_next = S.next(ui + 1, nxt);
;         const char* nA = has_next ? (const char*)g.A + (size_t)nxt.pm * tstepA : cA; const char* nB = has_next ? (const char*)g.Bt + (size_t)nxt.pn * tstepB : cB;
.LBB0_1157:
	s_and_b64 vcc, exec, s[12:13]
	s_cbranch_vccz .Ly_1163
	s_add_i32 s60, s19, 1
	s_mul_i32 s6, s60, s42
	s_mul_hi_u32 s7, s60, s16
	s_add_i32 s7, s7, s6
	s_mul_i32 s6, s60, s16
	s_add_u32 s22, s6, s40
	s_addc_u32 s23, s7, s41
	v_mov_b64_e32 v[2:3], s[10:11]
	v_cmp_ge_i64_e32 vcc, s[22:23], v[2:3]
	v_cmp_lt_i64_e64 s[6:7], s[22:23], v[2:3]
	s_cbranch_vccnz .LBB0_1162
	s_mov_b64 s[24:25], -1
	s_and_b64 vcc, exec, s[4:5]
	s_cbranch_vccz .LBB0_1160
	s_ashr_i32 s18, s22, 31
	s_lshr_b32 s18, s18, 29
	s_add_i32 s18, s22, s18
	s_ashr_i32 s20, s18, 3
	s_and_b32 s18, s18, -8
	s_sub_i32 s18, s22, s18
	s_lshr_b32 s21, s18, 31
	v_readlane_b32 s22, v254, 32
	s_or_b32 s21, s22, s21
	s_mul_i32 s18, s21, s18
	s_add_i32 s18, s18, s20
	s_cmp_lt_i32 s18, s10
	s_cselect_b32 s20, 32, 4
	v_cvt_f32_ubyte0_e32 v2, s20
	v_rcp_iflag_f32_e32 v2, v2
	s_cselect_b32 s21, 0, s10
	s_cselect_b32 s22, s22, 0
	s_sub_i32 s24, 0, s20
	v_mul_f32_e32 v2, 0x4f7ffffe, v2
	v_cvt_u32_f32_e32 v2, v2
	s_sub_i32 s18, s18, s21
	s_abs_i32 s23, s18
	s_ashr_i32 s21, s18, 31
	v_readfirstlane_b32 s25, v2
	s_mul_i32 s24, s24, s25
	s_mul_hi_u32 s24, s25, s24
	s_add_i32 s25, s25, s24
	s_mul_hi_u32 s24, s23, s25
	s_mul_i32 s25, s24, s20
	s_sub_i32 s23, s23, s25
	s_add_i32 s25, s24, 1
	s_sub_i32 s29, s23, s20
	s_cmp_ge_u32 s23, s20
	s_cselect_b32 s24, s25, s24
	s_cselect_b32 s23, s29, s23
	s_add_i32 s25, s24, 1
	s_cmp_ge_u32 s23, s20
	s_cselect_b32 s23, s25, s24
	s_xor_b32 s23, s23, s21
	s_sub_i32 s21, s23, s21
	s_lshl_b32 s23, s21, 2
	s_sub_i32 s22, s22, s23
	s_min_i32 s22, s22, 4
	s_abs_i32 s24, s22
	v_cvt_f32_u32_e32 v2, s24
	s_sub_i32 s25, 0, s24
	s_mul_i32 s21, s21, s20
	s_sub_i32 s20, s18, s21
	v_rcp_iflag_f32_e32 v2, v2
	s_abs_i32 s18, s20
	s_xor_b32 s21, s20, s22
	s_ashr_i32 s21, s21, 31
	v_mul_f32_e32 v2, 0x4f7ffffe, v2
	v_cvt_u32_f32_e32 v2, v2
	s_nop 0
	v_readfirstlane_b32 s29, v2
	s_mul_i32 s25, s25, s29
	s_mul_hi_u32 s25, s29, s25
	s_add_i32 s29, s29, s25
	s_mul_hi_u32 s25, s18, s29
	s_mul_i32 s29, s25, s24
	s_sub_i32 s18, s18, s29
	s_add_i32 s29, s25, 1
	s_sub_i32 s34, s18, s24
	s_cmp_ge_u32 s18, s24
	s_cselect_b32 s25, s29, s25
	s_cselect_b32 s18, s34, s18
	s_add_i32 s29, s25, 1
	s_cmp_ge_u32 s18, s24
	s_cselect_b32 s18, s29, s25
	s_xor_b32 s18, s18, s21
	s_sub_i32 s18, s18, s21
	s_mul_i32 s21, s18, s22
	s_sub_i32 s20, s20, s21
	s_add_i32 s20, s20, s23
	s_mov_b64 s[24:25], 0

; #define PG8_BAR __builtin_amdgcn_s_barrier()
;     __device__ __forceinline__ bool next(int i, Unit& u) const {
;         const long L = (long)i * G + c; if (L >= total) return false;
;         if (nM1 == 144 && nN1 == 8 && nM2 == 0 && G == 256) {
;             const int xcd = c & 7, o = c >> 3;
;             const int grp = (i < 4) ? xcd * 4 + i : 32 + (xcd >> 1), idx = (i < 4) ? o : (xcd & 1) * 16 + o;
;             u.pm = grp * 4 + (idx & 3); u.pn = idx >> 2; return true; }
;         int w = (int)L; { const int q = total / NXCD, r = total % NXCD, xcd = w % NXCD, off = w / NXCD; w = (xcd < r ? xcd * (q + 1) : r * (q + 1) + (xcd - r) * q) + off; }
;         int nM = nM1, nN = nN1; const bool second = w >= n1; if (second) { w -= n1; nM = nM2; nN = nN2; }
;         const int wgm = 4;
;         const int nig = wgm * nN, gid = w / nig, fm = gid * wgm, gsz = (nM - fm) < wgm ? (nM - fm) : wgm;
;         int pm = fm + ((w % nig) % gsz), pn = (w % nig) / gsz;
;         if (second) { pm += pm2; pn = pn < split ? a0 + pn : a1 + pn; }
;         u.pm = pm; u.pn = pn; return true;
; template <class Epi, class Sched, bool ALIGN_EPI = false, bool SP2 = false, bool ABLK = false, bool BBLK = false>
; __device__ __forceinline__ void gemm_phase(PG8_LAS unsigned char* lds, const Gemm g, const Sched& S, const Epi& E) {
;     ...
; #pragma unroll
;         for (int a = 0; a < 2; ++a)
; #pragma unroll
;             for (int b = 0; b < 2; ++b)
; #pragma unroll
;                 for (int m = 0; m < 4; ++m)
; #pragma unroll
;                     for (int n = 0; n < 2; ++n) acc[a][b][m][n] = (f32x4){0.f, 0.f, 0.f, 0.f};
;         cur = nxt; cA = nA; cB = nB; ++ui;
;         if constexpr (ALIGN_EPI) { if (wr == 1) PG8_BAR; }
.Ly_1163:
	v_pk_mov_b32 v[2:3], 0, 0
	v_pk_mov_b32 v[4:5], 0, 0
	v_pk_mov_b32 v[6:7], 0, 0
	v_pk_mov_b32 v[8:9], 0, 0
	v_pk_mov_b32 v[10:11], 0, 0
	v_pk_mov_b32 v[12:13], 0, 0
	v_pk_mov_b32 v[14:15], 0, 0
	v_pk_mov_b32 v[16:17], 0, 0
	v_pk_mov_b32 v[18:19], 0, 0
	v_pk_mov_b32 v[20:21], 0, 0
	v_pk_mov_b32 v[22:23], 0, 0
	v_pk_mov_b32 v[24:25], 0, 0
	v_pk_mov_b32 v[26:27], 0, 0
	v_pk_mov_b32 v[28:29], 0, 0
	v_pk_mov_b32 v[30:31], 0, 0
	v_pk_mov_b32 v[32:33], 0, 0
	v_pk_mov_b32 v[34:35], 0, 0
	v_pk_mov_b32 v[36:37], 0, 0
	v_pk_mov_b32 v[38:39], 0, 0
	v_pk_mov_b32 v[40:41], 0, 0
	v_pk_mov_b32 v[42:43], 0, 0
	v_pk_mov_b32 v[44:45], 0, 0
	v_pk_mov_b32 v[46:47], 0, 0
	v_pk_mov_b32 v[48:49], 0, 0
	v_pk_mov_b32 v[50:51], 0, 0
	v_pk_mov_b32 v[52:53], 0, 0
	v_pk_mov_b32 v[54:55], 0, 0
	v_pk_mov_b32 v[56:57], 0, 0
	v_pk_mov_b32 v[58:59], 0, 0
	v_pk_mov_b32 v[60:61], 0, 0
	v_pk_mov_b32 v[62:63], 0, 0
	v_pk_mov_b32 v[64:65], 0, 0
	v_pk_mov_b32 v[66:67], 0, 0
	v_pk_mov_b32 v[68:69], 0, 0
	v_pk_mov_b32 v[70:71], 0, 0
	v_pk_mov_b32 v[72:73], 0, 0
	v_pk_mov_b32 v[74:75], 0, 0
	v_pk_mov_b32 v[76:77], 0, 0
	v_pk_mov_b32 v[78:79], 0, 0
	v_pk_mov_b32 v[80:81], 0, 0
	v_pk_mov_b32 v[82:83], 0, 0
	v_pk_mov_b32 v[84:85], 0, 0
	v_pk_mov_b32 v[86:87], 0, 0
	v_pk_mov_b32 v[88:89], 0, 0
	v_pk_mov_b32 v[90:91], 0, 0
	v_pk_mov_b32 v[92:93], 0, 0
	v_pk_mov_b32 v[94:95], 0, 0
	v_pk_mov_b32 v[96:97], 0, 0
	v_pk_mov_b32 v[98:99], 0, 0
	v_pk_mov_b32 v[100:101], 0, 0
	v_pk_mov_b32 v[102:103], 0, 0
	v_pk_mov_b32 v[104:105], 0, 0
	v_pk_mov_b32 v[106:107], 0, 0
	v_pk_mov_b32 v[108:109], 0, 0
	v_pk_mov_b32 v[110:111], 0, 0
	v_pk_mov_b32 v[112:113], 0, 0
	v_pk_mov_b32 v[114:115], 0, 0
	v_pk_mov_b32 v[116:117], 0, 0
	v_pk_mov_b32 v[118:119], 0, 0
	v_pk_mov_b32 v[120:121], 0, 0
	v_pk_mov_b32 v[122:123], 0, 0
	v_pk_mov_b32 v[124:125], 0, 0
	v_pk_mov_b32 v[126:127], 0, 0
	v_pk_mov_b32 v[128:129], 0, 0
	s_add_i32 s60, s19, 1
	s_mul_i32 s6, s60, s42
	s_mul_hi_u32 s7, s60, s16
	s_add_i32 s7, s7, s6
	s_mul_i32 s6, s60, s16
	s_add_u32 s22, s6, s40
	s_addc_u32 s23, s7, s41
	v_mov_b64_e32 v[2:3], s[10:11]
	v_cmp_ge_i64_e32 vcc, s[22:23], v[2:3]
	v_cmp_lt_i64_e64 s[6:7], s[22:23], v[2:3]
	s_cbranch_vccnz .Lyh1163_1162
	s_mov_b64 s[24:25], -1
	s_and_b64 vcc, exec, s[4:5]
	s_cbranch_vccz .Lyh1163_1160
	s_ashr_i32 s18, s22, 31
	s_lshr_b32 s18, s18, 29
	s_add_i32 s18, s22, s18
	s_ashr_i32 s20, s18, 3
	s_and_b32 s18, s18, -8
	s_sub_i32 s18, s22, s18
	s_lshr_b32 s21, s18, 31
	v_readlane_b32 s22, v254, 32
	s_or_b32 s21, s22, s21
	s_mul_i32 s18, s21, s18
	s_add_i32 s18, s18, s20
	s_cmp_lt_i32 s18, s10
	s_cselect_b32 s20, 32, 4
	v_cvt_f32_ubyte0_e32 v2, s20
	v_rcp_iflag_f32_e32 v2, v2
	s_cselect_b32 s21, 0, s10
	s_cselect_b32 s22, s22, 0
	s_sub_i32 s24, 0, s20
	v_mul_f32_e32 v2, 0x4f7ffffe, v2
	v_cvt_u32_f32_e32 v2, v2
	s_sub_i32 s18, s18, s21
	s_abs_i32 s23, s18
	s_ashr_i32 s21, s18, 31
	v_readfirstlane_b32 s25, v2
	s_mul_i32 s24, s24, s25
	s_mul_hi_u32 s24, s25, s24
	s_add_i32 s25, s25, s24
	s_mul_hi_u32 s24, s23, s25
	s_mul_i32 s25, s24, s20
	s_sub_i32 s23, s23, s25
	s_add_i32 s25, s24, 1
	s_sub_i32 s29, s23, s20
	s_cmp_ge_u32 s23, s20
	s_cselect_b32 s24, s25, s24
	s_cselect_b32 s23, s29, s23
	s_add_i32 s25, s24, 1
	s_cmp_ge_u32 s23, s20
	s_cselect_b32 s23, s25, s24
	s_xor_b32 s23, s23, s21
	s_sub_i32 s21, s23, s21
	s_lshl_b32 s23, s21, 2
	s_sub_i32 s22, s22, s23
	s_min_i32 s22, s22, 4
	s_abs_i32 s24, s22
	v_cvt_f32_u32_e32 v2, s24
	s_sub_i32 s25, 0, s24
	s_mul_i32 s21, s21, s20
	s_sub_i32 s20, s18, s21
	v_rcp_iflag_f32_e32 v2, v2
	s_abs_i32 s18, s20
	s_xor_b32 s21, s20, s22
	s_ashr_i32 s21, s21, 31
	v_mul_f32_e32 v2, 0x4f7ffffe, v2
	v_cvt_u32_f32_e32 v2, v2
	s_nop 0
	v_readfirstlane_b32 s29, v2
	s_mul_i32 s25, s25, s29
	s_mul_hi_u32 s25, s29, s25
	s_add_i32 s29, s29, s25
	s_mul_hi_u32 s25, s18, s29
	s_mul_i32 s29, s25, s24
	s_sub_i32 s18, s18, s29
	s_add_i32 s29, s25, 1
	s_sub_i32 s34, s18, s24
	s_cmp_ge_u32 s18, s24
	s_cselect_b32 s25, s29, s25
	s_cselect_b32 s18, s34, s18
	s_add_i32 s29, s25, 1
	s_cmp_ge_u32 s18, s24
	s_cselect_b32 s18, s29, s25
	s_xor_b32 s18, s18, s21
	s_sub_i32 s18, s18, s21
	s_mul_i32 s21, s18, s22
	s_sub_i32 s20, s20, s21
	s_add_i32 s20, s20, s23
	s_mov_b64 s[24:25], 0

; #define PG8_STAGE(bufoff, gbase, voff) do { _Pragma("unroll") for (int _i = 0; _i < 2; ++_i) \
;         __builtin_amdgcn_global_load_lds((const unsigned*)((const char*)(gbase) + (voff)[_i]), (PG8_LAS unsigned*)(lds + (bufoff) + ldsw + _i * 8192), 16, 0, 0); } while (0)
; #define PG8_LDA(dst, b, h) do { _Pragma("unroll") for (int m = 0; m < 4; ++m) _Pragma("unroll") for (int k = 0; k < 2; ++k) dst[m][k] = *(const PG8_LAS bf16x8*)(lds + PG8_SA(b, h) + aoff + m * 2048 + k * 1024); } while (0)
; #define PG8_LDB(dst, b, h) do { _Pragma("unroll") for (int n = 0; n < 2; ++n) _Pragma("unroll") for (int k = 0; k < 2; ++k) dst[n][k] = *(const PG8_LAS bf16x8*)(lds + PG8_SB(b, h) + boff + n * 2048 + k * 1024); } while (0)
; #define PG8_MMA(ai, bj, At, Bt) do { __builtin_amdgcn_s_setprio(1); _Pragma("unroll") for (int m = 0; m < 4; ++m) _Pragma("unroll") for (int n = 0; n < 2; ++n) _Pragma("unroll") for (int k = 0; k < 2; ++k) \
;         acc[ai][bj][m][n] = __builtin_amdgcn_mfma_f32_16x16x32_bf16(Bt[n][k], At[m][k], acc[ai][bj][m][n], 0, 0, 0); __builtin_amdgcn_s_setprio(0); } while (0)
; #define PG8_WAIT_V(n) asm volatile("s_waitcnt vmcnt(" #n ")" ::: "memory")
; template <class Epi, class Sched, bool ALIGN_EPI = false, bool SP2 = false, bool ABLK = false, bool BBLK = false>
; __device__ __forceinline__ void gemm_phase(PG8_LAS unsigned char* lds, const Gemm g, const Sched& S, const Epi& E) {
;     ...
;     for (;;) {
;         const bool has_next = S.next(ui + 1, nxt);
;         const char* nA = has_next ? (const char*)g.A + (size_t)nxt.pm * tstepA : cA; const char* nB = has_next ? (const char*)g.Bt + (size_t)nxt.pn * tstepB : cB;
;         for (int t = 0; t < nt; t += 2) {
;             const bool last = (t == nt - 2);
;             const char* a1 = cA + (size_t)(t + 1) * kstepA;
;             const char* a2 = last ? nA : cA + (size_t)(t + 2) * kstepA; const char* b2 = last ? nB : cB + (size_t)(t + 2) * kstepB;
;             const char* a3 = a2 + kstepA; const char* b3 = b2 + kstepB;
;             if (last && has_next) S.a_ready(nxt);
;             if constexpr (SP2) {
;             PG8_LDB(B0, 0, 0); PG8_LDB(B1, 0, 1); PG8_SCHED; PG8_LDA(At, 0, 0); PG8_STAGE(PG8_SA(1, 1), a1 + hstepA, voffA);
;             PG8_WAIT_V(8); PG8_WAIT_L(0); PG8_BAR; PG8_MMA(0, 0, At, B0); PG8_MMA(0, 1, At, B1); PG8_BAR; PG8_SCHED;
;     ...
;         if constexpr (ALIGN_EPI) { if (wr == 1) PG8_BAR; }
.Lyh1163_1162:
	s_ashr_i32 s21, s20, 31
	s_lshl_b64 s[22:23], s[20:21], 18
	s_add_u32 s22, s33, s22
	s_addc_u32 s23, s36, s23
	s_and_b64 s[24:25], s[6:7], exec
	s_cselect_b32 s21, s23, s31
	s_cselect_b32 s29, s22, s30
	s_ashr_i32 s19, s18, 31
	s_lshl_b64 s[24:25], s[18:19], 18
	s_add_u32 s24, s37, s24
	s_addc_u32 s25, s44, s25
	s_and_b64 s[34:35], s[6:7], exec
	s_cselect_b32 s19, s25, s1
	s_cselect_b32 s61, s24, s0
	s_add_u32 s83, s0, 0x10000
	s_addc_u32 s84, s1, 0
	s_add_u32 s0, s30, 0x20080
	v_mov_b32_e32 v2, 0
	s_addc_u32 s1, s31, 0
	s_mov_b32 s86, -2
	v_pk_mov_b32 v[2:3], 0, 0
	s_barrier
	s_add_u32 s30, s0, 0xfffe0080
	s_addc_u32 s31, s1, -1
	s_add_i32 s52, 0, 0x10000
	s_cmp_eq_u32 s86, 4
	s_cselect_b32 s35, s21, s31
	s_cselect_b32 s34, s29, s30
	s_cselect_b32 s31, s19, s84
	s_cselect_b32 s30, s61, s83
	s_add_i32 s75, 0, 0x14000
	v_add_u32_e32 v142, s52, v223
	v_add_u32_e32 v158, s75, v223
	ds_read_b128 v[130:133], v142
	ds_read_b128 v[134:137], v142 offset:1024
	ds_read_b128 v[138:141], v142 offset:2048
	ds_read_b128 v[142:145], v142 offset:3072
	ds_read_b128 v[146:149], v158
	ds_read_b128 v[150:153], v158 offset:1024
	ds_read_b128 v[154:157], v158 offset:2048
	ds_read_b128 v[158:161], v158 offset:3072
	v_lshl_add_u64 v[188:189], s[0:1], 0, v[202:203]
	s_add_i32 m0, s27, 0xc000
	ds_read_b128 v[162:165], v225
	ds_read_b128 v[166:169], v225 offset:1024
	ds_read_b128 v[170:173], v225 offset:2048
	ds_read_b128 v[174:177], v225 offset:3072
	ds_read_b128 v[178:181], v225 offset:4096
	ds_read_b128 v[182:185], v225 offset:5120
	ds_read_b128 v[206:209], v225 offset:6144
	ds_read_b128 v[210:213], v225 offset:7168
	global_load_lds_dwordx4 v[188:189], off
	v_lshl_add_u64 v[188:189], s[0:1], 0, v[204:205]
	s_add_i32 m0, s27, 0xe000
	s_nop 0
	global_load_lds_dwordx4 v[188:189], off
	s_waitcnt vmcnt(8)
	s_waitcnt lgkmcnt(0)
	s_barrier
	s_branch .Lpeel_1163

;     __device__ __forceinline__ bool next(int i, Unit& u) const {
;         const long L = (long)i * G + c; if (L >= total) return false;
;         if (nM1 == 144 && nN1 == 8 && nM2 == 0 && G == 256) {
;             const int xcd = c & 7, o = c >> 3;
;             const int grp = (i < 4) ? xcd * 4 + i : 32 + (xcd >> 1), idx = (i < 4) ? o : (xcd & 1) * 16 + o;
;             u.pm = grp * 4 + (idx & 3); u.pn = idx >> 2; return true; }
;         int w = (int)L; { const int q = total / NXCD, r = total % NXCD, xcd = w % NXCD, off = w / NXCD; w = (xcd < r ? xcd * (q + 1) : r * (q + 1) + (xcd - r) * q) + off; }
;         int nM = nM1, nN = nN1; const bool second = w >= n1; if (second) { w -= n1; nM = nM2; nN = nN2; }
;         const int wgm = 4;
;         const int nig = wgm * nN, gid = w / nig, fm = gid * wgm, gsz = (nM - fm) < wgm ? (nM - fm) : wgm;
;         int pm = fm + ((w % nig) % gsz), pn = (w % nig) / gsz;
;         if (second) { pm += pm2; pn = pn < split ? a0 + pn : a1 + pn; }
;         u.pm = pm; u.pn = pn; return true;
; template <class Epi, class Sched, bool ALIGN_EPI = false, bool SP2 = false, bool ABLK = false, bool BBLK = false>
; __device__ __forceinline__ void gemm_phase(PG8_LAS unsigned char* lds, const Gemm g, const Sched& S, const Epi& E) {
;     ...
;         const bool has_next = S.next(ui + 1, nxt);
;         const char* nA = has_next ? (const char*)g.A + (size_t)nxt.pm * tstepA : cA; const char* nB = has_next ? (const char*)g.Bt + (size_t)nxt.pn * tstepB : cB;
.LBB0_1233:
	s_and_b64 vcc, exec, s[18:19]
	s_cbranch_vccz .Ly_1239
	s_add_i32 s3, s25, 1
	s_mul_i32 s6, s3, s44
	s_mul_hi_u32 s7, s3, s42
	s_add_i32 s7, s7, s6
	s_mul_i32 s6, s3, s42
	s_add_u32 s28, s6, s43
	s_addc_u32 s29, s7, s45
	v_mov_b64_e32 v[2:3], s[10:11]
	v_cmp_ge_i64_e32 vcc, s[28:29], v[2:3]
	v_cmp_lt_i64_e64 s[6:7], s[28:29], v[2:3]
	s_cbranch_vccnz .LBB0_1238
	s_mov_b64 s[30:31], -1
	s_and_b64 vcc, exec, s[22:23]
	s_cbranch_vccz .LBB0_1236
	s_ashr_i32 s24, s28, 31
	s_lshr_b32 s24, s24, 29
	s_add_i32 s24, s28, s24
	s_ashr_i32 s26, s24, 3
	s_and_b32 s24, s24, -8
	s_sub_i32 s24, s28, s24
	s_lshr_b32 s27, s24, 31
	v_readlane_b32 s28, v254, 32
	s_or_b32 s27, s28, s27
	s_mul_i32 s24, s27, s24
	s_add_i32 s24, s24, s26
	s_cmp_lt_i32 s24, s10
	s_cselect_b32 s26, 32, 4
	v_cvt_f32_ubyte0_e32 v2, s26
	v_rcp_iflag_f32_e32 v2, v2
	s_cselect_b32 s27, 0, s10
	s_cselect_b32 s28, s28, 0
	s_sub_i32 s30, 0, s26
	v_mul_f32_e32 v2, 0x4f7ffffe, v2
	v_cvt_u32_f32_e32 v2, v2
	s_sub_i32 s24, s24, s27
	s_abs_i32 s29, s24
	s_ashr_i32 s27, s24, 31
	v_readfirstlane_b32 s31, v2
	s_mul_i32 s30, s30, s31
	s_mul_hi_u32 s30, s31, s30
	s_add_i32 s31, s31, s30
	s_mul_hi_u32 s30, s29, s31
	s_mul_i32 s31, s30, s26
	s_sub_i32 s29, s29, s31
	s_add_i32 s31, s30, 1
	s_sub_i32 s35, s29, s26
	s_cmp_ge_u32 s29, s26
	s_cselect_b32 s30, s31, s30
	s_cselect_b32 s29, s35, s29
	s_add_i32 s31, s30, 1
	s_cmp_ge_u32 s29, s26
	s_cselect_b32 s29, s31, s30
	s_xor_b32 s29, s29, s27
	s_sub_i32 s27, s29, s27
	s_lshl_b32 s29, s27, 2
	s_sub_i32 s28, s28, s29
	s_min_i32 s28, s28, 4
	s_abs_i32 s30, s28
	v_cvt_f32_u32_e32 v2, s30
	s_sub_i32 s31, 0, s30
	s_mul_i32 s27, s27, s26
	s_sub_i32 s26, s24, s27
	v_rcp_iflag_f32_e32 v2, v2
	s_abs_i32 s24, s26
	s_xor_b32 s27, s26, s28
	s_ashr_i32 s27, s27, 31
	v_mul_f32_e32 v2, 0x4f7ffffe, v2
	v_cvt_u32_f32_e32 v2, v2
	s_nop 0
	v_readfirstlane_b32 s35, v2
	s_mul_i32 s31, s31, s35
	s_mul_hi_u32 s31, s35, s31
	s_add_i32 s35, s35, s31
	s_mul_hi_u32 s31, s24, s35
	s_mul_i32 s35, s31, s30
	s_sub_i32 s24, s24, s35
	s_add_i32 s35, s31, 1
	s_sub_i32 s37, s24, s30
	s_cmp_ge_u32 s24, s30
	s_cselect_b32 s31, s35, s31
	s_cselect_b32 s24, s37, s24
	s_add_i32 s35, s31, 1
	s_cmp_ge_u32 s24, s30
	s_cselect_b32 s24, s35, s31
	s_xor_b32 s24, s24, s27
	s_sub_i32 s24, s24, s27
	s_mul_i32 s27, s24, s28
	s_sub_i32 s26, s26, s27
	s_add_i32 s26, s26, s29
	s_mov_b64 s[30:31], 0

; #define PG8_BAR __builtin_amdgcn_s_barrier()
;     __device__ __forceinline__ bool next(int i, Unit& u) const {
;         const long L = (long)i * G + c; if (L >= total) return false;
;         if (nM1 == 144 && nN1 == 8 && nM2 == 0 && G == 256) {
;             const int xcd = c & 7, o = c >> 3;
;             const int grp = (i < 4) ? xcd * 4 + i : 32 + (xcd >> 1), idx = (i < 4) ? o : (xcd & 1) * 16 + o;
;             u.pm = grp * 4 + (idx & 3); u.pn = idx >> 2; return true; }
;         int w = (int)L; { const int q = total / NXCD, r = total % NXCD, xcd = w % NXCD, off = w / NXCD; w = (xcd < r ? xcd * (q + 1) : r * (q + 1) + (xcd - r) * q) + off; }
;         int nM = nM1, nN = nN1; const bool second = w >= n1; if (second) { w -= n1; nM = nM2; nN = nN2; }
;         const int wgm = 4;
;         const int nig = wgm * nN, gid = w / nig, fm = gid * wgm, gsz = (nM - fm) < wgm ? (nM - fm) : wgm;
;         int pm = fm + ((w % nig) % gsz), pn = (w % nig) / gsz;
;         if (second) { pm += pm2; pn = pn < split ? a0 + pn : a1 + pn; }
;         u.pm = pm; u.pn = pn; return true;
; template <class Epi, class Sched, bool ALIGN_EPI = false, bool SP2 = false, bool ABLK = false, bool BBLK = false>
; __device__ __forceinline__ void gemm_phase(PG8_LAS unsigned char* lds, const Gemm g, const Sched& S, const Epi& E) {
;     ...
; #pragma unroll
;         for (int a = 0; a < 2; ++a)
; #pragma unroll
;             for (int b = 0; b < 2; ++b)
; #pragma unroll
;                 for (int m = 0; m < 4; ++m)
; #pragma unroll
;                     for (int n = 0; n < 2; ++n) acc[a][b][m][n] = (f32x4){0.f, 0.f, 0.f, 0.f};
;         cur = nxt; cA = nA; cB = nB; ++ui;
;         if constexpr (ALIGN_EPI) { if (wr == 1) PG8_BAR; }
.Ly_1239:
	v_pk_mov_b32 v[2:3], 0, 0
	v_pk_mov_b32 v[4:5], 0, 0
	v_pk_mov_b32 v[6:7], 0, 0
	v_pk_mov_b32 v[8:9], 0, 0
	v_pk_mov_b32 v[10:11], 0, 0
	v_pk_mov_b32 v[12:13], 0, 0
	v_pk_mov_b32 v[14:15], 0, 0
	v_pk_mov_b32 v[16:17], 0, 0
	v_pk_mov_b32 v[18:19], 0, 0
	v_pk_mov_b32 v[20:21], 0, 0
	v_pk_mov_b32 v[22:23], 0, 0
	v_pk_mov_b32 v[24:25], 0, 0
	v_pk_mov_b32 v[26:27], 0, 0
	v_pk_mov_b32 v[28:29], 0, 0
	v_pk_mov_b32 v[30:31], 0, 0
	v_pk_mov_b32 v[32:33], 0, 0
	v_pk_mov_b32 v[34:35], 0, 0
	v_pk_mov_b32 v[36:37], 0, 0
	v_pk_mov_b32 v[38:39], 0, 0
	v_pk_mov_b32 v[40:41], 0, 0
	v_pk_mov_b32 v[42:43], 0, 0
	v_pk_mov_b32 v[44:45], 0, 0
	v_pk_mov_b32 v[46:47], 0, 0
	v_pk_mov_b32 v[48:49], 0, 0
	v_pk_mov_b32 v[50:51], 0, 0
	v_pk_mov_b32 v[52:53], 0, 0
	v_pk_mov_b32 v[54:55], 0, 0
	v_pk_mov_b32 v[56:57], 0, 0
	v_pk_mov_b32 v[58:59], 0, 0
	v_pk_mov_b32 v[60:61], 0, 0
	v_pk_mov_b32 v[62:63], 0, 0
	v_pk_mov_b32 v[64:65], 0, 0
	v_pk_mov_b32 v[66:67], 0, 0
	v_pk_mov_b32 v[68:69], 0, 0
	v_pk_mov_b32 v[70:71], 0, 0
	v_pk_mov_b32 v[72:73], 0, 0
	v_pk_mov_b32 v[74:75], 0, 0
	v_pk_mov_b32 v[76:77], 0, 0
	v_pk_mov_b32 v[78:79], 0, 0
	v_pk_mov_b32 v[80:81], 0, 0
	v_pk_mov_b32 v[82:83], 0, 0
	v_pk_mov_b32 v[84:85], 0, 0
	v_pk_mov_b32 v[86:87], 0, 0
	v_pk_mov_b32 v[88:89], 0, 0
	v_pk_mov_b32 v[90:91], 0, 0
	v_pk_mov_b32 v[92:93], 0, 0
	v_pk_mov_b32 v[94:95], 0, 0
	v_pk_mov_b32 v[96:97], 0, 0
	v_pk_mov_b32 v[98:99], 0, 0
	v_pk_mov_b32 v[100:101], 0, 0
	v_pk_mov_b32 v[102:103], 0, 0
	v_pk_mov_b32 v[104:105], 0, 0
	v_pk_mov_b32 v[106:107], 0, 0
	v_pk_mov_b32 v[108:109], 0, 0
	v_pk_mov_b32 v[110:111], 0, 0
	v_pk_mov_b32 v[112:113], 0, 0
	v_pk_mov_b32 v[114:115], 0, 0
	v_pk_mov_b32 v[116:117], 0, 0
	v_pk_mov_b32 v[118:119], 0, 0
	v_pk_mov_b32 v[120:121], 0, 0
	v_pk_mov_b32 v[130:131], 0, 0
	v_pk_mov_b32 v[132:133], 0, 0
	v_pk_mov_b32 v[134:135], 0, 0
	v_pk_mov_b32 v[136:137], 0, 0
	s_add_i32 s3, s25, 1
	s_mul_i32 s6, s3, s44
	s_mul_hi_u32 s7, s3, s42
	s_add_i32 s7, s7, s6
	s_mul_i32 s6, s3, s42
	s_add_u32 s28, s6, s43
	s_addc_u32 s29, s7, s45
	v_mov_b64_e32 v[2:3], s[10:11]
	v_cmp_ge_i64_e32 vcc, s[28:29], v[2:3]
	v_cmp_lt_i64_e64 s[6:7], s[28:29], v[2:3]
	s_cbranch_vccnz .Lyh1239_1238
	s_mov_b64 s[30:31], -1
	s_and_b64 vcc, exec, s[22:23]
	s_cbranch_vccz .Lyh1239_1236
	s_ashr_i32 s24, s28, 31
	s_lshr_b32 s24, s24, 29
	s_add_i32 s24, s28, s24
	s_ashr_i32 s26, s24, 3
	s_and_b32 s24, s24, -8
	s_sub_i32 s24, s28, s24
	s_lshr_b32 s27, s24, 31
	v_readlane_b32 s28, v254, 32
	s_or_b32 s27, s28, s27
	s_mul_i32 s24, s27, s24
	s_add_i32 s24, s24, s26
	s_cmp_lt_i32 s24, s10
	s_cselect_b32 s26, 32, 4
	v_cvt_f32_ubyte0_e32 v2, s26
	v_rcp_iflag_f32_e32 v2, v2
	s_cselect_b32 s27, 0, s10
	s_cselect_b32 s28, s28, 0
	s_sub_i32 s30, 0, s26
	v_mul_f32_e32 v2, 0x4f7ffffe, v2
	v_cvt_u32_f32_e32 v2, v2
	s_sub_i32 s24, s24, s27
	s_abs_i32 s29, s24
	s_ashr_i32 s27, s24, 31
	v_readfirstlane_b32 s31, v2
	s_mul_i32 s30, s30, s31
	s_mul_hi_u32 s30, s31, s30
	s_add_i32 s31, s31, s30
	s_mul_hi_u32 s30, s29, s31
	s_mul_i32 s31, s30, s26
	s_sub_i32 s29, s29, s31
	s_add_i32 s31, s30, 1
	s_sub_i32 s35, s29, s26
	s_cmp_ge_u32 s29, s26
	s_cselect_b32 s30, s31, s30
	s_cselect_b32 s29, s35, s29
	s_add_i32 s31, s30, 1
	s_cmp_ge_u32 s29, s26
	s_cselect_b32 s29, s31, s30
	s_xor_b32 s29, s29, s27
	s_sub_i32 s27, s29, s27
	s_lshl_b32 s29, s27, 2
	s_sub_i32 s28, s28, s29
	s_min_i32 s28, s28, 4
	s_abs_i32 s30, s28
	v_cvt_f32_u32_e32 v2, s30
	s_sub_i32 s31, 0, s30
	s_mul_i32 s27, s27, s26
	s_sub_i32 s26, s24, s27
	v_rcp_iflag_f32_e32 v2, v2
	s_abs_i32 s24, s26
	s_xor_b32 s27, s26, s28
	s_ashr_i32 s27, s27, 31
	v_mul_f32_e32 v2, 0x4f7ffffe, v2
	v_cvt_u32_f32_e32 v2, v2
	s_nop 0
	v_readfirstlane_b32 s35, v2
	s_mul_i32 s31, s31, s35
	s_mul_hi_u32 s31, s35, s31
	s_add_i32 s35, s35, s31
	s_mul_hi_u32 s31, s24, s35
	s_mul_i32 s35, s31, s30
	s_sub_i32 s24, s24, s35
	s_add_i32 s35, s31, 1
	s_sub_i32 s37, s24, s30
	s_cmp_ge_u32 s24, s30
	s_cselect_b32 s31, s35, s31
	s_cselect_b32 s24, s37, s24
	s_add_i32 s35, s31, 1
	s_cmp_ge_u32 s24, s30
	s_cselect_b32 s24, s35, s31
	s_xor_b32 s24, s24, s27
	s_sub_i32 s24, s24, s27
	s_mul_i32 s27, s24, s28
	s_sub_i32 s26, s26, s27
	s_add_i32 s26, s26, s29
	s_mov_b64 s[30:31], 0

; #define PG8_STAGE(bufoff, gbase, voff) do { _Pragma("unroll") for (int _i = 0; _i < 2; ++_i) \
;         __builtin_amdgcn_global_load_lds((const unsigned*)((const char*)(gbase) + (voff)[_i]), (PG8_LAS unsigned*)(lds + (bufoff) + ldsw + _i * 8192), 16, 0, 0); } while (0)
; #define PG8_LDA(dst, b, h) do { _Pragma("unroll") for (int m = 0; m < 4; ++m) _Pragma("unroll") for (int k = 0; k < 2; ++k) dst[m][k] = *(const PG8_LAS bf16x8*)(lds + PG8_SA(b, h) + aoff + m * 2048 + k * 1024); } while (0)
; #define PG8_LDB(dst, b, h) do { _Pragma("unroll") for (int n = 0; n < 2; ++n) _Pragma("unroll") for (int k = 0; k < 2; ++k) dst[n][k] = *(const PG8_LAS bf16x8*)(lds + PG8_SB(b, h) + boff + n * 2048 + k * 1024); } while (0)
; #define PG8_MMA(ai, bj, At, Bt) do { __builtin_amdgcn_s_setprio(1); _Pragma("unroll") for (int m = 0; m < 4; ++m) _Pragma("unroll") for (int n = 0; n < 2; ++n) _Pragma("unroll") for (int k = 0; k < 2; ++k) \
;         acc[ai][bj][m][n] = __builtin_amdgcn_mfma_f32_16x16x32_bf16(Bt[n][k], At[m][k], acc[ai][bj][m][n], 0, 0, 0); __builtin_amdgcn_s_setprio(0); } while (0)
; #define PG8_WAIT_V(n) asm volatile("s_waitcnt vmcnt(" #n ")" ::: "memory")
; template <class Epi, class Sched, bool ALIGN_EPI = false, bool SP2 = false, bool ABLK = false, bool BBLK = false>
; __device__ __forceinline__ void gemm_phase(PG8_LAS unsigned char* lds, const Gemm g, const Sched& S, const Epi& E) {
;     ...
;     for (;;) {
;         const bool has_next = S.next(ui + 1, nxt);
;         const char* nA = has_next ? (const char*)g.A + (size_t)nxt.pm * tstepA : cA; const char* nB = has_next ? (const char*)g.Bt + (size_t)nxt.pn * tstepB : cB;
;         for (int t = 0; t < nt; t += 2) {
;             const bool last = (t == nt - 2);
;             const char* a1 = cA + (size_t)(t + 1) * kstepA;
;             const char* a2 = last ? nA : cA + (size_t)(t + 2) * kstepA; const char* b2 = last ? nB : cB + (size_t)(t + 2) * kstepB;
;             const char* a3 = a2 + kstepA; const char* b3 = b2 + kstepB;
;             if (last && has_next) S.a_ready(nxt);
;             if constexpr (SP2) {
;             PG8_LDB(B0, 0, 0); PG8_LDB(B1, 0, 1); PG8_SCHED; PG8_LDA(At, 0, 0); PG8_STAGE(PG8_SA(1, 1), a1 + hstepA, voffA);
;             PG8_WAIT_V(8); PG8_WAIT_L(0); PG8_BAR; PG8_MMA(0, 0, At, B0); PG8_MMA(0, 1, At, B1); PG8_BAR; PG8_SCHED;
;     ...
;         if constexpr (ALIGN_EPI) { if (wr == 1) PG8_BAR; }
.Lyh1239_1238:
	s_ashr_i32 s27, s26, 31
	s_lshl_b64 s[28:29], s[26:27], 20
	s_add_u32 s28, s50, s28
	s_addc_u32 s29, s51, s29
	s_and_b64 s[30:31], s[6:7], exec
	s_cselect_b32 s27, s29, s9
	s_cselect_b32 s35, s28, s8
	s_ashr_i32 s25, s24, 31
	s_lshl_b64 s[30:31], s[24:25], 20
	s_add_u32 s30, s53, s30
	s_addc_u32 s31, s56, s31
	s_and_b64 s[40:41], s[6:7], exec
	s_cselect_b32 s25, s31, s1
	s_cselect_b32 s37, s30, s0
	s_add_u32 s60, s0, 0x10000
	s_addc_u32 s61, s1, 0
	s_add_u32 s0, s8, 0x80080
	v_mov_b32_e32 v38, 0
	s_addc_u32 s1, s9, 0
	s_mov_b32 s92, -2
	v_pk_mov_b32 v[2:3], 0, 0
	v_pk_mov_b32 v[38:39], 0, 0
	s_barrier
	s_add_u32 s8, s0, 0xfff80080
	s_addc_u32 s9, s1, -1
	s_add_i32 s52, 0, 0x10000
	s_cmp_eq_u32 s92, 28
	s_cselect_b32 s41, s27, s9
	s_cselect_b32 s40, s35, s8
	s_cselect_b32 s9, s25, s61
	s_cselect_b32 s8, s37, s60
	s_add_i32 s75, 0, 0x14000
	v_add_u32_e32 v142, s52, v206
	v_add_u32_e32 v158, s75, v206
	ds_read_b128 v[122:125], v142
	ds_read_b128 v[126:129], v142 offset:1024
	ds_read_b128 v[138:141], v142 offset:2048
	ds_read_b128 v[142:145], v142 offset:3072
	ds_read_b128 v[146:149], v158
	ds_read_b128 v[150:153], v158 offset:1024
	ds_read_b128 v[154:157], v158 offset:2048
	ds_read_b128 v[158:161], v158 offset:3072
	v_lshl_add_u64 v[188:189], s[0:1], 0, v[184:185]
	s_add_i32 m0, s47, 0xc000
	ds_read_b128 v[162:165], v207
	ds_read_b128 v[166:169], v207 offset:1024
	ds_read_b128 v[170:173], v207 offset:2048
	ds_read_b128 v[174:177], v207 offset:3072
	ds_read_b128 v[198:201], v207 offset:4096
	ds_read_b128 v[208:211], v207 offset:5120
	ds_read_b128 v[212:215], v207 offset:6144
	ds_read_b128 v[216:219], v207 offset:7168
	global_load_lds_dwordx4 v[188:189], off
	v_lshl_add_u64 v[188:189], s[0:1], 0, v[196:197]
	s_add_i32 m0, s47, 0xe000
	s_nop 0
	global_load_lds_dwordx4 v[188:189], off
	s_waitcnt vmcnt(8)
	s_waitcnt lgkmcnt(0)
	s_barrier
	s_branch .Lpeel_1239

;     __device__ __forceinline__ bool next(int i, Unit& u) const {
;         const long L = (long)i * G + c; if (L >= total) return false;
;         if (nM1 == 144 && nN1 == 8 && nM2 == 0 && G == 256) {
;             const int xcd = c & 7, o = c >> 3;
;             const int grp = (i < 4) ? xcd * 4 + i : 32 + (xcd >> 1), idx = (i < 4) ? o : (xcd & 1) * 16 + o;
;             u.pm = grp * 4 + (idx & 3); u.pn = idx >> 2; return true; }
;         int w = (int)L; { const int q = total / NXCD, r = total % NXCD, xcd = w % NXCD, off = w / NXCD; w = (xcd < r ? xcd * (q + 1) : r * (q + 1) + (xcd - r) * q) + off; }
;         int nM = nM1, nN = nN1; const bool second = w >= n1; if (second) { w -= n1; nM = nM2; nN = nN2; }
;         const int wgm = 4;
;         const int nig = wgm * nN, gid = w / nig, fm = gid * wgm, gsz = (nM - fm) < wgm ? (nM - fm) : wgm;
;         int pm = fm + ((w % nig) % gsz), pn = (w % nig) / gsz;
;         if (second) { pm += pm2; pn = pn < split ? a0 + pn : a1 + pn; }
;         u.pm = pm; u.pn = pn; return true;
; template <class Epi, class Sched, bool ALIGN_EPI = false, bool SP2 = false, bool ABLK = false, bool BBLK = false>
; __device__ __forceinline__ void gemm_phase(PG8_LAS unsigned char* lds, const Gemm g, const Sched& S, const Epi& E) {
;     ...
;         const bool has_next = S.next(ui + 1, nxt);
;         const char* nA = has_next ? (const char*)g.A + (size_t)nxt.pm * tstepA : cA; const char* nB = has_next ? (const char*)g.Bt + (size_t)nxt.pn * tstepB : cB;
.LBB0_1337:
	s_and_b64 vcc, exec, s[12:13]
	s_cbranch_vccz .Ly_1340
	s_add_i32 s68, s68, 1
	s_mul_i32 s1, s68, s65
	s_mul_hi_u32 s6, s68, s33
	s_add_i32 s6, s6, s1
	s_mul_i32 s1, s68, s33
	s_add_u32 s20, s1, s36
	s_addc_u32 s21, s6, s45
	v_mov_b64_e32 v[2:3], s[2:3]
	v_cmp_ge_i64_e32 vcc, s[20:21], v[2:3]
	v_cmp_lt_i64_e64 s[6:7], s[20:21], v[2:3]
	s_cbranch_vccnz .LBB0_1339
	s_ashr_i32 s1, s20, 31
	s_lshr_b32 s1, s1, 29
	s_add_i32 s1, s20, s1
	s_ashr_i32 s14, s1, 3
	s_and_b32 s1, s1, -8
	s_sub_i32 s1, s20, s1
	s_lshr_b32 s15, s1, 31
	s_or_b32 s15, s37, s15
	s_mul_i32 s1, s15, s1
	s_add_i32 s1, s1, s14
	s_cmp_lt_i32 s1, s2
	s_cselect_b32 s14, 0xb0, 4
	v_cvt_f32_ubyte0_e32 v2, s14
	v_rcp_iflag_f32_e32 v2, v2
	v_readlane_b32 s18, v254, 32
	s_cselect_b32 s15, 0, s2
	s_cselect_b32 s18, s18, 0
	v_mul_f32_e32 v2, 0x4f7ffffe, v2
	v_cvt_u32_f32_e32 v2, v2
	s_sub_i32 s20, 0, s14
	s_sub_i32 s1, s1, s15
	s_abs_i32 s19, s1
	v_readfirstlane_b32 s21, v2
	s_mul_i32 s20, s20, s21
	s_mul_hi_u32 s20, s21, s20
	s_add_i32 s21, s21, s20
	s_mul_hi_u32 s20, s19, s21
	s_mul_i32 s21, s20, s14
	s_sub_i32 s19, s19, s21
	s_ashr_i32 s15, s1, 31
	s_add_i32 s21, s20, 1
	s_sub_i32 s22, s19, s14
	s_cmp_ge_u32 s19, s14
	s_cselect_b32 s20, s21, s20
	s_cselect_b32 s19, s22, s19
	s_add_i32 s21, s20, 1
	s_cmp_ge_u32 s19, s14
	s_cselect_b32 s19, s21, s20
	s_xor_b32 s19, s19, s15
	s_sub_i32 s15, s19, s15
	s_lshl_b32 s19, s15, 2
	s_sub_i32 s18, s18, s19
	s_min_i32 s18, s18, 4
	s_abs_i32 s20, s18
	v_cvt_f32_u32_e32 v2, s20
	s_sub_i32 s21, 0, s20
	s_mul_i32 s15, s15, s14
	s_sub_i32 s1, s1, s15
	v_rcp_iflag_f32_e32 v2, v2
	s_abs_i32 s14, s1
	s_xor_b32 s15, s1, s18
	s_ashr_i32 s15, s15, 31
	v_mul_f32_e32 v2, 0x4f7ffffe, v2
	v_cvt_u32_f32_e32 v2, v2
	s_nop 0
	v_readfirstlane_b32 s22, v2
	s_mul_i32 s21, s21, s22
	s_mul_hi_u32 s21, s22, s21
	s_add_i32 s22, s22, s21
	s_mul_hi_u32 s21, s14, s22
	s_mul_i32 s22, s21, s20
	s_sub_i32 s14, s14, s22
	s_add_i32 s22, s21, 1
	s_sub_i32 s23, s14, s20
	s_cmp_ge_u32 s14, s20
	s_cselect_b32 s21, s22, s21
	s_cselect_b32 s14, s23, s14
	s_add_i32 s22, s21, 1
	s_cmp_ge_u32 s14, s20
	s_cselect_b32 s14, s22, s21
	s_xor_b32 s14, s14, s15
	s_sub_i32 s14, s14, s15
	s_mul_i32 s15, s14, s18
	s_sub_i32 s1, s1, s15
	s_add_i32 s18, s1, s19

;     __device__ __forceinline__ bool next(int i, Unit& u) const {
;         const long L = (long)i * G + c; if (L >= total) return false;
;         if (nM1 == 144 && nN1 == 8 && nM2 == 0 && G == 256) {
;             const int xcd = c & 7, o = c >> 3;
;             const int grp = (i < 4) ? xcd * 4 + i : 32 + (xcd >> 1), idx = (i < 4) ? o : (xcd & 1) * 16 + o;
;             u.pm = grp * 4 + (idx & 3); u.pn = idx >> 2; return true; }
;         int w = (int)L; { const int q = total / NXCD, r = total % NXCD, xcd = w % NXCD, off = w / NXCD; w = (xcd < r ? xcd * (q + 1) : r * (q + 1) + (xcd - r) * q) + off; }
;         int nM = nM1, nN = nN1; const bool second = w >= n1; if (second) { w -= n1; nM = nM2; nN = nN2; }
;         const int wgm = 4;
;         const int nig = wgm * nN, gid = w / nig, fm = gid * wgm, gsz = (nM - fm) < wgm ? (nM - fm) : wgm;
;         int pm = fm + ((w % nig) % gsz), pn = (w % nig) / gsz;
;         if (second) { pm += pm2; pn = pn < split ? a0 + pn : a1 + pn; }
;         u.pm = pm; u.pn = pn; return true;
; template <class Epi, class Sched, bool ALIGN_EPI = false, bool SP2 = false, bool ABLK = false, bool BBLK = false>
; __device__ __forceinline__ void gemm_phase(PG8_LAS unsigned char* lds, const Gemm g, const Sched& S, const Epi& E) {
;     ...
;     for (;;) {
;         const bool has_next = S.next(ui + 1, nxt);
;         const char* nA = has_next ? (const char*)g.A + (size_t)nxt.pm * tstepA : cA; const char* nB = has_next ? (const char*)g.Bt + (size_t)nxt.pn * tstepB : cB;
;         for (int t = 0; t < nt; t += 2) {
;             const bool last = (t == nt - 2);
;             const char* a1 = cA + (size_t)(t + 1) * kstepA;
;             const char* a2 = last ? nA : cA + (size_t)(t + 2) * kstepA; const char* b2 = last ? nB : cB + (size_t)(t + 2) * kstepB;
;             const char* a3 = a2 + kstepA; const char* b3 = b2 + kstepB;
;             if (last && has_next) S.a_ready(nxt);
;             if constexpr (SP2) {
;     ...
; #pragma unroll
;         for (int a = 0; a < 2; ++a)
; #pragma unroll
;             for (int b = 0; b < 2; ++b)
; #pragma unroll
;                 for (int m = 0; m < 4; ++m)
; #pragma unroll
;                     for (int n = 0; n < 2; ++n) acc[a][b][m][n] = (f32x4){0.f, 0.f, 0.f, 0.f};
;         cur = nxt; cA = nA; cB = nB; ++ui;
;         if constexpr (ALIGN_EPI) { if (wr == 1) PG8_BAR; }
.Ly_1340:
	v_pk_mov_b32 v[2:3], 0, 0
	v_pk_mov_b32 v[4:5], 0, 0
	v_pk_mov_b32 v[6:7], 0, 0
	v_pk_mov_b32 v[8:9], 0, 0
	v_pk_mov_b32 v[10:11], 0, 0
	v_pk_mov_b32 v[12:13], 0, 0
	v_pk_mov_b32 v[14:15], 0, 0
	v_pk_mov_b32 v[16:17], 0, 0
	v_pk_mov_b32 v[18:19], 0, 0
	v_pk_mov_b32 v[20:21], 0, 0
	v_pk_mov_b32 v[22:23], 0, 0
	v_pk_mov_b32 v[24:25], 0, 0
	v_pk_mov_b32 v[26:27], 0, 0
	v_pk_mov_b32 v[28:29], 0, 0
	v_pk_mov_b32 v[30:31], 0, 0
	v_pk_mov_b32 v[32:33], 0, 0
	v_pk_mov_b32 v[34:35], 0, 0
	v_pk_mov_b32 v[36:37], 0, 0
	v_pk_mov_b32 v[38:39], 0, 0
	v_pk_mov_b32 v[40:41], 0, 0
	v_pk_mov_b32 v[42:43], 0, 0
	v_pk_mov_b32 v[44:45], 0, 0
	v_pk_mov_b32 v[46:47], 0, 0
	v_pk_mov_b32 v[48:49], 0, 0
	v_pk_mov_b32 v[50:51], 0, 0
	v_pk_mov_b32 v[52:53], 0, 0
	v_pk_mov_b32 v[54:55], 0, 0
	v_pk_mov_b32 v[56:57], 0, 0
	v_pk_mov_b32 v[58:59], 0, 0
	v_pk_mov_b32 v[60:61], 0, 0
	v_pk_mov_b32 v[62:63], 0, 0
	v_pk_mov_b32 v[64:65], 0, 0
	v_pk_mov_b32 v[66:67], 0, 0
	v_pk_mov_b32 v[68:69], 0, 0
	v_pk_mov_b32 v[70:71], 0, 0
	v_pk_mov_b32 v[72:73], 0, 0
	v_pk_mov_b32 v[74:75], 0, 0
	v_pk_mov_b32 v[76:77], 0, 0
	v_pk_mov_b32 v[78:79], 0, 0
	v_pk_mov_b32 v[80:81], 0, 0
	v_pk_mov_b32 v[82:83], 0, 0
	v_pk_mov_b32 v[84:85], 0, 0
	v_pk_mov_b32 v[86:87], 0, 0
	v_pk_mov_b32 v[88:89], 0, 0
	v_pk_mov_b32 v[90:91], 0, 0
	v_pk_mov_b32 v[92:93], 0, 0
	v_pk_mov_b32 v[94:95], 0, 0
	v_pk_mov_b32 v[96:97], 0, 0
	v_pk_mov_b32 v[98:99], 0, 0
	v_pk_mov_b32 v[100:101], 0, 0
	v_pk_mov_b32 v[102:103], 0, 0
	v_pk_mov_b32 v[104:105], 0, 0
	v_pk_mov_b32 v[106:107], 0, 0
	v_pk_mov_b32 v[108:109], 0, 0
	v_pk_mov_b32 v[110:111], 0, 0
	v_pk_mov_b32 v[112:113], 0, 0
	v_pk_mov_b32 v[114:115], 0, 0
	v_pk_mov_b32 v[116:117], 0, 0
	v_pk_mov_b32 v[118:119], 0, 0
	v_pk_mov_b32 v[120:121], 0, 0
	v_pk_mov_b32 v[122:123], 0, 0
	v_pk_mov_b32 v[124:125], 0, 0
	v_pk_mov_b32 v[126:127], 0, 0
	v_pk_mov_b32 v[128:129], 0, 0
	s_add_i32 s68, s68, 1
	s_mul_i32 s1, s68, s65
	s_mul_hi_u32 s6, s68, s33
	s_add_i32 s6, s6, s1
	s_mul_i32 s1, s68, s33
	s_add_u32 s20, s1, s36
	s_addc_u32 s21, s6, s45
	v_mov_b64_e32 v[2:3], s[2:3]
	v_cmp_ge_i64_e32 vcc, s[20:21], v[2:3]
	v_cmp_lt_i64_e64 s[6:7], s[20:21], v[2:3]
	s_cbranch_vccnz .Lyh1340_1339
	s_ashr_i32 s1, s20, 31
	s_lshr_b32 s1, s1, 29
	s_add_i32 s1, s20, s1
	s_ashr_i32 s14, s1, 3
	s_and_b32 s1, s1, -8
	s_sub_i32 s1, s20, s1
	s_lshr_b32 s15, s1, 31
	s_or_b32 s15, s37, s15
	s_mul_i32 s1, s15, s1
	s_add_i32 s1, s1, s14
	s_cmp_lt_i32 s1, s2
	s_cselect_b32 s14, 0xb0, 4
	v_cvt_f32_ubyte0_e32 v2, s14
	v_rcp_iflag_f32_e32 v2, v2
	v_readlane_b32 s18, v254, 32
	s_cselect_b32 s15, 0, s2
	s_cselect_b32 s18, s18, 0
	v_mul_f32_e32 v2, 0x4f7ffffe, v2
	v_cvt_u32_f32_e32 v2, v2
	s_sub_i32 s20, 0, s14
	s_sub_i32 s1, s1, s15
	s_abs_i32 s19, s1
	v_readfirstlane_b32 s21, v2
	s_mul_i32 s20, s20, s21
	s_mul_hi_u32 s20, s21, s20
	s_add_i32 s21, s21, s20
	s_mul_hi_u32 s20, s19, s21
	s_mul_i32 s21, s20, s14
	s_sub_i32 s19, s19, s21
	s_ashr_i32 s15, s1, 31
	s_add_i32 s21, s20, 1
	s_sub_i32 s22, s19, s14
	s_cmp_ge_u32 s19, s14
	s_cselect_b32 s20, s21, s20
	s_cselect_b32 s19, s22, s19
	s_add_i32 s21, s20, 1
	s_cmp_ge_u32 s19, s14
	s_cselect_b32 s19, s21, s20
	s_xor_b32 s19, s19, s15
	s_sub_i32 s15, s19, s15
	s_lshl_b32 s19, s15, 2
	s_sub_i32 s18, s18, s19
	s_min_i32 s18, s18, 4
	s_abs_i32 s20, s18
	v_cvt_f32_u32_e32 v2, s20
	s_sub_i32 s21, 0, s20
	s_mul_i32 s15, s15, s14
	s_sub_i32 s1, s1, s15
	v_rcp_iflag_f32_e32 v2, v2
	s_abs_i32 s14, s1
	s_xor_b32 s15, s1, s18
	s_ashr_i32 s15, s15, 31
	v_mul_f32_e32 v2, 0x4f7ffffe, v2
	v_cvt_u32_f32_e32 v2, v2
	s_nop 0
	v_readfirstlane_b32 s22, v2
	s_mul_i32 s21, s21, s22
	s_mul_hi_u32 s21, s22, s21
	s_add_i32 s22, s22, s21
	s_mul_hi_u32 s21, s14, s22
	s_mul_i32 s22, s21, s20
	s_sub_i32 s14, s14, s22
	s_add_i32 s22, s21, 1
	s_sub_i32 s23, s14, s20
	s_cmp_ge_u32 s14, s20
	s_cselect_b32 s21, s22, s21
	s_cselect_b32 s14, s23, s14
	s_add_i32 s22, s21, 1
	s_cmp_ge_u32 s14, s20
	s_cselect_b32 s14, s22, s21
	s_xor_b32 s14, s14, s15
	s_sub_i32 s14, s14, s15
	s_mul_i32 s15, s14, s18
	s_sub_i32 s1, s1, s15
	s_add_i32 s18, s1, s19
.Lyh1340_1339:
	s_ashr_i32 s19, s18, 31
	s_lshl_b64 s[20:21], s[18:19], 20
	s_add_u32 s20, s40, s20
	s_addc_u32 s21, s41, s21
	s_and_b64 s[22:23], s[6:7], exec
	s_cselect_b32 s1, s21, s27
	s_cselect_b32 s19, s20, s26
	s_ashr_i32 s15, s14, 31
	s_lshl_b64 s[22:23], s[14:15], 20
	s_add_u32 s22, s42, s22
	s_addc_u32 s23, s43, s23
	s_and_b64 s[30:31], s[6:7], exec
	s_cselect_b32 s15, s23, s29
	s_cselect_b32 s72, s22, s28
	s_add_u32 s26, s26, 0xc000
	s_addc_u32 s27, s27, 0
	s_add_u32 s73, s28, 0x10000
	v_mov_b32_e32 v2, 0
	s_addc_u32 s81, s29, 0
	s_mov_b32 s83, -2
	v_pk_mov_b32 v[2:3], 0, 0
	s_barrier
	s_add_u32 s28, s26, 0x4000
	s_addc_u32 s29, s27, 0
	s_cmp_eq_u32 s83, 28
	s_cselect_b32 s34, s19, s28
	s_cselect_b32 s35, s1, s29
	s_cselect_b32 s30, s72, s73
	s_cselect_b32 s31, s15, s81
	s_add_u32 s28, s34, 0x8000
	s_addc_u32 s29, s35, 0
	s_add_i32 s52, 0, 0x10000
	v_add_u32_e32 v142, s52, v145
	s_add_i32 s75, 0, 0x14000
	ds_read_b128 v[148:151], v142
	ds_read_b128 v[152:155], v142 offset:1024
	ds_read_b128 v[156:159], v142 offset:2048
	ds_read_b128 v[160:163], v142 offset:3072
	v_add_u32_e32 v142, s75, v145
	ds_read_b128 v[164:167], v142
	ds_read_b128 v[168:171], v142 offset:1024
	ds_read_b128 v[172:175], v142 offset:2048
	ds_read_b128 v[176:179], v142 offset:3072
	v_lshl_add_u64 v[142:143], s[26:27], 0, v[138:139]
	s_add_i32 m0, s25, 0xc000
	ds_read_b128 v[180:183], v146
	ds_read_b128 v[196:199], v146 offset:1024
	ds_read_b128 v[200:203], v146 offset:2048
	ds_read_b128 v[204:207], v146 offset:3072
	ds_read_b128 v[208:211], v146 offset:4096
	ds_read_b128 v[212:215], v146 offset:5120
	ds_read_b128 v[216:219], v146 offset:6144
	ds_read_b128 v[220:223], v146 offset:7168
	global_load_lds_dwordx4 v[142:143], off
	v_lshl_add_u64 v[142:143], s[26:27], 0, v[140:141]
	s_add_i32 m0, s25, 0xe000
	s_nop 0
	global_load_lds_dwordx4 v[142:143], off
	s_waitcnt vmcnt(8)
	s_waitcnt lgkmcnt(0)
	s_barrier
	s_branch .Lpeel_1340

;     __device__ __forceinline__ bool next(int i, Unit& u) const {
;         const long L = (long)i * G + c; if (L >= total) return false;
;         if (nM1 == 144 && nN1 == 8 && nM2 == 0 && G == 256) {
;             const int xcd = c & 7, o = c >> 3;
;             const int grp = (i < 4) ? xcd * 4 + i : 32 + (xcd >> 1), idx = (i < 4) ? o : (xcd & 1) * 16 + o;
;             u.pm = grp * 4 + (idx & 3); u.pn = idx >> 2; return true; }
;         int w = (int)L; { const int q = total / NXCD, r = total % NXCD, xcd = w % NXCD, off = w / NXCD; w = (xcd < r ? xcd * (q + 1) : r * (q + 1) + (xcd - r) * q) + off; }
;         int nM = nM1, nN = nN1; const bool second = w >= n1; if (second) { w -= n1; nM = nM2; nN = nN2; }
;         const int wgm = 4;
;         const int nig = wgm * nN, gid = w / nig, fm = gid * wgm, gsz = (nM - fm) < wgm ? (nM - fm) : wgm;
;         int pm = fm + ((w % nig) % gsz), pn = (w % nig) / gsz;
;         if (second) { pm += pm2; pn = pn < split ? a0 + pn : a1 + pn; }
;         u.pm = pm; u.pn = pn; return true;
; template <class Epi, class Sched, bool ALIGN_EPI = false, bool SP2 = false, bool ABLK = false, bool BBLK = false>
; __device__ __forceinline__ void gemm_phase(PG8_LAS unsigned char* lds, const Gemm g, const Sched& S, const Epi& E) {
;     ...
;         const bool has_next = S.next(ui + 1, nxt);
;         const char* nA = has_next ? (const char*)g.A + (size_t)nxt.pm * tstepA : cA; const char* nB = has_next ? (const char*)g.Bt + (size_t)nxt.pn * tstepB : cB;
.LBB0_1413:
	s_and_b64 vcc, exec, s[14:15]
	s_cbranch_vccz .Ly_1420
	s_add_i32 s65, s65, 1
	s_mul_i32 s6, s65, s56
	s_mul_hi_u32 s7, s65, s42
	s_add_i32 s7, s7, s6
	s_mul_i32 s6, s65, s42
	s_add_u32 s6, s6, s51
	s_addc_u32 s7, s7, s60
	v_mov_b64_e32 v[2:3], s[10:11]
	v_cmp_ge_i64_e32 vcc, s[6:7], v[2:3]
	v_cmp_lt_i64_e64 s[8:9], s[6:7], v[2:3]
	s_cbranch_vccnz .LBB0_1415
	s_ashr_i32 s7, s6, 31
	s_lshr_b32 s7, s7, 29
	s_add_i32 s7, s6, s7
	s_ashr_i32 s18, s7, 3
	s_and_b32 s7, s7, -8
	s_sub_i32 s6, s6, s7
	s_lshr_b32 s7, s6, 31
	v_readlane_b32 s19, v254, 32
	s_or_b32 s7, s19, s7
	s_mul_i32 s6, s7, s6
	s_add_i32 s6, s6, s18
	s_cmp_lt_i32 s6, s10
	s_cselect_b32 s7, 32, 4
	v_cvt_f32_ubyte0_e32 v2, s7
	v_rcp_iflag_f32_e32 v2, v2
	s_cselect_b32 s18, 0, s10
	s_cselect_b32 s19, s19, 0
	s_sub_i32 s21, 0, s7
	v_mul_f32_e32 v2, 0x4f7ffffe, v2
	v_cvt_u32_f32_e32 v2, v2
	s_sub_i32 s6, s6, s18
	s_abs_i32 s20, s6
	s_ashr_i32 s18, s6, 31
	v_readfirstlane_b32 s23, v2
	s_mul_i32 s21, s21, s23
	s_mul_hi_u32 s21, s23, s21
	s_add_i32 s23, s23, s21
	s_mul_hi_u32 s21, s20, s23
	s_mul_i32 s23, s21, s7
	s_sub_i32 s20, s20, s23
	s_add_i32 s23, s21, 1
	s_sub_i32 s25, s20, s7
	s_cmp_ge_u32 s20, s7
	s_cselect_b32 s21, s23, s21
	s_cselect_b32 s20, s25, s20
	s_add_i32 s23, s21, 1
	s_cmp_ge_u32 s20, s7
	s_cselect_b32 s20, s23, s21
	s_xor_b32 s20, s20, s18
	s_sub_i32 s18, s20, s18
	s_lshl_b32 s20, s18, 2
	s_sub_i32 s19, s19, s20
	s_min_i32 s19, s19, 4
	s_abs_i32 s21, s19
	v_cvt_f32_u32_e32 v2, s21
	s_sub_i32 s23, 0, s21
	s_mul_i32 s18, s18, s7
	s_sub_i32 s6, s6, s18
	v_rcp_iflag_f32_e32 v2, v2
	s_abs_i32 s7, s6
	s_xor_b32 s18, s6, s19
	s_ashr_i32 s18, s18, 31
	v_mul_f32_e32 v2, 0x4f7ffffe, v2
	v_cvt_u32_f32_e32 v2, v2
	s_nop 0
	v_readfirstlane_b32 s25, v2
	s_mul_i32 s23, s23, s25
	s_mul_hi_u32 s23, s25, s23
	s_add_i32 s25, s25, s23
	s_mul_hi_u32 s23, s7, s25
	s_mul_i32 s25, s23, s21
	s_sub_i32 s7, s7, s25
	s_add_i32 s25, s23, 1
	s_sub_i32 s28, s7, s21
	s_cmp_ge_u32 s7, s21
	s_cselect_b32 s23, s25, s23
	s_cselect_b32 s7, s28, s7
	s_add_i32 s25, s23, 1
	s_cmp_ge_u32 s7, s21
	s_cselect_b32 s7, s25, s23
	s_xor_b32 s7, s7, s18
	s_sub_i32 s68, s7, s18
	s_mul_i32 s7, s68, s19
	s_sub_i32 s6, s6, s7
	s_add_i32 s72, s6, s20

; #define PG8_BAR __builtin_amdgcn_s_barrier()
;     __device__ __forceinline__ bool next(int i, Unit& u) const {
;         const long L = (long)i * G + c; if (L >= total) return false;
;         if (nM1 == 144 && nN1 == 8 && nM2 == 0 && G == 256) {
;             const int xcd = c & 7, o = c >> 3;
;             const int grp = (i < 4) ? xcd * 4 + i : 32 + (xcd >> 1), idx = (i < 4) ? o : (xcd & 1) * 16 + o;
;             u.pm = grp * 4 + (idx & 3); u.pn = idx >> 2; return true; }
;         int w = (int)L; { const int q = total / NXCD, r = total % NXCD, xcd = w % NXCD, off = w / NXCD; w = (xcd < r ? xcd * (q + 1) : r * (q + 1) + (xcd - r) * q) + off; }
;         int nM = nM1, nN = nN1; const bool second = w >= n1; if (second) { w -= n1; nM = nM2; nN = nN2; }
;         const int wgm = 4;
;         const int nig = wgm * nN, gid = w / nig, fm = gid * wgm, gsz = (nM - fm) < wgm ? (nM - fm) : wgm;
;         int pm = fm + ((w % nig) % gsz), pn = (w % nig) / gsz;
;         if (second) { pm += pm2; pn = pn < split ? a0 + pn : a1 + pn; }
;         u.pm = pm; u.pn = pn; return true;
; template <class Epi, class Sched, bool ALIGN_EPI = false, bool SP2 = false, bool ABLK = false, bool BBLK = false>
; __device__ __forceinline__ void gemm_phase(PG8_LAS unsigned char* lds, const Gemm g, const Sched& S, const Epi& E) {
;     ...
; #pragma unroll
;         for (int a = 0; a < 2; ++a)
; #pragma unroll
;             for (int b = 0; b < 2; ++b)
; #pragma unroll
;                 for (int m = 0; m < 4; ++m)
; #pragma unroll
;                     for (int n = 0; n < 2; ++n) acc[a][b][m][n] = (f32x4){0.f, 0.f, 0.f, 0.f};
;         cur = nxt; cA = nA; cB = nB; ++ui;
;         if constexpr (ALIGN_EPI) { if (wr == 1) PG8_BAR; }
.Ly_1420:
	v_pk_mov_b32 v[2:3], 0, 0
	v_pk_mov_b32 v[4:5], 0, 0
	v_pk_mov_b32 v[6:7], 0, 0
	v_pk_mov_b32 v[8:9], 0, 0
	v_pk_mov_b32 v[10:11], 0, 0
	v_pk_mov_b32 v[12:13], 0, 0
	v_pk_mov_b32 v[14:15], 0, 0
	v_pk_mov_b32 v[16:17], 0, 0
	v_pk_mov_b32 v[18:19], 0, 0
	v_pk_mov_b32 v[20:21], 0, 0
	v_pk_mov_b32 v[22:23], 0, 0
	v_pk_mov_b32 v[24:25], 0, 0
	v_pk_mov_b32 v[26:27], 0, 0
	v_pk_mov_b32 v[28:29], 0, 0
	v_pk_mov_b32 v[30:31], 0, 0
	v_pk_mov_b32 v[32:33], 0, 0
	v_pk_mov_b32 v[34:35], 0, 0
	v_pk_mov_b32 v[36:37], 0, 0
	v_pk_mov_b32 v[38:39], 0, 0
	v_pk_mov_b32 v[40:41], 0, 0
	v_pk_mov_b32 v[42:43], 0, 0
	v_pk_mov_b32 v[44:45], 0, 0
	v_pk_mov_b32 v[46:47], 0, 0
	v_pk_mov_b32 v[48:49], 0, 0
	v_pk_mov_b32 v[50:51], 0, 0
	v_pk_mov_b32 v[52:53], 0, 0
	v_pk_mov_b32 v[54:55], 0, 0
	v_pk_mov_b32 v[56:57], 0, 0
	v_pk_mov_b32 v[58:59], 0, 0
	v_pk_mov_b32 v[60:61], 0, 0
	v_pk_mov_b32 v[62:63], 0, 0
	v_pk_mov_b32 v[64:65], 0, 0
	v_pk_mov_b32 v[66:67], 0, 0
	v_pk_mov_b32 v[68:69], 0, 0
	v_pk_mov_b32 v[70:71], 0, 0
	v_pk_mov_b32 v[72:73], 0, 0
	v_pk_mov_b32 v[74:75], 0, 0
	v_pk_mov_b32 v[76:77], 0, 0
	v_pk_mov_b32 v[78:79], 0, 0
	v_pk_mov_b32 v[80:81], 0, 0
	v_pk_mov_b32 v[82:83], 0, 0
	v_pk_mov_b32 v[84:85], 0, 0
	v_pk_mov_b32 v[86:87], 0, 0
	v_pk_mov_b32 v[88:89], 0, 0
	v_pk_mov_b32 v[90:91], 0, 0
	v_pk_mov_b32 v[92:93], 0, 0
	v_pk_mov_b32 v[94:95], 0, 0
	v_pk_mov_b32 v[96:97], 0, 0
	v_pk_mov_b32 v[98:99], 0, 0
	v_pk_mov_b32 v[100:101], 0, 0
	v_pk_mov_b32 v[102:103], 0, 0
	v_pk_mov_b32 v[104:105], 0, 0
	v_pk_mov_b32 v[106:107], 0, 0
	v_pk_mov_b32 v[108:109], 0, 0
	v_pk_mov_b32 v[110:111], 0, 0
	v_pk_mov_b32 v[112:113], 0, 0
	v_pk_mov_b32 v[114:115], 0, 0
	v_pk_mov_b32 v[116:117], 0, 0
	v_pk_mov_b32 v[118:119], 0, 0
	v_pk_mov_b32 v[120:121], 0, 0
	v_pk_mov_b32 v[122:123], 0, 0
	v_pk_mov_b32 v[124:125], 0, 0
	v_pk_mov_b32 v[126:127], 0, 0
	v_pk_mov_b32 v[128:129], 0, 0
	s_add_i32 s65, s65, 1
	s_mul_i32 s6, s65, s56
	s_mul_hi_u32 s7, s65, s42
	s_add_i32 s7, s7, s6
	s_mul_i32 s6, s65, s42
	s_add_u32 s6, s6, s51
	s_addc_u32 s7, s7, s60
	v_mov_b64_e32 v[2:3], s[10:11]
	v_cmp_ge_i64_e32 vcc, s[6:7], v[2:3]
	v_cmp_lt_i64_e64 s[8:9], s[6:7], v[2:3]
	s_cbranch_vccnz .Lyh1420_1415
	s_ashr_i32 s7, s6, 31
	s_lshr_b32 s7, s7, 29
	s_add_i32 s7, s6, s7
	s_ashr_i32 s18, s7, 3
	s_and_b32 s7, s7, -8
	s_sub_i32 s6, s6, s7
	s_lshr_b32 s7, s6, 31
	v_readlane_b32 s19, v254, 32
	s_or_b32 s7, s19, s7
	s_mul_i32 s6, s7, s6
	s_add_i32 s6, s6, s18
	s_cmp_lt_i32 s6, s10
	s_cselect_b32 s7, 32, 4
	v_cvt_f32_ubyte0_e32 v2, s7
	v_rcp_iflag_f32_e32 v2, v2
	s_cselect_b32 s18, 0, s10
	s_cselect_b32 s19, s19, 0
	s_sub_i32 s21, 0, s7
	v_mul_f32_e32 v2, 0x4f7ffffe, v2
	v_cvt_u32_f32_e32 v2, v2
	s_sub_i32 s6, s6, s18
	s_abs_i32 s20, s6
	s_ashr_i32 s18, s6, 31
	v_readfirstlane_b32 s23, v2
	s_mul_i32 s21, s21, s23
	s_mul_hi_u32 s21, s23, s21
	s_add_i32 s23, s23, s21
	s_mul_hi_u32 s21, s20, s23
	s_mul_i32 s23, s21, s7
	s_sub_i32 s20, s20, s23
	s_add_i32 s23, s21, 1
	s_sub_i32 s25, s20, s7
	s_cmp_ge_u32 s20, s7
	s_cselect_b32 s21, s23, s21
	s_cselect_b32 s20, s25, s20
	s_add_i32 s23, s21, 1
	s_cmp_ge_u32 s20, s7
	s_cselect_b32 s20, s23, s21
	s_xor_b32 s20, s20, s18
	s_sub_i32 s18, s20, s18
	s_lshl_b32 s20, s18, 2
	s_sub_i32 s19, s19, s20
	s_min_i32 s19, s19, 4
	s_abs_i32 s21, s19
	v_cvt_f32_u32_e32 v2, s21
	s_sub_i32 s23, 0, s21
	s_mul_i32 s18, s18, s7
	s_sub_i32 s6, s6, s18
	v_rcp_iflag_f32_e32 v2, v2
	s_abs_i32 s7, s6
	s_xor_b32 s18, s6, s19
	s_ashr_i32 s18, s18, 31
	v_mul_f32_e32 v2, 0x4f7ffffe, v2
	v_cvt_u32_f32_e32 v2, v2
	s_nop 0
	v_readfirstlane_b32 s25, v2
	s_mul_i32 s23, s23, s25
	s_mul_hi_u32 s23, s25, s23
	s_add_i32 s25, s25, s23
	s_mul_hi_u32 s23, s7, s25
	s_mul_i32 s25, s23, s21
	s_sub_i32 s7, s7, s25
	s_add_i32 s25, s23, 1
	s_sub_i32 s28, s7, s21
	s_cmp_ge_u32 s7, s21
	s_cselect_b32 s23, s25, s23
	s_cselect_b32 s7, s28, s7
	s_add_i32 s25, s23, 1
	s_cmp_ge_u32 s7, s21
	s_cselect_b32 s7, s25, s23
	s_xor_b32 s7, s7, s18
	s_sub_i32 s68, s7, s18
	s_mul_i32 s7, s68, s19
	s_sub_i32 s6, s6, s7
	s_add_i32 s72, s6, s20

; #define PG8_STAGE(bufoff, gbase, voff) do { _Pragma("unroll") for (int _i = 0; _i < 2; ++_i) \
;         __builtin_amdgcn_global_load_lds((const unsigned*)((const char*)(gbase) + (voff)[_i]), (PG8_LAS unsigned*)(lds + (bufoff) + ldsw + _i * 8192), 16, 0, 0); } while (0)
; #define PG8_LDA(dst, b, h) do { _Pragma("unroll") for (int m = 0; m < 4; ++m) _Pragma("unroll") for (int k = 0; k < 2; ++k) dst[m][k] = *(const PG8_LAS bf16x8*)(lds + PG8_SA(b, h) + aoff + m * 2048 + k * 1024); } while (0)
; #define PG8_LDB(dst, b, h) do { _Pragma("unroll") for (int n = 0; n < 2; ++n) _Pragma("unroll") for (int k = 0; k < 2; ++k) dst[n][k] = *(const PG8_LAS bf16x8*)(lds + PG8_SB(b, h) + boff + n * 2048 + k * 1024); } while (0)
; #define PG8_MMA(ai, bj, At, Bt) do { __builtin_amdgcn_s_setprio(1); _Pragma("unroll") for (int m = 0; m < 4; ++m) _Pragma("unroll") for (int n = 0; n < 2; ++n) _Pragma("unroll") for (int k = 0; k < 2; ++k) \
;         acc[ai][bj][m][n] = __builtin_amdgcn_mfma_f32_16x16x32_bf16(Bt[n][k], At[m][k], acc[ai][bj][m][n], 0, 0, 0); __builtin_amdgcn_s_setprio(0); } while (0)
; #define PG8_WAIT_V(n) asm volatile("s_waitcnt vmcnt(" #n ")" ::: "memory")
; template <class Epi, class Sched, bool ALIGN_EPI = false, bool SP2 = false, bool ABLK = false, bool BBLK = false>
; __device__ __forceinline__ void gemm_phase(PG8_LAS unsigned char* lds, const Gemm g, const Sched& S, const Epi& E) {
;     ...
;     for (;;) {
;         const bool has_next = S.next(ui + 1, nxt);
;         const char* nA = has_next ? (const char*)g.A + (size_t)nxt.pm * tstepA : cA; const char* nB = has_next ? (const char*)g.Bt + (size_t)nxt.pn * tstepB : cB;
;         for (int t = 0; t < nt; t += 2) {
;             const bool last = (t == nt - 2);
;             const char* a1 = cA + (size_t)(t + 1) * kstepA;
;             const char* a2 = last ? nA : cA + (size_t)(t + 2) * kstepA; const char* b2 = last ? nB : cB + (size_t)(t + 2) * kstepB;
;             const char* a3 = a2 + kstepA; const char* b3 = b2 + kstepB;
;             if (last && has_next) S.a_ready(nxt);
;             if constexpr (SP2) {
;             PG8_LDB(B0, 0, 0); PG8_LDB(B1, 0, 1); PG8_SCHED; PG8_LDA(At, 0, 0); PG8_STAGE(PG8_SA(1, 1), a1 + hstepA, voffA);
;             PG8_WAIT_V(8); PG8_WAIT_L(0); PG8_BAR; PG8_MMA(0, 0, At, B0); PG8_MMA(0, 1, At, B1); PG8_BAR; PG8_SCHED;
;     ...
;         if constexpr (ALIGN_EPI) { if (wr == 1) PG8_BAR; }
.Lyh1420_1419:
	s_add_u32 s0, s0, 0xc000
	s_addc_u32 s1, s1, 0
	s_add_u32 s23, s26, 0x10000
	v_mov_b32_e32 v2, 0
	s_addc_u32 s25, s27, 0
	s_mov_b32 s73, -2
	v_pk_mov_b32 v[2:3], 0, 0
	s_barrier
	s_add_u32 s8, s0, 0x4000
	s_addc_u32 s9, s1, 0
	s_cmpk_eq_i32 s73, 0x54
	s_cselect_b32 s28, s18, s8
	s_cselect_b32 s29, s19, s9
	s_cselect_b32 s26, s20, s23
	s_cselect_b32 s27, s21, s25
	s_add_u32 s8, s28, 0x8000
	s_addc_u32 s9, s29, 0
	s_add_i32 s52, 0, 0x10000
	s_add_i32 s75, 0, 0x14000
	v_add_u32_e32 v142, s52, v180
	v_add_u32_e32 v168, s75, v180
	ds_read_b128 v[130:133], v142
	ds_read_b128 v[134:137], v142 offset:1024
	ds_read_b128 v[138:141], v142 offset:2048
	ds_read_b128 v[142:145], v142 offset:3072
	ds_read_b128 v[156:159], v168
	ds_read_b128 v[160:163], v168 offset:1024
	ds_read_b128 v[164:167], v168 offset:2048
	ds_read_b128 v[168:171], v168 offset:3072
	v_lshl_add_u64 v[176:177], s[0:1], 0, v[152:153]
	s_add_i32 m0, s3, 0xc000
	ds_read_b128 v[172:175], v181
	ds_read_b128 v[182:185], v181 offset:1024
	ds_read_b128 v[196:199], v181 offset:2048
	ds_read_b128 v[200:203], v181 offset:3072
	ds_read_b128 v[204:207], v181 offset:4096
	ds_read_b128 v[208:211], v181 offset:5120
	ds_read_b128 v[212:215], v181 offset:6144
	ds_read_b128 v[216:219], v181 offset:7168
	global_load_lds_dwordx4 v[176:177], off
	v_lshl_add_u64 v[176:177], s[0:1], 0, v[154:155]
	s_add_i32 m0, s3, 0xe000
	s_nop 0
	global_load_lds_dwordx4 v[176:177], off
	s_waitcnt vmcnt(8)
	s_waitcnt lgkmcnt(0)
	s_barrier
	s_branch .Lpeel_1420

;     __device__ __forceinline__ bool next(int i, Unit& u) const {
;         const long L = (long)i * G + c; if (L >= total) return false;
;         if (nM1 == 144 && nN1 == 8 && nM2 == 0 && G == 256) {
;             const int xcd = c & 7, o = c >> 3;
;             const int grp = (i < 4) ? xcd * 4 + i : 32 + (xcd >> 1), idx = (i < 4) ? o : (xcd & 1) * 16 + o;
;             u.pm = grp * 4 + (idx & 3); u.pn = idx >> 2; return true; }
;         int w = (int)L; { const int q = total / NXCD, r = total % NXCD, xcd = w % NXCD, off = w / NXCD; w = (xcd < r ? xcd * (q + 1) : r * (q + 1) + (xcd - r) * q) + off; }
;         int nM = nM1, nN = nN1; const bool second = w >= n1; if (second) { w -= n1; nM = nM2; nN = nN2; }
;         const int wgm = 4;
;         const int nig = wgm * nN, gid = w / nig, fm = gid * wgm, gsz = (nM - fm) < wgm ? (nM - fm) : wgm;
;         int pm = fm + ((w % nig) % gsz), pn = (w % nig) / gsz;
;         if (second) { pm += pm2; pn = pn < split ? a0 + pn : a1 + pn; }
;         u.pm = pm; u.pn = pn; return true;
; template <class Epi, class Sched, bool ALIGN_EPI = false, bool SP2 = false, bool ABLK = false, bool BBLK = false>
; __device__ __forceinline__ void gemm_phase(PG8_LAS unsigned char* lds, const Gemm g, const Sched& S, const Epi& E) {
;     ...
;         const bool has_next = S.next(ui + 1, nxt);
;         const char* nA = has_next ? (const char*)g.A + (size_t)nxt.pm * tstepA : cA; const char* nB = has_next ? (const char*)g.Bt + (size_t)nxt.pn * tstepB : cB;
.LBB0_1473:
	s_and_b64 vcc, exec, s[20:21]
	s_cbranch_vccz .Ly_1483
	s_add_i32 s89, s28, 1
	s_mul_i32 s6, s89, s81
	s_mul_hi_u32 s7, s89, s42
	s_add_i32 s7, s7, s6
	s_mul_i32 s6, s89, s42
	s_add_u32 s6, s6, s51
	s_addc_u32 s7, s7, s83
	v_mov_b64_e32 v[2:3], s[10:11]
	v_cmp_ge_i64_e32 vcc, s[6:7], v[2:3]
	v_cmp_lt_i64_e64 s[8:9], s[6:7], v[2:3]
	s_cbranch_vccnz .LBB0_1478
	v_readlane_b32 s40, v254, 41
	v_readlane_b32 s41, v254, 42
	s_mov_b64 s[26:27], -1
	s_and_b64 vcc, exec, s[40:41]
	s_cbranch_vccz .LBB0_1476
	s_ashr_i32 s7, s6, 31
	s_lshr_b32 s7, s7, 29
	s_add_i32 s7, s6, s7
	s_ashr_i32 s26, s7, 3
	s_and_b32 s7, s7, -8
	s_sub_i32 s6, s6, s7
	s_lshr_b32 s7, s6, 31
	v_readlane_b32 s27, v254, 32
	s_or_b32 s7, s27, s7
	s_mul_i32 s6, s7, s6
	s_add_i32 s6, s6, s26
	s_cmp_lt_i32 s6, s10
	s_cselect_b32 s7, 32, 4
	v_cvt_f32_ubyte0_e32 v2, s7
	v_rcp_iflag_f32_e32 v2, v2
	s_cselect_b32 s26, 0, s10
	s_cselect_b32 s27, s27, 0
	s_sub_i32 s31, 0, s7
	v_mul_f32_e32 v2, 0x4f7ffffe, v2
	v_cvt_u32_f32_e32 v2, v2
	s_sub_i32 s6, s6, s26
	s_abs_i32 s29, s6
	s_ashr_i32 s26, s6, 31
	v_readfirstlane_b32 s33, v2
	s_mul_i32 s31, s31, s33
	s_mul_hi_u32 s31, s33, s31
	s_add_i32 s33, s33, s31
	s_mul_hi_u32 s31, s29, s33
	s_mul_i32 s33, s31, s7
	s_sub_i32 s29, s29, s33
	s_add_i32 s33, s31, 1
	s_sub_i32 s35, s29, s7
	s_cmp_ge_u32 s29, s7
	s_cselect_b32 s31, s33, s31
	s_cselect_b32 s29, s35, s29
	s_add_i32 s33, s31, 1
	s_cmp_ge_u32 s29, s7
	s_cselect_b32 s29, s33, s31
	s_xor_b32 s29, s29, s26
	s_sub_i32 s26, s29, s26
	s_lshl_b32 s29, s26, 2
	s_sub_i32 s27, s27, s29
	s_min_i32 s27, s27, 4
	s_abs_i32 s31, s27
	v_cvt_f32_u32_e32 v2, s31
	s_sub_i32 s33, 0, s31
	s_mul_i32 s26, s26, s7
	s_sub_i32 s6, s6, s26
	v_rcp_iflag_f32_e32 v2, v2
	s_abs_i32 s7, s6
	s_xor_b32 s26, s6, s27
	s_ashr_i32 s26, s26, 31
	v_mul_f32_e32 v2, 0x4f7ffffe, v2
	v_cvt_u32_f32_e32 v2, v2
	s_nop 0
	v_readfirstlane_b32 s35, v2
	s_mul_i32 s33, s33, s35
	s_mul_hi_u32 s33, s35, s33
	s_add_i32 s35, s35, s33
	s_mul_hi_u32 s33, s7, s35
	s_mul_i32 s35, s33, s31
	s_sub_i32 s7, s7, s35
	s_add_i32 s35, s33, 1
	s_sub_i32 s40, s7, s31
	s_cmp_ge_u32 s7, s31
	s_cselect_b32 s33, s35, s33
	s_cselect_b32 s7, s40, s7
	s_add_i32 s35, s33, 1
	s_cmp_ge_u32 s7, s31
	s_cselect_b32 s7, s35, s33
	s_xor_b32 s7, s7, s26
	s_sub_i32 s46, s7, s26
	s_mul_i32 s7, s46, s27
	s_sub_i32 s6, s6, s7
	s_add_i32 s47, s6, s29
	s_mov_b64 s[26:27], 0

; #define PG8_BAR __builtin_amdgcn_s_barrier()
;     __device__ __forceinline__ bool next(int i, Unit& u) const {
;         const long L = (long)i * G + c; if (L >= total) return false;
;         if (nM1 == 144 && nN1 == 8 && nM2 == 0 && G == 256) {
;             const int xcd = c & 7, o = c >> 3;
;             const int grp = (i < 4) ? xcd * 4 + i : 32 + (xcd >> 1), idx = (i < 4) ? o : (xcd & 1) * 16 + o;
;             u.pm = grp * 4 + (idx & 3); u.pn = idx >> 2; return true; }
;         int w = (int)L; { const int q = total / NXCD, r = total % NXCD, xcd = w % NXCD, off = w / NXCD; w = (xcd < r ? xcd * (q + 1) : r * (q + 1) + (xcd - r) * q) + off; }
;         int nM = nM1, nN = nN1; const bool second = w >= n1; if (second) { w -= n1; nM = nM2; nN = nN2; }
;         const int wgm = 4;
;         const int nig = wgm * nN, gid = w / nig, fm = gid * wgm, gsz = (nM - fm) < wgm ? (nM - fm) : wgm;
;         int pm = fm + ((w % nig) % gsz), pn = (w % nig) / gsz;
;         if (second) { pm += pm2; pn = pn < split ? a0 + pn : a1 + pn; }
;         u.pm = pm; u.pn = pn; return true;
; template <class Epi, class Sched, bool ALIGN_EPI = false, bool SP2 = false, bool ABLK = false, bool BBLK = false>
; __device__ __forceinline__ void gemm_phase(PG8_LAS unsigned char* lds, const Gemm g, const Sched& S, const Epi& E) {
;     ...
; #pragma unroll
;         for (int a = 0; a < 2; ++a)
; #pragma unroll
;             for (int b = 0; b < 2; ++b)
; #pragma unroll
;                 for (int m = 0; m < 4; ++m)
; #pragma unroll
;                     for (int n = 0; n < 2; ++n) acc[a][b][m][n] = (f32x4){0.f, 0.f, 0.f, 0.f};
;         cur = nxt; cA = nA; cB = nB; ++ui;
;         if constexpr (ALIGN_EPI) { if (wr == 1) PG8_BAR; }
.Ly_1483:
	v_pk_mov_b32 v[2:3], 0, 0
	v_pk_mov_b32 v[4:5], 0, 0
	v_pk_mov_b32 v[6:7], 0, 0
	v_pk_mov_b32 v[8:9], 0, 0
	v_pk_mov_b32 v[10:11], 0, 0
	v_pk_mov_b32 v[12:13], 0, 0
	v_pk_mov_b32 v[14:15], 0, 0
	v_pk_mov_b32 v[16:17], 0, 0
	v_pk_mov_b32 v[18:19], 0, 0
	v_pk_mov_b32 v[20:21], 0, 0
	v_pk_mov_b32 v[22:23], 0, 0
	v_pk_mov_b32 v[24:25], 0, 0
	v_pk_mov_b32 v[26:27], 0, 0
	v_pk_mov_b32 v[28:29], 0, 0
	v_pk_mov_b32 v[30:31], 0, 0
	v_pk_mov_b32 v[32:33], 0, 0
	v_pk_mov_b32 v[34:35], 0, 0
	v_pk_mov_b32 v[36:37], 0, 0
	v_pk_mov_b32 v[38:39], 0, 0
	v_pk_mov_b32 v[40:41], 0, 0
	v_pk_mov_b32 v[42:43], 0, 0
	v_pk_mov_b32 v[44:45], 0, 0
	v_pk_mov_b32 v[46:47], 0, 0
	v_pk_mov_b32 v[48:49], 0, 0
	v_pk_mov_b32 v[50:51], 0, 0
	v_pk_mov_b32 v[52:53], 0, 0
	v_pk_mov_b32 v[54:55], 0, 0
	v_pk_mov_b32 v[56:57], 0, 0
	v_pk_mov_b32 v[58:59], 0, 0
	v_pk_mov_b32 v[60:61], 0, 0
	v_pk_mov_b32 v[62:63], 0, 0
	v_pk_mov_b32 v[64:65], 0, 0
	v_pk_mov_b32 v[66:67], 0, 0
	v_pk_mov_b32 v[68:69], 0, 0
	v_pk_mov_b32 v[70:71], 0, 0
	v_pk_mov_b32 v[72:73], 0, 0
	v_pk_mov_b32 v[74:75], 0, 0
	v_pk_mov_b32 v[76:77], 0, 0
	v_pk_mov_b32 v[78:79], 0, 0
	v_pk_mov_b32 v[80:81], 0, 0
	v_pk_mov_b32 v[82:83], 0, 0
	v_pk_mov_b32 v[84:85], 0, 0
	v_pk_mov_b32 v[86:87], 0, 0
	v_pk_mov_b32 v[88:89], 0, 0
	v_pk_mov_b32 v[90:91], 0, 0
	v_pk_mov_b32 v[92:93], 0, 0
	v_pk_mov_b32 v[94:95], 0, 0
	v_pk_mov_b32 v[96:97], 0, 0
	v_pk_mov_b32 v[98:99], 0, 0
	v_pk_mov_b32 v[100:101], 0, 0
	v_pk_mov_b32 v[102:103], 0, 0
	v_pk_mov_b32 v[104:105], 0, 0
	v_pk_mov_b32 v[106:107], 0, 0
	v_pk_mov_b32 v[108:109], 0, 0
	v_pk_mov_b32 v[110:111], 0, 0
	v_pk_mov_b32 v[112:113], 0, 0
	v_pk_mov_b32 v[114:115], 0, 0
	v_pk_mov_b32 v[116:117], 0, 0
	v_pk_mov_b32 v[118:119], 0, 0
	v_pk_mov_b32 v[120:121], 0, 0
	v_pk_mov_b32 v[122:123], 0, 0
	v_pk_mov_b32 v[124:125], 0, 0
	v_pk_mov_b32 v[126:127], 0, 0
	v_pk_mov_b32 v[128:129], 0, 0
	s_add_i32 s89, s28, 1
	s_mul_i32 s6, s89, s81
	s_mul_hi_u32 s7, s89, s42
	s_add_i32 s7, s7, s6
	s_mul_i32 s6, s89, s42
	s_add_u32 s6, s6, s51
	s_addc_u32 s7, s7, s83
	v_mov_b64_e32 v[2:3], s[10:11]
	v_cmp_ge_i64_e32 vcc, s[6:7], v[2:3]
	v_cmp_lt_i64_e64 s[8:9], s[6:7], v[2:3]
	s_cbranch_vccnz .Lyh1483_1478
	v_readlane_b32 s40, v254, 41
	v_readlane_b32 s41, v254, 42
	s_mov_b64 s[26:27], -1
	s_and_b64 vcc, exec, s[40:41]
	s_cbranch_vccz .Lyh1483_1476
	s_ashr_i32 s7, s6, 31
	s_lshr_b32 s7, s7, 29
	s_add_i32 s7, s6, s7
	s_ashr_i32 s26, s7, 3
	s_and_b32 s7, s7, -8
	s_sub_i32 s6, s6, s7
	s_lshr_b32 s7, s6, 31
	v_readlane_b32 s27, v254, 32
	s_or_b32 s7, s27, s7
	s_mul_i32 s6, s7, s6
	s_add_i32 s6, s6, s26
	s_cmp_lt_i32 s6, s10
	s_cselect_b32 s7, 32, 4
	v_cvt_f32_ubyte0_e32 v2, s7
	v_rcp_iflag_f32_e32 v2, v2
	s_cselect_b32 s26, 0, s10
	s_cselect_b32 s27, s27, 0
	s_sub_i32 s31, 0, s7
	v_mul_f32_e32 v2, 0x4f7ffffe, v2
	v_cvt_u32_f32_e32 v2, v2
	s_sub_i32 s6, s6, s26
	s_abs_i32 s29, s6
	s_ashr_i32 s26, s6, 31
	v_readfirstlane_b32 s33, v2
	s_mul_i32 s31, s31, s33
	s_mul_hi_u32 s31, s33, s31
	s_add_i32 s33, s33, s31
	s_mul_hi_u32 s31, s29, s33
	s_mul_i32 s33, s31, s7
	s_sub_i32 s29, s29, s33
	s_add_i32 s33, s31, 1
	s_sub_i32 s35, s29, s7
	s_cmp_ge_u32 s29, s7
	s_cselect_b32 s31, s33, s31
	s_cselect_b32 s29, s35, s29
	s_add_i32 s33, s31, 1
	s_cmp_ge_u32 s29, s7
	s_cselect_b32 s29, s33, s31
	s_xor_b32 s29, s29, s26
	s_sub_i32 s26, s29, s26
	s_lshl_b32 s29, s26, 2
	s_sub_i32 s27, s27, s29
	s_min_i32 s27, s27, 4
	s_abs_i32 s31, s27
	v_cvt_f32_u32_e32 v2, s31
	s_sub_i32 s33, 0, s31
	s_mul_i32 s26, s26, s7
	s_sub_i32 s6, s6, s26
	v_rcp_iflag_f32_e32 v2, v2
	s_abs_i32 s7, s6
	s_xor_b32 s26, s6, s27
	s_ashr_i32 s26, s26, 31
	v_mul_f32_e32 v2, 0x4f7ffffe, v2
	v_cvt_u32_f32_e32 v2, v2
	s_nop 0
	v_readfirstlane_b32 s35, v2
	s_mul_i32 s33, s33, s35
	s_mul_hi_u32 s33, s35, s33
	s_add_i32 s35, s35, s33
	s_mul_hi_u32 s33, s7, s35
	s_mul_i32 s35, s33, s31
	s_sub_i32 s7, s7, s35
	s_add_i32 s35, s33, 1
	s_sub_i32 s40, s7, s31
	s_cmp_ge_u32 s7, s31
	s_cselect_b32 s33, s35, s33
	s_cselect_b32 s7, s40, s7
	s_add_i32 s35, s33, 1
	s_cmp_ge_u32 s7, s31
	s_cselect_b32 s7, s35, s33
	s_xor_b32 s7, s7, s26
	s_sub_i32 s46, s7, s26
	s_mul_i32 s7, s46, s27
	s_sub_i32 s6, s6, s7
	s_add_i32 s47, s6, s29
	s_mov_b64 s[26:27], 0

; #define PG8_STAGE(bufoff, gbase, voff) do { _Pragma("unroll") for (int _i = 0; _i < 2; ++_i) \
;         __builtin_amdgcn_global_load_lds((const unsigned*)((const char*)(gbase) + (voff)[_i]), (PG8_LAS unsigned*)(lds + (bufoff) + ldsw + _i * 8192), 16, 0, 0); } while (0)
; #define PG8_LDA(dst, b, h) do { _Pragma("unroll") for (int m = 0; m < 4; ++m) _Pragma("unroll") for (int k = 0; k < 2; ++k) dst[m][k] = *(const PG8_LAS bf16x8*)(lds + PG8_SA(b, h) + aoff + m * 2048 + k * 1024); } while (0)
; #define PG8_LDB(dst, b, h) do { _Pragma("unroll") for (int n = 0; n < 2; ++n) _Pragma("unroll") for (int k = 0; k < 2; ++k) dst[n][k] = *(const PG8_LAS bf16x8*)(lds + PG8_SB(b, h) + boff + n * 2048 + k * 1024); } while (0)
; #define PG8_MMA(ai, bj, At, Bt) do { __builtin_amdgcn_s_setprio(1); _Pragma("unroll") for (int m = 0; m < 4; ++m) _Pragma("unroll") for (int n = 0; n < 2; ++n) _Pragma("unroll") for (int k = 0; k < 2; ++k) \
;         acc[ai][bj][m][n] = __builtin_amdgcn_mfma_f32_16x16x32_bf16(Bt[n][k], At[m][k], acc[ai][bj][m][n], 0, 0, 0); __builtin_amdgcn_s_setprio(0); } while (0)
; #define PG8_WAIT_V(n) asm volatile("s_waitcnt vmcnt(" #n ")" ::: "memory")
; template <class Epi, class Sched, bool ALIGN_EPI = false, bool SP2 = false, bool ABLK = false, bool BBLK = false>
; __device__ __forceinline__ void gemm_phase(PG8_LAS unsigned char* lds, const Gemm g, const Sched& S, const Epi& E) {
;     ...
;     for (;;) {
;         const bool has_next = S.next(ui + 1, nxt);
;         const char* nA = has_next ? (const char*)g.A + (size_t)nxt.pm * tstepA : cA; const char* nB = has_next ? (const char*)g.Bt + (size_t)nxt.pn * tstepB : cB;
;         for (int t = 0; t < nt; t += 2) {
;             const bool last = (t == nt - 2);
;             const char* a1 = cA + (size_t)(t + 1) * kstepA;
;             const char* a2 = last ? nA : cA + (size_t)(t + 2) * kstepA; const char* b2 = last ? nB : cB + (size_t)(t + 2) * kstepB;
;             const char* a3 = a2 + kstepA; const char* b3 = b2 + kstepB;
;             if (last && has_next) S.a_ready(nxt);
;             if constexpr (SP2) {
;             PG8_LDB(B0, 0, 0); PG8_LDB(B1, 0, 1); PG8_SCHED; PG8_LDA(At, 0, 0); PG8_STAGE(PG8_SA(1, 1), a1 + hstepA, voffA);
;             PG8_WAIT_V(8); PG8_WAIT_L(0); PG8_BAR; PG8_MMA(0, 0, At, B0); PG8_MMA(0, 1, At, B1); PG8_BAR; PG8_SCHED;
;     ...
;         if constexpr (ALIGN_EPI) { if (wr == 1) PG8_BAR; }
.Lyh1483_1482:
	s_add_u32 s0, s0, 0xc000
	s_addc_u32 s1, s1, 0
	s_add_u32 s31, s36, 0x10000
	v_mov_b32_e32 v2, 0
	s_addc_u32 s33, s37, 0
	s_mov_b32 s35, -2
	v_pk_mov_b32 v[2:3], 0, 0
	s_barrier
	s_add_u32 s8, s0, 0x4000
	s_addc_u32 s9, s1, 0
	s_cmpk_eq_i32 s35, 0x54
	s_cselect_b32 s40, s26, s8
	s_cselect_b32 s41, s27, s9
	s_cselect_b32 s36, s28, s31
	s_cselect_b32 s37, s29, s33
	s_add_u32 s8, s40, 0x8000
	s_addc_u32 s9, s41, 0
	s_add_i32 s44, 0, 0x10000
	s_add_i32 s52, 0, 0x14000
	v_add_u32_e32 v142, s44, v206
	v_add_u32_e32 v158, s52, v206
	ds_read_b128 v[130:133], v142
	ds_read_b128 v[134:137], v142 offset:1024
	ds_read_b128 v[138:141], v142 offset:2048
	ds_read_b128 v[142:145], v142 offset:3072
	ds_read_b128 v[146:149], v158
	ds_read_b128 v[150:153], v158 offset:1024
	ds_read_b128 v[154:157], v158 offset:2048
	ds_read_b128 v[158:161], v158 offset:3072
	v_lshl_add_u64 v[188:189], s[0:1], 0, v[184:185]
	s_add_i32 m0, s68, 0xc000
	ds_read_b128 v[162:165], v207
	ds_read_b128 v[166:169], v207 offset:1024
	ds_read_b128 v[170:173], v207 offset:2048
	ds_read_b128 v[174:177], v207 offset:3072
	ds_read_b128 v[198:201], v207 offset:4096
	ds_read_b128 v[208:211], v207 offset:5120
	ds_read_b128 v[212:215], v207 offset:6144
	ds_read_b128 v[216:219], v207 offset:7168
	global_load_lds_dwordx4 v[188:189], off
	v_lshl_add_u64 v[188:189], s[0:1], 0, v[196:197]
	s_add_i32 m0, s68, 0xe000
	s_nop 0
	global_load_lds_dwordx4 v[188:189], off
	s_waitcnt vmcnt(8)
	s_waitcnt lgkmcnt(0)
	s_barrier
	s_branch .Lpeel_1483
